# act intermediate stored tile-blocked (64KB tiles, two 32KB column halves); SwiGLU epilogue rewritten with wave-pair LDS exchange so stores are 1KB-contiguous; P2/P7 A-operand addressing changed to mat
# baseline (speedup 1.0000x reference)
; #define GAS __attribute__((address_space(1)))
; template <class Epi, class Sched, bool ALIGN_EPI = false, bool SP2 = false>
; __device__ __forceinline__ void gemm_phase(PG8_LAS unsigned char* lds, const Gemm g, const Sched& S, const Epi& E, int wv) {
;     ...
; #pragma unroll
;         for (int a = 0; a < 2; ++a)
; #pragma unroll
;             for (int b = 0; b < 2; ++b)
; #pragma unroll
;                 for (int m = 0; m < 4; ++m)
; #pragma unroll
;                     for (int n = 0; n < 2; ++n) acc[a][b][m][n] = (f32x4){0.f, 0.f, 0.f, 0.f};
;     __device__ __forceinline__ void operator()(const f32x4 (&acc)[2][2][4][2], const Unit& u, int wr, int wc, int fr_, int fq_) const {
;     ...
;         const int row0 = u.pm * 256 + wr * 64 + fr, col0 = u.pn * 128 + wc * 32 + 8 * fq;
;         const GAS float* sq = (const GAS float*)ssq + row0; GAS bf16_t* ap = (GAS bf16_t*)act + (size_t)row0 * DFF + col0;
;         float rsv[8];
; #pragma unroll
;         for (int j = 0; j < 8; ++j) rsv[j] = sq[(j >> 2) * 128 + (j & 3) * 16];
.LBB0_772:
	s_lshl_b32 s98, s25, 8
	s_add_i32 s98, s98, s56
	v_and_or_b32 v248, v182, 15, s98
	v_mov_b32_e32 v249, 0
	v_lshl_add_u64 v[248:249], v[248:249], 2, s[8:9]
	global_load_dword v240, v[248:249], off
	global_load_dword v241, v[248:249], off offset:64
	global_load_dword v242, v[248:249], off offset:128
	global_load_dword v243, v[248:249], off offset:192
	global_load_dword v244, v[248:249], off offset:512
	global_load_dword v245, v[248:249], off offset:576
	global_load_dword v246, v[248:249], off offset:640
	global_load_dword v247, v[248:249], off offset:704
	s_ashr_i32 s13, s12, 31
	s_lshl_b64 s[34:35], s[12:13], 19
	s_add_u32 s34, s30, s34
	s_addc_u32 s35, s31, s35
	s_and_b64 s[40:41], s[18:19], exec
	s_cselect_b32 s13, s35, s43
	s_cselect_b32 s63, s34, s42
	s_ashr_i32 s15, s14, 31
	s_lshl_b64 s[40:41], s[14:15], 19
	s_add_u32 s40, s16, s40
	s_addc_u32 s41, s29, s41
	s_and_b64 s[48:49], s[18:19], exec
	s_cselect_b32 s15, s41, s45
	s_cselect_b32 s64, s40, s44
	s_add_u32 s42, s42, 0x40080
	s_addc_u32 s43, s43, 0
	s_add_u32 s65, s44, 0x100
	v_mov_b32_e32 v0, 0
	s_addc_u32 s66, s45, 0
	s_mov_b32 s67, -2
	v_mov_b32_e32 v1, v0
	v_mov_b32_e32 v2, v0
	v_mov_b32_e32 v3, v0
	v_mov_b32_e32 v4, v0
	v_mov_b32_e32 v5, v0
	v_mov_b32_e32 v6, v0
	v_mov_b32_e32 v7, v0
	v_mov_b32_e32 v16, v0
	v_mov_b32_e32 v17, v0
	v_mov_b32_e32 v18, v0
	v_mov_b32_e32 v19, v0
	v_mov_b32_e32 v20, v0
	v_mov_b32_e32 v21, v0
	v_mov_b32_e32 v22, v0
	v_mov_b32_e32 v23, v0
	v_mov_b32_e32 v32, v0
	v_mov_b32_e32 v33, v0
	v_mov_b32_e32 v34, v0
	v_mov_b32_e32 v35, v0
	v_mov_b32_e32 v36, v0
	v_mov_b32_e32 v37, v0
	v_mov_b32_e32 v38, v0
	v_mov_b32_e32 v39, v0
	v_mov_b32_e32 v48, v0
	v_mov_b32_e32 v49, v0
	v_mov_b32_e32 v50, v0
	v_mov_b32_e32 v51, v0
	v_mov_b32_e32 v52, v0
	v_mov_b32_e32 v53, v0
	v_mov_b32_e32 v54, v0
	v_mov_b32_e32 v55, v0
	v_mov_b32_e32 v8, v0
	v_mov_b32_e32 v9, v0
	v_mov_b32_e32 v10, v0
	v_mov_b32_e32 v11, v0
	v_mov_b32_e32 v12, v0
	v_mov_b32_e32 v13, v0
	v_mov_b32_e32 v14, v0
	v_mov_b32_e32 v15, v0
	v_mov_b32_e32 v24, v0
	v_mov_b32_e32 v25, v0
	v_mov_b32_e32 v26, v0
	v_mov_b32_e32 v27, v0
	v_mov_b32_e32 v28, v0
	v_mov_b32_e32 v29, v0
	v_mov_b32_e32 v30, v0
	v_mov_b32_e32 v31, v0
	v_mov_b32_e32 v40, v0
	v_mov_b32_e32 v41, v0
	v_mov_b32_e32 v42, v0
	v_mov_b32_e32 v43, v0
	v_mov_b32_e32 v44, v0
	v_mov_b32_e32 v45, v0
	v_mov_b32_e32 v46, v0
	v_mov_b32_e32 v47, v0
	v_mov_b32_e32 v56, v0
	v_mov_b32_e32 v57, v0
	v_mov_b32_e32 v58, v0
	v_mov_b32_e32 v59, v0
	v_mov_b32_e32 v60, v0
	v_mov_b32_e32 v61, v0
	v_mov_b32_e32 v62, v0
	v_mov_b32_e32 v63, v0
	v_mov_b32_e32 v64, v0
	v_mov_b32_e32 v65, v0
	v_mov_b32_e32 v66, v0
	v_mov_b32_e32 v67, v0
	v_mov_b32_e32 v68, v0
	v_mov_b32_e32 v69, v0
	v_mov_b32_e32 v70, v0
	v_mov_b32_e32 v71, v0
	v_mov_b32_e32 v80, v0
	v_mov_b32_e32 v81, v0
	v_mov_b32_e32 v82, v0
	v_mov_b32_e32 v83, v0
	v_mov_b32_e32 v84, v0
	v_mov_b32_e32 v85, v0
	v_mov_b32_e32 v86, v0
	v_mov_b32_e32 v87, v0
	v_mov_b32_e32 v96, v0
	v_mov_b32_e32 v97, v0
	v_mov_b32_e32 v98, v0
	v_mov_b32_e32 v99, v0
	v_mov_b32_e32 v100, v0
	v_mov_b32_e32 v101, v0
	v_mov_b32_e32 v102, v0
	v_mov_b32_e32 v103, v0
	v_mov_b32_e32 v112, v0
	v_mov_b32_e32 v113, v0
	v_mov_b32_e32 v114, v0
	v_mov_b32_e32 v115, v0
	v_mov_b32_e32 v116, v0
	v_mov_b32_e32 v117, v0
	v_mov_b32_e32 v118, v0
	v_mov_b32_e32 v119, v0
	v_mov_b32_e32 v72, v0
	v_mov_b32_e32 v73, v0
	v_mov_b32_e32 v74, v0
	v_mov_b32_e32 v75, v0
	v_mov_b32_e32 v76, v0
	v_mov_b32_e32 v77, v0
	v_mov_b32_e32 v78, v0
	v_mov_b32_e32 v79, v0
	v_mov_b32_e32 v88, v0
	v_mov_b32_e32 v89, v0
	v_mov_b32_e32 v90, v0
	v_mov_b32_e32 v91, v0
	v_mov_b32_e32 v92, v0
	v_mov_b32_e32 v93, v0
	v_mov_b32_e32 v94, v0
	v_mov_b32_e32 v95, v0
	v_mov_b32_e32 v104, v0
	v_mov_b32_e32 v105, v0
	v_mov_b32_e32 v106, v0
	v_mov_b32_e32 v107, v0
	v_mov_b32_e32 v108, v0
	v_mov_b32_e32 v109, v0
	v_mov_b32_e32 v110, v0
	v_mov_b32_e32 v111, v0
	v_mov_b32_e32 v120, v0
	v_mov_b32_e32 v121, v0
	v_mov_b32_e32 v122, v0
	v_mov_b32_e32 v123, v0
	v_mov_b32_e32 v124, v0
	v_mov_b32_e32 v125, v0
	v_mov_b32_e32 v126, v0
	v_mov_b32_e32 v127, v0

; __device__ __forceinline__ unsigned pk2(float lo, float hi) { f32x2 v = {lo, hi}; bf16x2_t b = __builtin_convertvector(v, bf16x2_t); return __builtin_bit_cast(unsigned, b); }
; __device__ __forceinline__ float silu_f(float g) { return g * __builtin_amdgcn_rcpf(1.0f + __builtin_amdgcn_exp2f(-LOG2E * g)); }
; #define GAS __attribute__((address_space(1)))
;     __device__ __forceinline__ void operator()(const f32x4 (&acc)[2][2][4][2], const Unit& u, int wr, int wc, int fr_, int fq_) const {
;         int l_ = (int)__builtin_amdgcn_mbcnt_hi(~0u, __builtin_amdgcn_mbcnt_lo(~0u, 0u)); asm volatile("" : "+v"(l_)); const int fr = l_ & 15, fq = l_ >> 4; (void)fr_; (void)fq_;
;         const int row0 = u.pm * 256 + wr * 64 + fr, col0 = u.pn * 128 + wc * 32 + 8 * fq;
;         const GAS float* sq = (const GAS float*)ssq + row0; GAS bf16_t* ap = (GAS bf16_t*)act + (size_t)row0 * DFF + col0;
;         float rsv[8];
; #pragma unroll
;         for (int j = 0; j < 8; ++j) rsv[j] = sq[(j >> 2) * 128 + (j & 3) * 16];
; #pragma unroll
;         for (int j = 0; j < 8; ++j) rsv[j] = __builtin_amdgcn_rsqf(rsv[j] * (1.0f / 1024.0f) + EPS);
; #pragma unroll
;         for (int ai = 0; ai < 2; ++ai)
; #pragma unroll
;             for (int m = 0; m < 4; ++m) {
;                 const float rs = rsv[ai * 4 + m];
;                 const f32x4 g0 = acc[ai][0][m][0] * rs, g1 = acc[ai][0][m][1] * rs, u0 = acc[ai][1][m][0] * rs, u1 = acc[ai][1][m][1] * rs;
;                 u32x4 w;
;                 w.x = pk2(silu_f(g0[0]) * u0[0], silu_f(g0[1]) * u0[1]); w.y = pk2(silu_f(g0[2]) * u0[2], silu_f(g0[3]) * u0[3]);
;                 w.z = pk2(silu_f(g1[0]) * u1[0], silu_f(g1[1]) * u1[1]); w.w = pk2(silu_f(g1[2]) * u1[2], silu_f(g1[3]) * u1[3]);
;                 *(GAS u32x4*)(ap + (size_t)(ai * 128 + m * 16) * DFF) = w;
.LBB0_776:
	v_and_b32_e32 v164, 15, v182
	v_lshrrev_b32_e32 v165, 4, v182
	s_bfe_u32 s13, s57, 0x10005
	s_lshl_b32 s21, s13, 2
	v_add_u32_e32 v166, s21, v165
	v_and_b32_e32 v167, 7, v164
	v_xor_b32_e32 v166, v166, v167
	v_lshlrev_b32_e32 v166, 4, v166
	v_lshl_add_u32 v166, v164, 7, v166
	s_lshr_b32 s21, s56, 5
	s_lshr_b32 s26, s57, 6
	s_add_i32 s21, s21, s26
	s_lshl_b32 s21, s21, 11
	s_add_i32 s21, s21, 0xc000
	v_add_u32_e32 v172, s21, v166
	v_lshrrev_b32_e32 v165, 3, v182
	v_and_b32_e32 v167, 7, v182
	v_xor_b32_e32 v168, v167, v165
	v_lshlrev_b32_e32 v168, 4, v168
	s_lshl_b32 s13, s13, 3
	v_add_u32_e32 v165, s13, v165
	v_lshl_add_u32 v168, v165, 7, v168
	v_add_u32_e32 v173, s21, v168
	v_add_u32_e32 v165, s56, v165
	s_lshl_b32 s26, s26, 15
	v_lshl_add_u32 v167, v167, 4, s26
	v_lshl_add_u32 v174, v165, 7, v167
	s_mul_i32 s13, s25, 0x160000
	s_lshl_b32 s21, s24, 16
	s_add_u32 s13, s13, s21
	s_add_u32 s98, s6, s13
	s_addc_u32 s99, s7, 0
	s_mov_b64 s[24:25], -1
	v_fmamk_f32 v240, v240, 0x3a800000, v189
	v_fmamk_f32 v241, v241, 0x3a800000, v189
	v_fmamk_f32 v242, v242, 0x3a800000, v189
	v_fmamk_f32 v243, v243, 0x3a800000, v189
	v_fmamk_f32 v244, v244, 0x3a800000, v189
	v_fmamk_f32 v245, v245, 0x3a800000, v189
	v_fmamk_f32 v246, v246, 0x3a800000, v189
	v_fmamk_f32 v247, v247, 0x3a800000, v189
	v_rsq_f32_e32 v240, v240
	v_rsq_f32_e32 v241, v241
	v_rsq_f32_e32 v242, v242
	v_rsq_f32_e32 v243, v243
	v_rsq_f32_e32 v244, v244
	v_rsq_f32_e32 v245, v245
	v_rsq_f32_e32 v246, v246
	v_rsq_f32_e32 v247, v247
	v_mov_b32_e32 v162, 1.0
	v_mul_f32_e32 v144, 0xbfb8aa3b, v240
	v_mul_f32_e32 v146, 0xbfb8aa3b, v241
	v_mul_f32_e32 v148, 0xbfb8aa3b, v242
	v_mul_f32_e32 v150, 0xbfb8aa3b, v243
	v_mul_f32_e32 v152, 0xbfb8aa3b, v244
	v_mul_f32_e32 v154, 0xbfb8aa3b, v245
	v_mul_f32_e32 v156, 0xbfb8aa3b, v246
	v_mul_f32_e32 v158, 0xbfb8aa3b, v247
	v_mul_f32_e32 v145, v240, v240
	v_mul_f32_e32 v147, v241, v241
	v_mul_f32_e32 v149, v242, v242
	v_mul_f32_e32 v151, v243, v243
	v_mul_f32_e32 v153, v244, v244
	v_mul_f32_e32 v155, v245, v245
	v_mul_f32_e32 v157, v246, v246
	v_mul_f32_e32 v159, v247, v247
	v_pk_mul_f32 v[116:117], v[124:125], v[116:117]
	v_pk_mul_f32 v[118:119], v[126:127], v[118:119]
	v_pk_mul_f32 v[112:113], v[120:121], v[112:113]
	v_pk_mul_f32 v[114:115], v[122:123], v[114:115]
	v_pk_mul_f32 v[124:125], v[124:125], v[144:145] op_sel_hi:[1,0]
	v_pk_mul_f32 v[126:127], v[126:127], v[144:145] op_sel_hi:[1,0]
	v_pk_mul_f32 v[120:121], v[120:121], v[144:145] op_sel_hi:[1,0]
	v_pk_mul_f32 v[122:123], v[122:123], v[144:145] op_sel_hi:[1,0]
	v_pk_mul_f32 v[116:117], v[116:117], v[144:145] op_sel:[0,1] op_sel_hi:[1,1]
	v_pk_mul_f32 v[118:119], v[118:119], v[144:145] op_sel:[0,1] op_sel_hi:[1,1]
	v_pk_mul_f32 v[112:113], v[112:113], v[144:145] op_sel:[0,1] op_sel_hi:[1,1]
	v_pk_mul_f32 v[114:115], v[114:115], v[144:145] op_sel:[0,1] op_sel_hi:[1,1]
	v_exp_f32_e32 v124, v124
	v_exp_f32_e32 v125, v125
	v_exp_f32_e32 v126, v126
	v_exp_f32_e32 v127, v127
	v_exp_f32_e32 v120, v120
	v_exp_f32_e32 v121, v121
	v_exp_f32_e32 v122, v122
	v_exp_f32_e32 v123, v123
	v_pk_add_f32 v[124:125], v[124:125], v[162:163] op_sel_hi:[1,0]
	v_pk_add_f32 v[126:127], v[126:127], v[162:163] op_sel_hi:[1,0]
	v_pk_add_f32 v[120:121], v[120:121], v[162:163] op_sel_hi:[1,0]
	v_pk_add_f32 v[122:123], v[122:123], v[162:163] op_sel_hi:[1,0]
	v_rcp_f32_e32 v124, v124
	v_rcp_f32_e32 v125, v125
	v_rcp_f32_e32 v126, v126
	v_rcp_f32_e32 v127, v127
	v_rcp_f32_e32 v120, v120
	v_rcp_f32_e32 v121, v121
	v_rcp_f32_e32 v122, v122
	v_rcp_f32_e32 v123, v123
	v_pk_mul_f32 v[116:117], v[116:117], v[124:125]
	v_pk_mul_f32 v[118:119], v[118:119], v[126:127]
	v_pk_mul_f32 v[112:113], v[112:113], v[120:121]
	v_pk_mul_f32 v[114:115], v[114:115], v[122:123]
	v_cvt_pk_bf16_f32 v124, v116, v117
	v_cvt_pk_bf16_f32 v125, v118, v119
	v_cvt_pk_bf16_f32 v126, v112, v113
	v_cvt_pk_bf16_f32 v127, v114, v115
	ds_write_b128 v172, v[124:127]
	s_waitcnt lgkmcnt(0)
	s_barrier
	ds_read_b128 v[176:179], v173
	v_pk_mul_f32 v[100:101], v[108:109], v[100:101]
	v_pk_mul_f32 v[102:103], v[110:111], v[102:103]
	v_pk_mul_f32 v[96:97], v[104:105], v[96:97]
	v_pk_mul_f32 v[98:99], v[106:107], v[98:99]
	v_pk_mul_f32 v[108:109], v[108:109], v[146:147] op_sel_hi:[1,0]
	v_pk_mul_f32 v[110:111], v[110:111], v[146:147] op_sel_hi:[1,0]
	v_pk_mul_f32 v[104:105], v[104:105], v[146:147] op_sel_hi:[1,0]
	v_pk_mul_f32 v[106:107], v[106:107], v[146:147] op_sel_hi:[1,0]
	v_pk_mul_f32 v[100:101], v[100:101], v[146:147] op_sel:[0,1] op_sel_hi:[1,1]
	v_pk_mul_f32 v[102:103], v[102:103], v[146:147] op_sel:[0,1] op_sel_hi:[1,1]
	v_pk_mul_f32 v[96:97], v[96:97], v[146:147] op_sel:[0,1] op_sel_hi:[1,1]
	v_pk_mul_f32 v[98:99], v[98:99], v[146:147] op_sel:[0,1] op_sel_hi:[1,1]
	v_exp_f32_e32 v108, v108
	v_exp_f32_e32 v109, v109
	v_exp_f32_e32 v110, v110
	v_exp_f32_e32 v111, v111
	v_exp_f32_e32 v104, v104
	v_exp_f32_e32 v105, v105
	v_exp_f32_e32 v106, v106
	v_exp_f32_e32 v107, v107
	v_pk_add_f32 v[108:109], v[108:109], v[162:163] op_sel_hi:[1,0]
	v_pk_add_f32 v[110:111], v[110:111], v[162:163] op_sel_hi:[1,0]
	v_pk_add_f32 v[104:105], v[104:105], v[162:163] op_sel_hi:[1,0]
	v_pk_add_f32 v[106:107], v[106:107], v[162:163] op_sel_hi:[1,0]
	v_rcp_f32_e32 v108, v108
	v_rcp_f32_e32 v109, v109
	v_rcp_f32_e32 v110, v110
	v_rcp_f32_e32 v111, v111
	v_rcp_f32_e32 v104, v104
	v_rcp_f32_e32 v105, v105
	v_rcp_f32_e32 v106, v106
	v_rcp_f32_e32 v107, v107
	v_pk_mul_f32 v[100:101], v[100:101], v[108:109]
	v_pk_mul_f32 v[102:103], v[102:103], v[110:111]
	v_pk_mul_f32 v[96:97], v[96:97], v[104:105]
	v_pk_mul_f32 v[98:99], v[98:99], v[106:107]
	v_cvt_pk_bf16_f32 v108, v100, v101
	v_cvt_pk_bf16_f32 v109, v102, v103
	v_cvt_pk_bf16_f32 v110, v96, v97
	v_cvt_pk_bf16_f32 v111, v98, v99
	ds_write_b128 v172, v[108:111] offset:8192
	s_waitcnt lgkmcnt(1)
	global_store_dwordx4 v174, v[176:179], s[98:99]
	s_waitcnt lgkmcnt(0)
	s_barrier
; __device__ __forceinline__ unsigned pk2(float lo, float hi) { f32x2 v = {lo, hi}; bf16x2_t b = __builtin_convertvector(v, bf16x2_t); return __builtin_bit_cast(unsigned, b); }
; __device__ __forceinline__ float silu_f(float g) { return g * __builtin_amdgcn_rcpf(1.0f + __builtin_amdgcn_exp2f(-LOG2E * g)); }
; #define GAS __attribute__((address_space(1)))
;     __device__ __forceinline__ void operator()(const f32x4 (&acc)[2][2][4][2], const Unit& u, int wr, int wc, int fr_, int fq_) const {
;     ...
;         for (int ai = 0; ai < 2; ++ai)
; #pragma unroll
;             for (int m = 0; m < 4; ++m) {
;                 const float rs = rsv[ai * 4 + m];
;                 const f32x4 g0 = acc[ai][0][m][0] * rs, g1 = acc[ai][0][m][1] * rs, u0 = acc[ai][1][m][0] * rs, u1 = acc[ai][1][m][1] * rs;
;                 u32x4 w;
;                 w.x = pk2(silu_f(g0[0]) * u0[0], silu_f(g0[1]) * u0[1]); w.y = pk2(silu_f(g0[2]) * u0[2], silu_f(g0[3]) * u0[3]);
;                 w.z = pk2(silu_f(g1[0]) * u1[0], silu_f(g1[1]) * u1[1]); w.w = pk2(silu_f(g1[2]) * u1[2], silu_f(g1[3]) * u1[3]);
;                 *(GAS u32x4*)(ap + (size_t)(ai * 128 + m * 16) * DFF) = w;
	ds_read_b128 v[176:179], v173 offset:8192
	v_pk_mul_f32 v[84:85], v[92:93], v[84:85]
	v_pk_mul_f32 v[86:87], v[94:95], v[86:87]
	v_pk_mul_f32 v[80:81], v[88:89], v[80:81]
	v_pk_mul_f32 v[82:83], v[90:91], v[82:83]
	v_pk_mul_f32 v[92:93], v[92:93], v[148:149] op_sel_hi:[1,0]
	v_pk_mul_f32 v[94:95], v[94:95], v[148:149] op_sel_hi:[1,0]
	v_pk_mul_f32 v[88:89], v[88:89], v[148:149] op_sel_hi:[1,0]
	v_pk_mul_f32 v[90:91], v[90:91], v[148:149] op_sel_hi:[1,0]
	v_pk_mul_f32 v[84:85], v[84:85], v[148:149] op_sel:[0,1] op_sel_hi:[1,1]
	v_pk_mul_f32 v[86:87], v[86:87], v[148:149] op_sel:[0,1] op_sel_hi:[1,1]
	v_pk_mul_f32 v[80:81], v[80:81], v[148:149] op_sel:[0,1] op_sel_hi:[1,1]
	v_pk_mul_f32 v[82:83], v[82:83], v[148:149] op_sel:[0,1] op_sel_hi:[1,1]
	v_exp_f32_e32 v92, v92
	v_exp_f32_e32 v93, v93
	v_exp_f32_e32 v94, v94
	v_exp_f32_e32 v95, v95
	v_exp_f32_e32 v88, v88
	v_exp_f32_e32 v89, v89
	v_exp_f32_e32 v90, v90
	v_exp_f32_e32 v91, v91
	v_pk_add_f32 v[92:93], v[92:93], v[162:163] op_sel_hi:[1,0]
	v_pk_add_f32 v[94:95], v[94:95], v[162:163] op_sel_hi:[1,0]
	v_pk_add_f32 v[88:89], v[88:89], v[162:163] op_sel_hi:[1,0]
	v_pk_add_f32 v[90:91], v[90:91], v[162:163] op_sel_hi:[1,0]
	v_rcp_f32_e32 v92, v92
	v_rcp_f32_e32 v93, v93
	v_rcp_f32_e32 v94, v94
	v_rcp_f32_e32 v95, v95
	v_rcp_f32_e32 v88, v88
	v_rcp_f32_e32 v89, v89
	v_rcp_f32_e32 v90, v90
	v_rcp_f32_e32 v91, v91
	v_pk_mul_f32 v[84:85], v[84:85], v[92:93]
	v_pk_mul_f32 v[86:87], v[86:87], v[94:95]
	v_pk_mul_f32 v[80:81], v[80:81], v[88:89]
	v_pk_mul_f32 v[82:83], v[82:83], v[90:91]
	v_cvt_pk_bf16_f32 v92, v84, v85
	v_cvt_pk_bf16_f32 v93, v86, v87
	v_cvt_pk_bf16_f32 v94, v80, v81
	v_cvt_pk_bf16_f32 v95, v82, v83
	ds_write_b128 v172, v[92:95]
	v_add_u32_e32 v175, 0x800, v174
	s_waitcnt lgkmcnt(1)
	global_store_dwordx4 v175, v[176:179], s[98:99]
	s_waitcnt lgkmcnt(0)
	s_barrier
	ds_read_b128 v[176:179], v173
	v_pk_mul_f32 v[68:69], v[76:77], v[68:69]
	v_pk_mul_f32 v[70:71], v[78:79], v[70:71]
	v_pk_mul_f32 v[64:65], v[72:73], v[64:65]
	v_pk_mul_f32 v[66:67], v[74:75], v[66:67]
	v_pk_mul_f32 v[76:77], v[76:77], v[150:151] op_sel_hi:[1,0]
	v_pk_mul_f32 v[78:79], v[78:79], v[150:151] op_sel_hi:[1,0]
	v_pk_mul_f32 v[72:73], v[72:73], v[150:151] op_sel_hi:[1,0]
	v_pk_mul_f32 v[74:75], v[74:75], v[150:151] op_sel_hi:[1,0]
	v_pk_mul_f32 v[68:69], v[68:69], v[150:151] op_sel:[0,1] op_sel_hi:[1,1]
	v_pk_mul_f32 v[70:71], v[70:71], v[150:151] op_sel:[0,1] op_sel_hi:[1,1]
	v_pk_mul_f32 v[64:65], v[64:65], v[150:151] op_sel:[0,1] op_sel_hi:[1,1]
	v_pk_mul_f32 v[66:67], v[66:67], v[150:151] op_sel:[0,1] op_sel_hi:[1,1]
	v_exp_f32_e32 v76, v76
	v_exp_f32_e32 v77, v77
	v_exp_f32_e32 v78, v78
	v_exp_f32_e32 v79, v79
	v_exp_f32_e32 v72, v72
	v_exp_f32_e32 v73, v73
	v_exp_f32_e32 v74, v74
	v_exp_f32_e32 v75, v75
	v_pk_add_f32 v[76:77], v[76:77], v[162:163] op_sel_hi:[1,0]
	v_pk_add_f32 v[78:79], v[78:79], v[162:163] op_sel_hi:[1,0]
	v_pk_add_f32 v[72:73], v[72:73], v[162:163] op_sel_hi:[1,0]
	v_pk_add_f32 v[74:75], v[74:75], v[162:163] op_sel_hi:[1,0]
	v_rcp_f32_e32 v76, v76
	v_rcp_f32_e32 v77, v77
	v_rcp_f32_e32 v78, v78
	v_rcp_f32_e32 v79, v79
	v_rcp_f32_e32 v72, v72
	v_rcp_f32_e32 v73, v73
	v_rcp_f32_e32 v74, v74
	v_rcp_f32_e32 v75, v75
	v_pk_mul_f32 v[68:69], v[68:69], v[76:77]
	v_pk_mul_f32 v[70:71], v[70:71], v[78:79]
	v_pk_mul_f32 v[64:65], v[64:65], v[72:73]
	v_pk_mul_f32 v[66:67], v[66:67], v[74:75]
	v_cvt_pk_bf16_f32 v76, v68, v69
	v_cvt_pk_bf16_f32 v77, v70, v71
	v_cvt_pk_bf16_f32 v78, v64, v65
	v_cvt_pk_bf16_f32 v79, v66, v67
	ds_write_b128 v172, v[76:79] offset:8192
	v_add_u32_e32 v175, 0x1000, v174
	s_waitcnt lgkmcnt(1)
	global_store_dwordx4 v175, v[176:179], s[98:99]
	s_waitcnt lgkmcnt(0)
	s_barrier
	ds_read_b128 v[176:179], v173 offset:8192
	v_pk_mul_f32 v[52:53], v[60:61], v[52:53]
	v_pk_mul_f32 v[54:55], v[62:63], v[54:55]
	v_pk_mul_f32 v[48:49], v[56:57], v[48:49]
	v_pk_mul_f32 v[50:51], v[58:59], v[50:51]
	v_pk_mul_f32 v[60:61], v[60:61], v[152:153] op_sel_hi:[1,0]
	v_pk_mul_f32 v[62:63], v[62:63], v[152:153] op_sel_hi:[1,0]
	v_pk_mul_f32 v[56:57], v[56:57], v[152:153] op_sel_hi:[1,0]
	v_pk_mul_f32 v[58:59], v[58:59], v[152:153] op_sel_hi:[1,0]
	v_pk_mul_f32 v[52:53], v[52:53], v[152:153] op_sel:[0,1] op_sel_hi:[1,1]
	v_pk_mul_f32 v[54:55], v[54:55], v[152:153] op_sel:[0,1] op_sel_hi:[1,1]
	v_pk_mul_f32 v[48:49], v[48:49], v[152:153] op_sel:[0,1] op_sel_hi:[1,1]
	v_pk_mul_f32 v[50:51], v[50:51], v[152:153] op_sel:[0,1] op_sel_hi:[1,1]
	v_exp_f32_e32 v60, v60
	v_exp_f32_e32 v61, v61
	v_exp_f32_e32 v62, v62
	v_exp_f32_e32 v63, v63
	v_exp_f32_e32 v56, v56
	v_exp_f32_e32 v57, v57
	v_exp_f32_e32 v58, v58
	v_exp_f32_e32 v59, v59
	v_pk_add_f32 v[60:61], v[60:61], v[162:163] op_sel_hi:[1,0]
	v_pk_add_f32 v[62:63], v[62:63], v[162:163] op_sel_hi:[1,0]
	v_pk_add_f32 v[56:57], v[56:57], v[162:163] op_sel_hi:[1,0]
	v_pk_add_f32 v[58:59], v[58:59], v[162:163] op_sel_hi:[1,0]
	v_rcp_f32_e32 v60, v60
	v_rcp_f32_e32 v61, v61
	v_rcp_f32_e32 v62, v62
	v_rcp_f32_e32 v63, v63
	v_rcp_f32_e32 v56, v56
	v_rcp_f32_e32 v57, v57
	v_rcp_f32_e32 v58, v58
	v_rcp_f32_e32 v59, v59
	v_pk_mul_f32 v[52:53], v[52:53], v[60:61]
	v_pk_mul_f32 v[54:55], v[54:55], v[62:63]
	v_pk_mul_f32 v[48:49], v[48:49], v[56:57]
	v_pk_mul_f32 v[50:51], v[50:51], v[58:59]
	v_cvt_pk_bf16_f32 v60, v52, v53
	v_cvt_pk_bf16_f32 v61, v54, v55
	v_cvt_pk_bf16_f32 v62, v48, v49
	v_cvt_pk_bf16_f32 v63, v50, v51
	ds_write_b128 v172, v[60:63]
	v_add_u32_e32 v175, 0x1800, v174
	s_waitcnt lgkmcnt(1)
	global_store_dwordx4 v175, v[176:179], s[98:99]
	s_waitcnt lgkmcnt(0)
	s_barrier
; __device__ __forceinline__ unsigned pk2(float lo, float hi) { f32x2 v = {lo, hi}; bf16x2_t b = __builtin_convertvector(v, bf16x2_t); return __builtin_bit_cast(unsigned, b); }
; __device__ __forceinline__ float silu_f(float g) { return g * __builtin_amdgcn_rcpf(1.0f + __builtin_amdgcn_exp2f(-LOG2E * g)); }
; #define GAS __attribute__((address_space(1)))
; template <class Epi, class Sched, bool ALIGN_EPI = false, bool SP2 = false>
; __device__ __forceinline__ void gemm_phase(PG8_LAS unsigned char* lds, const Gemm g, const Sched& S, const Epi& E, int wv) {
;     ...
;         if constexpr (!Epi::AFTER_DRAIN) { E(acc, cur, wr, wc, fr, fq); S.done(cur); }
;         if (!has_next) break;
;     __device__ __forceinline__ void operator()(const f32x4 (&acc)[2][2][4][2], const Unit& u, int wr, int wc, int fr_, int fq_) const {
;     ...
;         for (int ai = 0; ai < 2; ++ai)
; #pragma unroll
;             for (int m = 0; m < 4; ++m) {
;                 const float rs = rsv[ai * 4 + m];
;                 const f32x4 g0 = acc[ai][0][m][0] * rs, g1 = acc[ai][0][m][1] * rs, u0 = acc[ai][1][m][0] * rs, u1 = acc[ai][1][m][1] * rs;
;                 u32x4 w;
;                 w.x = pk2(silu_f(g0[0]) * u0[0], silu_f(g0[1]) * u0[1]); w.y = pk2(silu_f(g0[2]) * u0[2], silu_f(g0[3]) * u0[3]);
;                 w.z = pk2(silu_f(g1[0]) * u1[0], silu_f(g1[1]) * u1[1]); w.w = pk2(silu_f(g1[2]) * u1[2], silu_f(g1[3]) * u1[3]);
;                 *(GAS u32x4*)(ap + (size_t)(ai * 128 + m * 16) * DFF) = w;
	ds_read_b128 v[176:179], v173
	v_pk_mul_f32 v[36:37], v[44:45], v[36:37]
	v_pk_mul_f32 v[38:39], v[46:47], v[38:39]
	v_pk_mul_f32 v[32:33], v[40:41], v[32:33]
	v_pk_mul_f32 v[34:35], v[42:43], v[34:35]
	v_pk_mul_f32 v[44:45], v[44:45], v[154:155] op_sel_hi:[1,0]
	v_pk_mul_f32 v[46:47], v[46:47], v[154:155] op_sel_hi:[1,0]
	v_pk_mul_f32 v[40:41], v[40:41], v[154:155] op_sel_hi:[1,0]
	v_pk_mul_f32 v[42:43], v[42:43], v[154:155] op_sel_hi:[1,0]
	v_pk_mul_f32 v[36:37], v[36:37], v[154:155] op_sel:[0,1] op_sel_hi:[1,1]
	v_pk_mul_f32 v[38:39], v[38:39], v[154:155] op_sel:[0,1] op_sel_hi:[1,1]
	v_pk_mul_f32 v[32:33], v[32:33], v[154:155] op_sel:[0,1] op_sel_hi:[1,1]
	v_pk_mul_f32 v[34:35], v[34:35], v[154:155] op_sel:[0,1] op_sel_hi:[1,1]
	v_exp_f32_e32 v44, v44
	v_exp_f32_e32 v45, v45
	v_exp_f32_e32 v46, v46
	v_exp_f32_e32 v47, v47
	v_exp_f32_e32 v40, v40
	v_exp_f32_e32 v41, v41
	v_exp_f32_e32 v42, v42
	v_exp_f32_e32 v43, v43
	v_pk_add_f32 v[44:45], v[44:45], v[162:163] op_sel_hi:[1,0]
	v_pk_add_f32 v[46:47], v[46:47], v[162:163] op_sel_hi:[1,0]
	v_pk_add_f32 v[40:41], v[40:41], v[162:163] op_sel_hi:[1,0]
	v_pk_add_f32 v[42:43], v[42:43], v[162:163] op_sel_hi:[1,0]
	v_rcp_f32_e32 v44, v44
	v_rcp_f32_e32 v45, v45
	v_rcp_f32_e32 v46, v46
	v_rcp_f32_e32 v47, v47
	v_rcp_f32_e32 v40, v40
	v_rcp_f32_e32 v41, v41
	v_rcp_f32_e32 v42, v42
	v_rcp_f32_e32 v43, v43
	v_pk_mul_f32 v[36:37], v[36:37], v[44:45]
	v_pk_mul_f32 v[38:39], v[38:39], v[46:47]
	v_pk_mul_f32 v[32:33], v[32:33], v[40:41]
	v_pk_mul_f32 v[34:35], v[34:35], v[42:43]
	v_cvt_pk_bf16_f32 v44, v36, v37
	v_cvt_pk_bf16_f32 v45, v38, v39
	v_cvt_pk_bf16_f32 v46, v32, v33
	v_cvt_pk_bf16_f32 v47, v34, v35
	ds_write_b128 v172, v[44:47] offset:8192
	v_add_u32_e32 v175, 0x4000, v174
	s_waitcnt lgkmcnt(1)
	global_store_dwordx4 v175, v[176:179], s[98:99]
	s_waitcnt lgkmcnt(0)
	s_barrier
	ds_read_b128 v[176:179], v173 offset:8192
	v_pk_mul_f32 v[20:21], v[28:29], v[20:21]
	v_pk_mul_f32 v[22:23], v[30:31], v[22:23]
	v_pk_mul_f32 v[16:17], v[24:25], v[16:17]
	v_pk_mul_f32 v[18:19], v[26:27], v[18:19]
	v_pk_mul_f32 v[28:29], v[28:29], v[156:157] op_sel_hi:[1,0]
	v_pk_mul_f32 v[30:31], v[30:31], v[156:157] op_sel_hi:[1,0]
	v_pk_mul_f32 v[24:25], v[24:25], v[156:157] op_sel_hi:[1,0]
	v_pk_mul_f32 v[26:27], v[26:27], v[156:157] op_sel_hi:[1,0]
	v_pk_mul_f32 v[20:21], v[20:21], v[156:157] op_sel:[0,1] op_sel_hi:[1,1]
	v_pk_mul_f32 v[22:23], v[22:23], v[156:157] op_sel:[0,1] op_sel_hi:[1,1]
	v_pk_mul_f32 v[16:17], v[16:17], v[156:157] op_sel:[0,1] op_sel_hi:[1,1]
	v_pk_mul_f32 v[18:19], v[18:19], v[156:157] op_sel:[0,1] op_sel_hi:[1,1]
	v_exp_f32_e32 v28, v28
	v_exp_f32_e32 v29, v29
	v_exp_f32_e32 v30, v30
	v_exp_f32_e32 v31, v31
	v_exp_f32_e32 v24, v24
	v_exp_f32_e32 v25, v25
	v_exp_f32_e32 v26, v26
	v_exp_f32_e32 v27, v27
	v_pk_add_f32 v[28:29], v[28:29], v[162:163] op_sel_hi:[1,0]
	v_pk_add_f32 v[30:31], v[30:31], v[162:163] op_sel_hi:[1,0]
	v_pk_add_f32 v[24:25], v[24:25], v[162:163] op_sel_hi:[1,0]
	v_pk_add_f32 v[26:27], v[26:27], v[162:163] op_sel_hi:[1,0]
	v_rcp_f32_e32 v28, v28
	v_rcp_f32_e32 v29, v29
	v_rcp_f32_e32 v30, v30
	v_rcp_f32_e32 v31, v31
	v_rcp_f32_e32 v24, v24
	v_rcp_f32_e32 v25, v25
	v_rcp_f32_e32 v26, v26
	v_rcp_f32_e32 v27, v27
	v_pk_mul_f32 v[20:21], v[20:21], v[28:29]
	v_pk_mul_f32 v[22:23], v[22:23], v[30:31]
	v_pk_mul_f32 v[16:17], v[16:17], v[24:25]
	v_pk_mul_f32 v[18:19], v[18:19], v[26:27]
	v_cvt_pk_bf16_f32 v28, v20, v21
	v_cvt_pk_bf16_f32 v29, v22, v23
	v_cvt_pk_bf16_f32 v30, v16, v17
	v_cvt_pk_bf16_f32 v31, v18, v19
	ds_write_b128 v172, v[28:31]
	v_add_u32_e32 v175, 0x4800, v174
	s_waitcnt lgkmcnt(1)
	global_store_dwordx4 v175, v[176:179], s[98:99]
	s_waitcnt lgkmcnt(0)
	s_barrier
	ds_read_b128 v[176:179], v173
	v_pk_mul_f32 v[4:5], v[12:13], v[4:5]
	v_pk_mul_f32 v[6:7], v[14:15], v[6:7]
	v_pk_mul_f32 v[0:1], v[8:9], v[0:1]
	v_pk_mul_f32 v[2:3], v[10:11], v[2:3]
	v_pk_mul_f32 v[12:13], v[12:13], v[158:159] op_sel_hi:[1,0]
	v_pk_mul_f32 v[14:15], v[14:15], v[158:159] op_sel_hi:[1,0]
	v_pk_mul_f32 v[8:9], v[8:9], v[158:159] op_sel_hi:[1,0]
	v_pk_mul_f32 v[10:11], v[10:11], v[158:159] op_sel_hi:[1,0]
	v_pk_mul_f32 v[4:5], v[4:5], v[158:159] op_sel:[0,1] op_sel_hi:[1,1]
	v_pk_mul_f32 v[6:7], v[6:7], v[158:159] op_sel:[0,1] op_sel_hi:[1,1]
	v_pk_mul_f32 v[0:1], v[0:1], v[158:159] op_sel:[0,1] op_sel_hi:[1,1]
	v_pk_mul_f32 v[2:3], v[2:3], v[158:159] op_sel:[0,1] op_sel_hi:[1,1]
	v_exp_f32_e32 v12, v12
	v_exp_f32_e32 v13, v13
	v_exp_f32_e32 v14, v14
	v_exp_f32_e32 v15, v15
	v_exp_f32_e32 v8, v8
	v_exp_f32_e32 v9, v9
	v_exp_f32_e32 v10, v10
	v_exp_f32_e32 v11, v11
	v_pk_add_f32 v[12:13], v[12:13], v[162:163] op_sel_hi:[1,0]
	v_pk_add_f32 v[14:15], v[14:15], v[162:163] op_sel_hi:[1,0]
	v_pk_add_f32 v[8:9], v[8:9], v[162:163] op_sel_hi:[1,0]
	v_pk_add_f32 v[10:11], v[10:11], v[162:163] op_sel_hi:[1,0]
	v_rcp_f32_e32 v12, v12
	v_rcp_f32_e32 v13, v13
	v_rcp_f32_e32 v14, v14
	v_rcp_f32_e32 v15, v15
	v_rcp_f32_e32 v8, v8
	v_rcp_f32_e32 v9, v9
	v_rcp_f32_e32 v10, v10
	v_rcp_f32_e32 v11, v11
	v_pk_mul_f32 v[4:5], v[4:5], v[12:13]
	v_pk_mul_f32 v[6:7], v[6:7], v[14:15]
	v_pk_mul_f32 v[0:1], v[0:1], v[8:9]
	v_pk_mul_f32 v[2:3], v[2:3], v[10:11]
	v_cvt_pk_bf16_f32 v12, v4, v5
	v_cvt_pk_bf16_f32 v13, v6, v7
	v_cvt_pk_bf16_f32 v14, v0, v1
	v_cvt_pk_bf16_f32 v15, v2, v3
	ds_write_b128 v172, v[12:15] offset:8192
	v_add_u32_e32 v175, 0x5000, v174
	s_waitcnt lgkmcnt(1)
	global_store_dwordx4 v175, v[176:179], s[98:99]
	s_waitcnt lgkmcnt(0)
	s_barrier
	ds_read_b128 v[176:179], v173 offset:8192
	v_add_u32_e32 v175, 0x5800, v174
	s_waitcnt lgkmcnt(0)
	global_store_dwordx4 v175, v[176:179], s[98:99]
	s_barrier
	s_andn2_b64 vcc, exec, s[18:19]
	s_cbranch_vccnz .LBB0_769
	s_andn2_b64 vcc, exec, s[4:5]
	s_cbranch_vccnz .LBB0_768
	s_barrier
	s_branch .LBB0_768

; #define PG8_STAGE(bufoff, gbase, voff) do { _Pragma("unroll") for (int _i = 0; _i < 2; ++_i) \
;         __builtin_amdgcn_global_load_lds((const unsigned*)((const char*)(gbase) + (voff)[_i]), (PG8_LAS unsigned*)(lds + (bufoff) + ldsw + _i * 8192), 16, 0, 0); } while (0)
; #define PG8_WAIT_V(n) asm volatile("s_waitcnt vmcnt(" #n ")" ::: "memory")
; #define PG8_BAR __builtin_amdgcn_s_barrier()
; template <class Epi, class Sched, bool ALIGN_EPI = false, bool SP2 = false>
; __device__ __forceinline__ void gemm_phase(PG8_LAS unsigned char* lds, const Gemm g, const Sched& S, const Epi& E, int wv) {
;     ...
;     for (int i = 0; i < 2; ++i) { int R, C; stage_rc(tid * 16 + i * 8192, R, C); const int Rb = Epi::PERM ? ((R & ~31) + perm32(R & 31)) : R;
;         voffA[i] = (unsigned)(R * K + C) * 2u; voffB[i] = (unsigned)(Rb * K + C) * 2u; }
;     const size_t kstep = (size_t)(BK * 2);
;     const size_t hstep = (size_t)HALF * K * 2;
;     const size_t tstep = 2 * hstep;
;     const unsigned ldsw = (unsigned)wid * 1024u;
;     const int aoff = lds_byte(wr * 64 + fr, fq * 8), boff = lds_byte(wc * 32 + fr, fq * 8);
;     ...
;     const char* cA = (const char*)g.A + (size_t)cur.pm * tstep; const char* cB = (const char*)g.Bt + (size_t)cur.pn * tstep;
;     S.a_ready(cur);
;     if constexpr (SP2) {
;         PG8_STAGE(PG8_SB(0, 0), cB, voffB); PG8_STAGE(PG8_SB(0, 1), cB + hstep, voffB); PG8_STAGE(PG8_SA(0, 0), cA, voffA); PG8_STAGE(PG8_SA(0, 1), cA + hstep, voffA);
;         if (wr == 1) PG8_BAR;
;         PG8_WAIT_V(2); PG8_BAR;
;         PG8_STAGE(PG8_SB(1, 0), cB + kstep, voffB); PG8_STAGE(PG8_SA(1, 0), cA + kstep, voffA); PG8_STAGE(PG8_SB(1, 1), cB + hstep + kstep, voffB);
;         PG8_WAIT_V(6); PG8_BAR;
.LBB0_832:
	s_or_b64 exec, exec, s[4:5]
	s_mov_b64 s[4:5], 0
	v_readlane_b32 s12, v250, 0
	s_waitcnt lgkmcnt(0)
	v_mov_b32_e32 v0, v161
	s_barrier
	v_readlane_b32 s8, v250, 1
	v_add_u32_e32 v0, 0, v0
	v_add_u32_e32 v0, 0x201c0, v0
	ds_read_b64 v[0:1], v0
	v_readlane_b32 s9, v250, 2
	v_mov_b32_e32 v16, v183
	s_andn2_b64 vcc, exec, s[8:9]
	s_waitcnt lgkmcnt(0)
	v_readfirstlane_b32 s7, v0
	v_mov_b32_e32 v0, v161
	v_readfirstlane_b32 s6, v1
	v_add_u32_e32 v0, 0, v0
	v_add_u32_e32 v0, 0x201c8, v0
	ds_read_b64 v[0:1], v0
	s_waitcnt lgkmcnt(0)
	v_cndmask_b32_e64 v0, 0, 1, s[8:9]
	v_cmp_ne_u32_e64 s[10:11], 1, v0
	s_nop 0
	v_readfirstlane_b32 s24, v16
	v_writelane_b32 v250, s10, 42
	s_nop 1
	v_writelane_b32 v250, s11, 43
	s_cbranch_vccnz .LBB0_868
	v_lshlrev_b32_e32 v0, 4, v16
	v_add_u32_e32 v1, 0x2000, v0
	v_ashrrev_i32_e32 v2, 31, v1
	v_lshrrev_b32_e32 v2, 22, v2
	v_add_u32_e32 v2, v1, v2
	v_ashrrev_i32_e32 v8, 10, v2
	v_mul_i32_i24_e32 v2, 0x400, v8
	v_sub_u32_e32 v1, v1, v2
	v_lshrrev_b32_e32 v2, 4, v1
	v_bitop3_b32 v1, v2, v1, 32 bitop3:0x6c
	v_ashrrev_i32_e32 v2, 31, v1
	v_lshrrev_b32_e32 v2, 26, v2
	v_add_u32_e32 v2, v1, v2
	v_lshlrev_b32_e32 v3, 3, v8
	v_ashrrev_i32_e32 v9, 6, v2
	v_and_b32_e32 v3, -16, v3
	s_add_u32 s13, s7, s4
	v_add_u32_e32 v3, v9, v3
	s_addc_u32 s18, s6, s5
	v_and_b32_e32 v4, 3, v9
	s_mov_b32 s6, 0xffffe0
	v_lshrrev_b32_e32 v5, 2, v3
	v_lshlrev_b32_e32 v6, 1, v3
	v_and_b32_e32 v2, 0xc0, v2
	v_and_or_b32 v4, v3, s6, v4
	v_and_b32_e32 v5, 4, v5
	v_and_b32_e32 v6, 24, v6
	v_sub_u32_e32 v1, v1, v2
	v_or3_b32 v4, v4, v5, v6
	v_lshlrev_b32_e32 v5, 5, v8
	v_ashrrev_i16_sdwa v1, v193, sext(v1) dst_sel:DWORD dst_unused:UNUSED_PAD src0_sel:DWORD src1_sel:BYTE_0
	v_and_b32_e32 v10, 32, v5
	v_bfe_i32 v11, v1, 0, 16
	s_movk_i32 s7, 0xb00
	v_mul_u32_u24_e32 v4, 0xb00, v4
	v_add_u32_e32 v1, v10, v11
	v_lshlrev_b32_e32 v2, 6, v3
	v_add_lshl_u32 v152, v4, v1, 1
	v_add_lshl_u32 v154, v1, v2, 1
	v_bfe_i32 v1, v16, 27, 1
	v_lshrrev_b32_e32 v1, 22, v1
	v_add_u32_e32 v1, v0, v1
	v_and_b32_e32 v1, 0xfffffc00, v1
	v_sub_u32_e32 v0, v0, v1
	v_lshrrev_b32_e32 v1, 4, v0
	v_ashrrev_i32_e32 v2, 31, v16
	v_bitop3_b32 v0, v1, v0, 32 bitop3:0x6c
	v_lshrrev_b32_e32 v2, 26, v2
	v_ashrrev_i32_e32 v1, 31, v0
	v_add_u32_e32 v2, v16, v2
	s_add_u32 s14, s13, 0xd600000
	v_lshrrev_b32_e32 v1, 26, v1
	v_ashrrev_i32_e32 v13, 6, v2
	s_addc_u32 s15, s18, 0
	s_mul_i32 s5, s12, 0x2900000
	v_add_u32_e32 v1, v0, v1
	v_lshlrev_b32_e32 v2, 3, v13
	s_mul_hi_i32 s4, s12, 0x2900000
	s_add_u32 s19, s13, s5
	v_ashrrev_i32_e32 v12, 6, v1
	v_and_b32_e32 v2, -16, v2
	s_addc_u32 s21, s18, s4
	v_add_u32_e32 v2, v12, v2
	s_add_u32 s16, s19, 0xb00000
	v_and_b32_e32 v3, 3, v12
	v_lshrrev_b32_e32 v4, 2, v2
	v_lshlrev_b32_e32 v5, 1, v2
	v_and_b32_e32 v1, 0xc0, v1
	s_addc_u32 s29, s21, 0
	s_ashr_i32 s4, s24, 6
	v_and_or_b32 v3, v2, s6, v3
	v_and_b32_e32 v4, 4, v4
	v_and_b32_e32 v5, 24, v5
	v_sub_u32_e32 v0, v0, v1
	s_ashr_i32 s5, s24, 8
	s_lshl_b32 s30, s4, 10
	v_or3_b32 v3, v3, v4, v5
	v_lshlrev_b32_e32 v4, 5, v13
	v_ashrrev_i16_sdwa v0, v193, sext(v0) dst_sel:DWORD dst_unused:UNUSED_PAD src0_sel:DWORD src1_sel:BYTE_0
	v_readlane_b32 s6, v250, 14
	v_and_b32_e32 v14, 32, v4
	v_bfe_i32 v15, v0, 0, 16
	s_add_u32 s44, s16, s6
	v_readlane_b32 s6, v250, 12
	v_mul_u32_u24_e32 v3, 0xb00, v3
	v_add_u32_e32 v0, v14, v15
	s_addc_u32 s45, s29, s6
	s_add_i32 s31, s30, 0
	v_add_lshl_u32 v160, v3, v0, 1
	s_add_i32 m0, s31, 0x10000
	v_lshlrev_b32_e32 v1, 6, v2
	global_load_lds_dwordx4 v160, s[44:45]
	s_add_i32 m0, s31, 0x12000
	s_add_u32 s6, s44, 0xb0000
	global_load_lds_dwordx4 v152, s[44:45]
	s_addc_u32 s7, s45, 0
	s_add_i32 m0, s31, 0x14000
	v_add_lshl_u32 v156, v0, v1, 1
	global_load_lds_dwordx4 v160, s[6:7]
	s_add_i32 m0, s31, 0x16000
	v_mov_b32_e32 v153, v161
	global_load_lds_dwordx4 v152, s[6:7]
	v_readlane_b32 s6, v250, 11
	s_add_u32 s6, s14, s6
	v_readlane_b32 s7, v250, 10
	s_addc_u32 s7, s15, s7
	s_add_i32 s52, s31, 0x2000
	s_mov_b32 m0, s31
	s_mov_b64 s[98:99], 0x8000
	s_add_u32 s8, s6, 0x4000
	s_addc_u32 s9, s7, 0
	global_load_lds_dwordx4 v156, s[6:7]
	s_mov_b32 m0, s52
	s_add_i32 s53, s31, 0x4000
	global_load_lds_dwordx4 v154, s[6:7]
	s_mov_b32 m0, s53
	s_add_i32 s54, s31, 0x6000
	global_load_lds_dwordx4 v156, s[8:9]
	s_mov_b32 m0, s54
	v_mov_b32_e32 v157, v161
	global_load_lds_dwordx4 v154, s[8:9]
	v_mov_b32_e32 v155, v161
	s_cmp_eq_u32 s5, 1
	v_lshl_add_u64 v[6:7], s[44:45], 0, v[160:161]
	v_lshl_add_u64 v[4:5], s[44:45], 0, v[152:153]
	v_lshl_add_u64 v[0:1], s[6:7], 0, v[156:157]
	s_cselect_b64 s[8:9], -1, 0
	s_cmp_lg_u32 s5, 1
	v_lshl_add_u64 v[2:3], s[6:7], 0, v[154:155]
	s_cbranch_scc1 .LBB0_835
	s_barrier
.LBB0_835:
	s_add_u32 s10, s13, 0x5200000
	s_addc_u32 s11, s18, 0
	s_mul_i32 s26, s12, 0xfd808000
	s_mul_hi_i32 s25, s12, 0xfd808000
	s_add_u32 s19, s19, s26
	s_addc_u32 s21, s21, s25
	s_add_u32 s25, s13, 0x28700000
	s_addc_u32 s13, s18, 0
	s_cmp_eq_u32 s12, 0
	s_cselect_b32 s13, s11, s13
	s_cselect_b32 s12, s10, s25
	s_add_u32 s18, s19, 0x28342000
	s_addc_u32 s19, s21, 0
	s_lshl_b32 s4, s4, 5
	v_and_b32_e32 v17, 48, v16
	v_lshlrev_b32_e32 v18, 6, v16
	s_movk_i32 s21, 0x3c0
	v_lshlrev_b32_e32 v16, 2, v16
	s_and_b32 s60, s4, 0x60
	s_add_i32 m0, s31, 0x18000
	v_lshl_add_u64 v[6:7], v[6:7], 0, s[74:75]
	s_lshl_b32 s57, s5, 6
	s_lshl_b32 s5, s5, 13
	v_and_or_b32 v17, v18, s21, v17
	v_and_b32_e32 v16, 32, v16
	s_lshl_b32 s4, s60, 7
	s_waitcnt vmcnt(2)
	s_barrier
	global_load_lds_dwordx4 v[6:7], off
	v_lshl_add_u64 v[4:5], v[4:5], 0, s[74:75]
	s_add_i32 m0, s31, 0x1a000
	s_add_i32 s61, s31, 0x8000
	s_add_i32 s62, s31, 0xa000
	v_bitop3_b32 v170, s4, v17, v16 bitop3:0xf6
	global_load_lds_dwordx4 v[4:5], off
	v_lshl_add_u64 v[0:1], v[0:1], 0, s[98:99]
	s_mov_b32 m0, s61
	s_add_u32 s4, s44, 0xb0080
	v_bitop3_b32 v18, v17, s5, v16 bitop3:0xde
	global_load_lds_dwordx4 v[0:1], off
	v_lshl_add_u64 v[0:1], v[2:3], 0, s[98:99]
	s_mov_b32 m0, s62
	s_addc_u32 s5, s45, 0
	global_load_lds_dwordx4 v[0:1], off
	s_add_i32 m0, s31, 0x1c000
	v_lshl_add_u64 v[0:1], s[4:5], 0, v[160:161]
	global_load_lds_dwordx4 v[0:1], off
	v_lshl_add_u64 v[0:1], s[4:5], 0, v[152:153]
	s_add_i32 m0, s31, 0x1e000
	s_movk_i32 s21, 0x40
	global_load_lds_dwordx4 v[0:1], off
	s_cmpk_lt_u32 s24, 0x100
	v_lshrrev_b32_e32 v1, 1, v13
	v_mul_lo_u32 v0, v12, s21
	s_mov_b32 s24, 0x400
	v_mad_u64_u32 v[0:1], s[4:5], v1, s24, v[0:1]
	v_or_b32_e32 v0, v0, v14
	v_add_lshl_u32 v0, v0, v15, 1
	v_mov_b32_e32 v1, v161
	s_mov_b64 s[40:41], 0xc000
	v_lshl_add_u64 v[158:159], v[0:1], 0, s[40:41]
	v_lshrrev_b32_e32 v1, 1, v8
	v_mul_lo_u32 v0, v9, s21
	v_mad_u64_u32 v[0:1], s[4:5], v1, s24, v[0:1]
	s_waitcnt vmcnt(6)
	v_or_b32_e32 v0, v0, v10
	v_add_lshl_u32 v0, v0, v11, 1
	v_mov_b32_e32 v1, v161
	v_readlane_b32 s4, v250, 27
	s_mov_b32 s56, 0
	s_cselect_b64 s[34:35], -1, 0
	v_lshl_add_u64 v[162:163], v[0:1], 0, s[40:41]
	v_add_u32_e32 v171, 0, v18
	v_readlane_b32 s65, v250, 13
	s_mov_b32 s66, s4
	s_barrier
	v_readlane_b32 s5, v250, 28
	s_branch .LBB0_838

; #define PG8_STAGE(bufoff, gbase, voff) do { _Pragma("unroll") for (int _i = 0; _i < 2; ++_i) \
;         __builtin_amdgcn_global_load_lds((const unsigned*)((const char*)(gbase) + (voff)[_i]), (PG8_LAS unsigned*)(lds + (bufoff) + ldsw + _i * 8192), 16, 0, 0); } while (0)
; #define PG8_LDA(dst, b, h) do { _Pragma("unroll") for (int m = 0; m < 4; ++m) _Pragma("unroll") for (int k = 0; k < 2; ++k) dst[m][k] = *(const PG8_LAS bf16x8*)(lds + PG8_SA(b, h) + aoff + m * 2048 + k * 1024); } while (0)
; #define PG8_LDB(dst, b, h) do { _Pragma("unroll") for (int n = 0; n < 2; ++n) _Pragma("unroll") for (int k = 0; k < 2; ++k) dst[n][k] = *(const PG8_LAS bf16x8*)(lds + PG8_SB(b, h) + boff + n * 2048 + k * 1024); } while (0)
; #define PG8_MMA(ai, bj, At, Bt) do { __builtin_amdgcn_s_setprio(1); _Pragma("unroll") for (int m = 0; m < 4; ++m) _Pragma("unroll") for (int n = 0; n < 2; ++n) _Pragma("unroll") for (int k = 0; k < 2; ++k) \
;         acc[ai][bj][m][n] = __builtin_amdgcn_mfma_f32_16x16x32_bf16(Bt[n][k], At[m][k], acc[ai][bj][m][n], 0, 0, 0); __builtin_amdgcn_s_setprio(0); } while (0)
; #define PG8_BAR __builtin_amdgcn_s_barrier()
; template <class Epi, class Sched, bool ALIGN_EPI = false, bool SP2 = false>
; __device__ __forceinline__ void gemm_phase(PG8_LAS unsigned char* lds, const Gemm g, const Sched& S, const Epi& E, int wv) {
;     ...
;         for (int t = 0; t < nt; t += 2) {
;             const bool last = (t == nt - 2);
;             const char* a1 = cA + (size_t)(t + 1) * kstep;
;             const char* a2 = last ? nA : cA + (size_t)(t + 2) * kstep; const char* b2 = last ? nB : cB + (size_t)(t + 2) * kstep;
;             const char* a3 = a2 + kstep; const char* b3 = b2 + kstep;
;             if (last && has_next) S.a_ready(nxt);
;             if constexpr (SP2) {
;             PG8_LDB(B0, 0, 0); PG8_LDB(B1, 0, 1); PG8_SCHED; PG8_LDA(At, 0, 0); PG8_STAGE(PG8_SA(1, 1), a1 + hstep, voffA);
;             PG8_WAIT_V(8); PG8_WAIT_L(0); PG8_BAR; PG8_MMA(0, 0, At, B0); PG8_MMA(0, 1, At, B1); PG8_BAR; PG8_SCHED;
;     ...
; #pragma unroll
;         for (int a = 0; a < 2; ++a)
; #pragma unroll
;             for (int b = 0; b < 2; ++b)
; #pragma unroll
;                 for (int m = 0; m < 4; ++m)
; #pragma unroll
;                     for (int n = 0; n < 2; ++n) acc[a][b][m][n] = (f32x4){0.f, 0.f, 0.f, 0.f};
;         cur = nxt; cA = nA; cB = nB; ++ui;
.LBB0_844:
	s_add_u32 s24, s44, 0x100
	v_mov_b32_e32 v0, 0
	s_addc_u32 s25, s45, 0
	s_mov_b32 s67, -2
	s_waitcnt lgkmcnt(0)
	v_mov_b32_e32 v1, v0
	v_mov_b32_e32 v2, v0
	v_mov_b32_e32 v3, v0
	v_mov_b32_e32 v4, v0
	v_mov_b32_e32 v5, v0
	v_mov_b32_e32 v6, v0
	v_mov_b32_e32 v7, v0
	v_mov_b32_e32 v16, v0
	v_mov_b32_e32 v17, v0
	v_mov_b32_e32 v18, v0
	v_mov_b32_e32 v19, v0
	v_mov_b32_e32 v20, v0
	v_mov_b32_e32 v21, v0
	v_mov_b32_e32 v22, v0
	v_mov_b32_e32 v23, v0
	v_mov_b32_e32 v32, v0
	v_mov_b32_e32 v33, v0
	v_mov_b32_e32 v34, v0
	v_mov_b32_e32 v35, v0
	v_mov_b32_e32 v36, v0
	v_mov_b32_e32 v37, v0
	v_mov_b32_e32 v38, v0
	v_mov_b32_e32 v39, v0
	v_mov_b32_e32 v48, v0
	v_mov_b32_e32 v49, v0
	v_mov_b32_e32 v50, v0
	v_mov_b32_e32 v51, v0
	v_mov_b32_e32 v52, v0
	v_mov_b32_e32 v53, v0
	v_mov_b32_e32 v54, v0
	v_mov_b32_e32 v55, v0
	v_mov_b32_e32 v8, v0
	v_mov_b32_e32 v9, v0
	v_mov_b32_e32 v10, v0
	v_mov_b32_e32 v11, v0
	v_mov_b32_e32 v12, v0
	v_mov_b32_e32 v13, v0
	v_mov_b32_e32 v14, v0
	v_mov_b32_e32 v15, v0
	v_mov_b32_e32 v24, v0
	v_mov_b32_e32 v25, v0
	v_mov_b32_e32 v26, v0
	v_mov_b32_e32 v27, v0
	v_mov_b32_e32 v28, v0
	v_mov_b32_e32 v29, v0
	v_mov_b32_e32 v30, v0
	v_mov_b32_e32 v31, v0
	v_mov_b32_e32 v40, v0
	v_mov_b32_e32 v41, v0
	v_mov_b32_e32 v42, v0
	v_mov_b32_e32 v43, v0
	v_mov_b32_e32 v44, v0
	v_mov_b32_e32 v45, v0
	v_mov_b32_e32 v46, v0
	v_mov_b32_e32 v47, v0
	v_mov_b32_e32 v56, v0
	v_mov_b32_e32 v57, v0
	v_mov_b32_e32 v58, v0
	v_mov_b32_e32 v59, v0
	v_mov_b32_e32 v60, v0
	v_mov_b32_e32 v61, v0
	v_mov_b32_e32 v62, v0
	v_mov_b32_e32 v63, v0
	v_mov_b32_e32 v64, v0
	v_mov_b32_e32 v65, v0
	v_mov_b32_e32 v66, v0
	v_mov_b32_e32 v67, v0
	v_mov_b32_e32 v68, v0
	v_mov_b32_e32 v69, v0
	v_mov_b32_e32 v70, v0
	v_mov_b32_e32 v71, v0
	v_mov_b32_e32 v80, v0
	v_mov_b32_e32 v81, v0
	v_mov_b32_e32 v82, v0
	v_mov_b32_e32 v83, v0
	v_mov_b32_e32 v84, v0
	v_mov_b32_e32 v85, v0
	v_mov_b32_e32 v86, v0
	v_mov_b32_e32 v87, v0
	v_mov_b32_e32 v96, v0
	v_mov_b32_e32 v97, v0
	v_mov_b32_e32 v98, v0
	v_mov_b32_e32 v99, v0
	v_mov_b32_e32 v100, v0
	v_mov_b32_e32 v101, v0
	v_mov_b32_e32 v102, v0
	v_mov_b32_e32 v103, v0
	v_mov_b32_e32 v112, v0
	v_mov_b32_e32 v113, v0
	v_mov_b32_e32 v114, v0
	v_mov_b32_e32 v115, v0
	v_mov_b32_e32 v116, v0
	v_mov_b32_e32 v117, v0
	v_mov_b32_e32 v118, v0
	v_mov_b32_e32 v119, v0
	v_mov_b32_e32 v72, v0
	v_mov_b32_e32 v73, v0
	v_mov_b32_e32 v74, v0
	v_mov_b32_e32 v75, v0
	v_mov_b32_e32 v76, v0
	v_mov_b32_e32 v77, v0
	v_mov_b32_e32 v78, v0
	v_mov_b32_e32 v79, v0
	v_mov_b32_e32 v88, v0
	v_mov_b32_e32 v89, v0
	v_mov_b32_e32 v90, v0
	v_mov_b32_e32 v91, v0
	v_mov_b32_e32 v92, v0
	v_mov_b32_e32 v93, v0
	v_mov_b32_e32 v94, v0
	v_mov_b32_e32 v95, v0
	v_mov_b32_e32 v104, v0
	v_mov_b32_e32 v105, v0
	v_mov_b32_e32 v106, v0
	v_mov_b32_e32 v107, v0
	v_mov_b32_e32 v108, v0
	v_mov_b32_e32 v109, v0
	v_mov_b32_e32 v110, v0
	v_mov_b32_e32 v111, v0
	v_mov_b32_e32 v120, v0
	v_mov_b32_e32 v121, v0
	v_mov_b32_e32 v122, v0
	v_mov_b32_e32 v123, v0
	v_mov_b32_e32 v124, v0
	v_mov_b32_e32 v125, v0
	v_mov_b32_e32 v126, v0
	v_mov_b32_e32 v127, v0
.LBB0_845:
	s_add_u32 s44, s6, 0x10000
	s_addc_u32 s45, s7, 0
	s_add_i32 s21, 0, 0x10000
	s_cmp_eq_u32 s67, 40
	s_cselect_b32 s51, s41, s45
	s_cselect_b32 s50, s40, s44
	s_cselect_b32 s49, s43, s25
	s_cselect_b32 s48, s42, s24
	s_add_i32 s26, 0, 0x14000
	v_add_u32_e32 v140, s21, v170
	v_add_u32_e32 v168, s26, v170
	ds_read_b128 v[128:131], v140
	ds_read_b128 v[132:135], v140 offset:1024
	ds_read_b128 v[136:139], v140 offset:2048
	ds_read_b128 v[140:143], v140 offset:3072
	ds_read_b128 v[144:147], v168
	ds_read_b128 v[148:151], v168 offset:1024
	ds_read_b128 v[164:167], v168 offset:2048
	ds_read_b128 v[172:175], v168 offset:3072
	v_lshl_add_u64 v[168:169], s[6:7], 0, v[158:159]
	s_add_i32 m0, s31, 0xc000
	ds_read_b128 v[176:179], v171
	ds_read_b128 v[204:207], v171 offset:1024
	ds_read_b128 v[208:211], v171 offset:2048
	ds_read_b128 v[212:215], v171 offset:3072
	ds_read_b128 v[216:219], v171 offset:4096
	ds_read_b128 v[220:223], v171 offset:5120
	ds_read_b128 v[224:227], v171 offset:6144
	ds_read_b128 v[228:231], v171 offset:7168
	global_load_lds_dwordx4 v[168:169], off
	v_lshl_add_u64 v[168:169], s[6:7], 0, v[162:163]
	s_add_i32 m0, s31, 0xe000
	s_nop 0
	global_load_lds_dwordx4 v[168:169], off
	s_waitcnt vmcnt(8)
	s_waitcnt lgkmcnt(0)
	s_barrier
	s_setprio 1
	s_waitcnt lgkmcnt(0)
	v_mfma_f32_16x16x32_bf16 v[124:127], v[128:131], v[176:179], v[124:127]
	v_mfma_f32_16x16x32_bf16 v[120:123], v[136:139], v[176:179], v[120:123]
	v_mfma_f32_16x16x32_bf16 v[108:111], v[128:131], v[208:211], v[108:111]
	v_mfma_f32_16x16x32_bf16 v[104:107], v[136:139], v[208:211], v[104:107]
	v_mfma_f32_16x16x32_bf16 v[92:95], v[128:131], v[216:219], v[92:95]
	v_mfma_f32_16x16x32_bf16 v[88:91], v[136:139], v[216:219], v[88:91]
	v_mfma_f32_16x16x32_bf16 v[76:79], v[128:131], v[224:227], v[76:79]
	v_mfma_f32_16x16x32_bf16 v[72:75], v[136:139], v[224:227], v[72:75]
	v_mfma_f32_16x16x32_bf16 v[124:127], v[132:135], v[204:207], v[124:127]
	v_mfma_f32_16x16x32_bf16 v[120:123], v[140:143], v[204:207], v[120:123]
	v_mfma_f32_16x16x32_bf16 v[108:111], v[132:135], v[212:215], v[108:111]
	v_mfma_f32_16x16x32_bf16 v[104:107], v[140:143], v[212:215], v[104:107]
	v_mfma_f32_16x16x32_bf16 v[92:95], v[132:135], v[220:223], v[92:95]
	v_mfma_f32_16x16x32_bf16 v[88:91], v[140:143], v[220:223], v[88:91]
	v_mfma_f32_16x16x32_bf16 v[76:79], v[132:135], v[228:231], v[76:79]
	v_mfma_f32_16x16x32_bf16 v[72:75], v[140:143], v[228:231], v[72:75]
	s_setprio 0
	s_setprio 1
	v_mfma_f32_16x16x32_bf16 v[116:119], v[144:147], v[176:179], v[116:119]
	v_mfma_f32_16x16x32_bf16 v[112:115], v[164:167], v[176:179], v[112:115]
	v_mfma_f32_16x16x32_bf16 v[100:103], v[144:147], v[208:211], v[100:103]
	v_mfma_f32_16x16x32_bf16 v[96:99], v[164:167], v[208:211], v[96:99]
	v_mfma_f32_16x16x32_bf16 v[84:87], v[144:147], v[216:219], v[84:87]
	v_mfma_f32_16x16x32_bf16 v[80:83], v[164:167], v[216:219], v[80:83]
	v_mfma_f32_16x16x32_bf16 v[68:71], v[144:147], v[224:227], v[68:71]
	v_mfma_f32_16x16x32_bf16 v[64:67], v[164:167], v[224:227], v[64:67]
	v_mfma_f32_16x16x32_bf16 v[116:119], v[148:151], v[204:207], v[116:119]
	v_mfma_f32_16x16x32_bf16 v[112:115], v[172:175], v[204:207], v[112:115]
	v_mfma_f32_16x16x32_bf16 v[100:103], v[148:151], v[212:215], v[100:103]
	v_mfma_f32_16x16x32_bf16 v[96:99], v[172:175], v[212:215], v[96:99]
	v_mfma_f32_16x16x32_bf16 v[84:87], v[148:151], v[220:223], v[84:87]
	v_mfma_f32_16x16x32_bf16 v[80:83], v[172:175], v[220:223], v[80:83]
	v_mfma_f32_16x16x32_bf16 v[68:71], v[148:151], v[228:231], v[68:71]
	v_mfma_f32_16x16x32_bf16 v[64:67], v[172:175], v[228:231], v[64:67]
	s_setprio 0
	s_barrier
; #define PG8_STAGE(bufoff, gbase, voff) do { _Pragma("unroll") for (int _i = 0; _i < 2; ++_i) \
;         __builtin_amdgcn_global_load_lds((const unsigned*)((const char*)(gbase) + (voff)[_i]), (PG8_LAS unsigned*)(lds + (bufoff) + ldsw + _i * 8192), 16, 0, 0); } while (0)
; #define PG8_LDA(dst, b, h) do { _Pragma("unroll") for (int m = 0; m < 4; ++m) _Pragma("unroll") for (int k = 0; k < 2; ++k) dst[m][k] = *(const PG8_LAS bf16x8*)(lds + PG8_SA(b, h) + aoff + m * 2048 + k * 1024); } while (0)
; #define PG8_LDB(dst, b, h) do { _Pragma("unroll") for (int n = 0; n < 2; ++n) _Pragma("unroll") for (int k = 0; k < 2; ++k) dst[n][k] = *(const PG8_LAS bf16x8*)(lds + PG8_SB(b, h) + boff + n * 2048 + k * 1024); } while (0)
; #define PG8_MMA(ai, bj, At, Bt) do { __builtin_amdgcn_s_setprio(1); _Pragma("unroll") for (int m = 0; m < 4; ++m) _Pragma("unroll") for (int n = 0; n < 2; ++n) _Pragma("unroll") for (int k = 0; k < 2; ++k) \
;         acc[ai][bj][m][n] = __builtin_amdgcn_mfma_f32_16x16x32_bf16(Bt[n][k], At[m][k], acc[ai][bj][m][n], 0, 0, 0); __builtin_amdgcn_s_setprio(0); } while (0)
; #define PG8_WAIT_V(n) asm volatile("s_waitcnt vmcnt(" #n ")" ::: "memory")
; #define PG8_WAIT_L(n) asm volatile("s_waitcnt lgkmcnt(" #n ")" ::: "memory")
; #define PG8_BAR __builtin_amdgcn_s_barrier()
; #define PG8_SCHED __builtin_amdgcn_sched_barrier(0)
; template <class Epi, class Sched, bool ALIGN_EPI = false, bool SP2 = false>
; __device__ __forceinline__ void gemm_phase(PG8_LAS unsigned char* lds, const Gemm g, const Sched& S, const Epi& E, int wv) {
;     ...
;             PG8_WAIT_V(8); PG8_WAIT_L(0); PG8_BAR; PG8_MMA(0, 0, At, B0); PG8_MMA(0, 1, At, B1); PG8_BAR; PG8_SCHED;
;             PG8_LDA(At, 0, 1); PG8_STAGE(PG8_SB(0, 0), b2, voffB); PG8_STAGE(PG8_SB(0, 1), b2 + hstep, voffB); PG8_STAGE(PG8_SA(0, 0), a2, voffA);
;             PG8_WAIT_V(8); PG8_WAIT_L(0); PG8_BAR; PG8_MMA(1, 0, At, B0); PG8_MMA(1, 1, At, B1); PG8_BAR; PG8_SCHED;
;             PG8_LDB(B0, 1, 0); PG8_LDB(B1, 1, 1); PG8_SCHED; PG8_LDA(At, 1, 0); PG8_STAGE(PG8_SA(0, 1), a2 + hstep, voffA);
;             PG8_WAIT_V(8); PG8_WAIT_L(0); PG8_BAR; PG8_MMA(0, 0, At, B0); PG8_MMA(0, 1, At, B1); PG8_BAR; PG8_SCHED;
	s_add_i32 s6, s21, s30
	v_lshl_add_u64 v[168:169], s[48:49], 0, v[160:161]
	s_mov_b32 m0, s6
	ds_read_b128 v[176:179], v171 offset:16384
	ds_read_b128 v[204:207], v171 offset:17408
	ds_read_b128 v[208:211], v171 offset:18432
	ds_read_b128 v[212:215], v171 offset:19456
	ds_read_b128 v[216:219], v171 offset:20480
	ds_read_b128 v[220:223], v171 offset:21504
	ds_read_b128 v[224:227], v171 offset:22528
	ds_read_b128 v[228:231], v171 offset:23552
	global_load_lds_dwordx4 v[168:169], off
	s_add_i32 m0, s6, 0x2000
	s_add_u32 s6, s48, 0xb0000
	v_lshl_add_u64 v[180:181], s[48:49], 0, v[152:153]
	s_addc_u32 s7, s49, 0
	s_add_i32 s21, s26, s30
	global_load_lds_dwordx4 v[180:181], off
	v_lshl_add_u64 v[232:233], s[6:7], 0, v[160:161]
	s_mov_b32 m0, s21
	v_lshl_add_u64 v[234:235], s[50:51], 0, v[154:155]
	global_load_lds_dwordx4 v[232:233], off
	v_lshl_add_u64 v[232:233], s[6:7], 0, v[152:153]
	s_add_i32 m0, s21, 0x2000
	s_nop 0
	global_load_lds_dwordx4 v[232:233], off
	v_lshl_add_u64 v[232:233], s[50:51], 0, v[156:157]
	s_mov_b32 m0, s31
	s_nop 0
	global_load_lds_dwordx4 v[232:233], off
	s_mov_b32 m0, s52
	s_nop 0
	global_load_lds_dwordx4 v[234:235], off
	s_waitcnt vmcnt(8)
	s_waitcnt lgkmcnt(0)
	s_barrier
	s_setprio 1
	s_waitcnt lgkmcnt(0)
	v_mfma_f32_16x16x32_bf16 v[60:63], v[128:131], v[176:179], v[60:63]
	v_mfma_f32_16x16x32_bf16 v[56:59], v[136:139], v[176:179], v[56:59]
	v_mfma_f32_16x16x32_bf16 v[44:47], v[128:131], v[208:211], v[44:47]
	v_mfma_f32_16x16x32_bf16 v[40:43], v[136:139], v[208:211], v[40:43]
	v_mfma_f32_16x16x32_bf16 v[28:31], v[128:131], v[216:219], v[28:31]
	v_mfma_f32_16x16x32_bf16 v[24:27], v[136:139], v[216:219], v[24:27]
	v_mfma_f32_16x16x32_bf16 v[12:15], v[128:131], v[224:227], v[12:15]
	v_mfma_f32_16x16x32_bf16 v[8:11], v[136:139], v[224:227], v[8:11]
	v_mfma_f32_16x16x32_bf16 v[60:63], v[132:135], v[204:207], v[60:63]
	v_mfma_f32_16x16x32_bf16 v[56:59], v[140:143], v[204:207], v[56:59]
	v_mfma_f32_16x16x32_bf16 v[44:47], v[132:135], v[212:215], v[44:47]
	v_mfma_f32_16x16x32_bf16 v[40:43], v[140:143], v[212:215], v[40:43]
	v_mfma_f32_16x16x32_bf16 v[28:31], v[132:135], v[220:223], v[28:31]
	v_mfma_f32_16x16x32_bf16 v[24:27], v[140:143], v[220:223], v[24:27]
	v_mfma_f32_16x16x32_bf16 v[12:15], v[132:135], v[228:231], v[12:15]
	v_mfma_f32_16x16x32_bf16 v[8:11], v[140:143], v[228:231], v[8:11]
	s_setprio 0
	s_setprio 1
	v_mfma_f32_16x16x32_bf16 v[52:55], v[144:147], v[176:179], v[52:55]
	v_mfma_f32_16x16x32_bf16 v[48:51], v[164:167], v[176:179], v[48:51]
	v_mfma_f32_16x16x32_bf16 v[36:39], v[144:147], v[208:211], v[36:39]
	v_mfma_f32_16x16x32_bf16 v[32:35], v[164:167], v[208:211], v[32:35]
	v_mfma_f32_16x16x32_bf16 v[20:23], v[144:147], v[216:219], v[20:23]
	v_mfma_f32_16x16x32_bf16 v[16:19], v[164:167], v[216:219], v[16:19]
	v_mfma_f32_16x16x32_bf16 v[4:7], v[144:147], v[224:227], v[4:7]
	v_mfma_f32_16x16x32_bf16 v[0:3], v[164:167], v[224:227], v[0:3]
	v_mfma_f32_16x16x32_bf16 v[52:55], v[148:151], v[204:207], v[52:55]
	v_mfma_f32_16x16x32_bf16 v[48:51], v[172:175], v[204:207], v[48:51]
	v_mfma_f32_16x16x32_bf16 v[36:39], v[148:151], v[212:215], v[36:39]
	v_mfma_f32_16x16x32_bf16 v[32:35], v[172:175], v[212:215], v[32:35]
	v_mfma_f32_16x16x32_bf16 v[20:23], v[148:151], v[220:223], v[20:23]
	v_mfma_f32_16x16x32_bf16 v[16:19], v[172:175], v[220:223], v[16:19]
	v_mfma_f32_16x16x32_bf16 v[4:7], v[148:151], v[228:231], v[4:7]
	v_mfma_f32_16x16x32_bf16 v[0:3], v[172:175], v[228:231], v[0:3]
	s_setprio 0
	s_barrier
	s_add_i32 s21, 0, 0x18000
	s_add_i32 s26, 0, 0x1c000
	v_add_u32_e32 v140, s21, v170
	v_add_u32_e32 v172, s26, v170
	ds_read_b128 v[128:131], v140
	ds_read_b128 v[132:135], v140 offset:1024
	ds_read_b128 v[136:139], v140 offset:2048
	ds_read_b128 v[140:143], v140 offset:3072
	ds_read_b128 v[144:147], v172
	ds_read_b128 v[148:151], v172 offset:1024
	ds_read_b128 v[164:167], v172 offset:2048
	ds_read_b128 v[172:175], v172 offset:3072
	s_add_u32 s6, s50, 0x4000
	s_addc_u32 s7, s51, 0
	s_mov_b32 m0, s53
	v_lshl_add_u64 v[236:237], s[6:7], 0, v[156:157]
	ds_read_b128 v[176:179], v171 offset:32768
	ds_read_b128 v[204:207], v171 offset:33792
	ds_read_b128 v[208:211], v171 offset:34816
	ds_read_b128 v[212:215], v171 offset:35840
	ds_read_b128 v[216:219], v171 offset:36864
	ds_read_b128 v[220:223], v171 offset:37888
	ds_read_b128 v[224:227], v171 offset:38912
	ds_read_b128 v[228:231], v171 offset:39936
	global_load_lds_dwordx4 v[236:237], off
	v_lshl_add_u64 v[236:237], s[6:7], 0, v[154:155]
	s_mov_b32 m0, s54
	s_nop 0
	global_load_lds_dwordx4 v[236:237], off
	s_waitcnt vmcnt(8)
	s_waitcnt lgkmcnt(0)
	s_barrier
; #define PG8_STAGE(bufoff, gbase, voff) do { _Pragma("unroll") for (int _i = 0; _i < 2; ++_i) \
;         __builtin_amdgcn_global_load_lds((const unsigned*)((const char*)(gbase) + (voff)[_i]), (PG8_LAS unsigned*)(lds + (bufoff) + ldsw + _i * 8192), 16, 0, 0); } while (0)
; #define PG8_LDA(dst, b, h) do { _Pragma("unroll") for (int m = 0; m < 4; ++m) _Pragma("unroll") for (int k = 0; k < 2; ++k) dst[m][k] = *(const PG8_LAS bf16x8*)(lds + PG8_SA(b, h) + aoff + m * 2048 + k * 1024); } while (0)
; #define PG8_MMA(ai, bj, At, Bt) do { __builtin_amdgcn_s_setprio(1); _Pragma("unroll") for (int m = 0; m < 4; ++m) _Pragma("unroll") for (int n = 0; n < 2; ++n) _Pragma("unroll") for (int k = 0; k < 2; ++k) \
;         acc[ai][bj][m][n] = __builtin_amdgcn_mfma_f32_16x16x32_bf16(Bt[n][k], At[m][k], acc[ai][bj][m][n], 0, 0, 0); __builtin_amdgcn_s_setprio(0); } while (0)
; #define PG8_WAIT_V(n) asm volatile("s_waitcnt vmcnt(" #n ")" ::: "memory")
; #define PG8_WAIT_L(n) asm volatile("s_waitcnt lgkmcnt(" #n ")" ::: "memory")
; #define PG8_BAR __builtin_amdgcn_s_barrier()
; #define PG8_SCHED __builtin_amdgcn_sched_barrier(0)
; template <class Epi, class Sched, bool ALIGN_EPI = false, bool SP2 = false>
; __device__ __forceinline__ void gemm_phase(PG8_LAS unsigned char* lds, const Gemm g, const Sched& S, const Epi& E, int wv) {
;     ...
;         for (int t = 0; t < nt; t += 2) {
;     ...
;             PG8_WAIT_V(8); PG8_WAIT_L(0); PG8_BAR; PG8_MMA(0, 0, At, B0); PG8_MMA(0, 1, At, B1); PG8_BAR; PG8_SCHED;
;             PG8_LDA(At, 1, 1); PG8_STAGE(PG8_SB(1, 0), b3, voffB); PG8_STAGE(PG8_SB(1, 1), b3 + hstep, voffB); PG8_STAGE(PG8_SA(1, 0), a3, voffA);
;             PG8_WAIT_V(8); PG8_WAIT_L(0); PG8_BAR; PG8_MMA(1, 0, At, B0); PG8_MMA(1, 1, At, B1); PG8_BAR; PG8_SCHED;
	s_setprio 1
	s_waitcnt lgkmcnt(0)
	v_mfma_f32_16x16x32_bf16 v[124:127], v[128:131], v[176:179], v[124:127]
	v_mfma_f32_16x16x32_bf16 v[120:123], v[136:139], v[176:179], v[120:123]
	v_mfma_f32_16x16x32_bf16 v[108:111], v[128:131], v[208:211], v[108:111]
	v_mfma_f32_16x16x32_bf16 v[104:107], v[136:139], v[208:211], v[104:107]
	v_mfma_f32_16x16x32_bf16 v[92:95], v[128:131], v[216:219], v[92:95]
	v_mfma_f32_16x16x32_bf16 v[88:91], v[136:139], v[216:219], v[88:91]
	v_mfma_f32_16x16x32_bf16 v[76:79], v[128:131], v[224:227], v[76:79]
	v_mfma_f32_16x16x32_bf16 v[72:75], v[136:139], v[224:227], v[72:75]
	v_mfma_f32_16x16x32_bf16 v[124:127], v[132:135], v[204:207], v[124:127]
	v_mfma_f32_16x16x32_bf16 v[120:123], v[140:143], v[204:207], v[120:123]
	v_mfma_f32_16x16x32_bf16 v[108:111], v[132:135], v[212:215], v[108:111]
	v_mfma_f32_16x16x32_bf16 v[104:107], v[140:143], v[212:215], v[104:107]
	v_mfma_f32_16x16x32_bf16 v[92:95], v[132:135], v[220:223], v[92:95]
	v_mfma_f32_16x16x32_bf16 v[88:91], v[140:143], v[220:223], v[88:91]
	v_mfma_f32_16x16x32_bf16 v[76:79], v[132:135], v[228:231], v[76:79]
	v_mfma_f32_16x16x32_bf16 v[72:75], v[140:143], v[228:231], v[72:75]
	s_setprio 0
	s_setprio 1
	v_mfma_f32_16x16x32_bf16 v[116:119], v[144:147], v[176:179], v[116:119]
	v_mfma_f32_16x16x32_bf16 v[112:115], v[164:167], v[176:179], v[112:115]
	v_mfma_f32_16x16x32_bf16 v[100:103], v[144:147], v[208:211], v[100:103]
	v_mfma_f32_16x16x32_bf16 v[96:99], v[164:167], v[208:211], v[96:99]
	v_mfma_f32_16x16x32_bf16 v[84:87], v[144:147], v[216:219], v[84:87]
	v_mfma_f32_16x16x32_bf16 v[80:83], v[164:167], v[216:219], v[80:83]
	v_mfma_f32_16x16x32_bf16 v[68:71], v[144:147], v[224:227], v[68:71]
	v_mfma_f32_16x16x32_bf16 v[64:67], v[164:167], v[224:227], v[64:67]
	v_mfma_f32_16x16x32_bf16 v[116:119], v[148:151], v[204:207], v[116:119]
	v_mfma_f32_16x16x32_bf16 v[112:115], v[172:175], v[204:207], v[112:115]
	v_mfma_f32_16x16x32_bf16 v[100:103], v[148:151], v[212:215], v[100:103]
	v_mfma_f32_16x16x32_bf16 v[96:99], v[172:175], v[212:215], v[96:99]
	v_mfma_f32_16x16x32_bf16 v[84:87], v[148:151], v[220:223], v[84:87]
	v_mfma_f32_16x16x32_bf16 v[80:83], v[172:175], v[220:223], v[80:83]
	v_mfma_f32_16x16x32_bf16 v[68:71], v[148:151], v[228:231], v[68:71]
	v_mfma_f32_16x16x32_bf16 v[64:67], v[172:175], v[228:231], v[64:67]
	s_setprio 0
	s_barrier
	s_add_i32 s6, s21, s30
	v_lshl_add_u64 v[168:169], v[168:169], 0, s[74:75]
	s_mov_b32 m0, s6
	ds_read_b128 v[176:179], v171 offset:49152
	ds_read_b128 v[204:207], v171 offset:50176
	ds_read_b128 v[208:211], v171 offset:51200
	ds_read_b128 v[212:215], v171 offset:52224
	ds_read_b128 v[216:219], v171 offset:53248
	ds_read_b128 v[220:223], v171 offset:54272
	ds_read_b128 v[224:227], v171 offset:55296
	ds_read_b128 v[228:231], v171 offset:56320
	global_load_lds_dwordx4 v[168:169], off
	s_add_i32 m0, s6, 0x2000
	s_add_u32 s6, s48, 0xb0080
	v_lshl_add_u64 v[168:169], v[180:181], 0, s[74:75]
	s_addc_u32 s7, s49, 0
	s_add_i32 s21, s26, s30
	global_load_lds_dwordx4 v[168:169], off
	v_lshl_add_u64 v[168:169], s[6:7], 0, v[160:161]
	s_mov_b32 m0, s21
	s_nop 0
	global_load_lds_dwordx4 v[168:169], off
	v_lshl_add_u64 v[168:169], s[6:7], 0, v[152:153]
	s_add_i32 m0, s21, 0x2000
	s_nop 0
	global_load_lds_dwordx4 v[168:169], off
	v_lshl_add_u64 v[168:169], v[232:233], 0, s[98:99]
	s_mov_b32 m0, s61
	s_nop 0
	global_load_lds_dwordx4 v[168:169], off
	v_lshl_add_u64 v[168:169], v[234:235], 0, s[98:99]
	s_mov_b32 m0, s62
	s_nop 0
	global_load_lds_dwordx4 v[168:169], off
	s_waitcnt vmcnt(8)
	s_waitcnt lgkmcnt(0)
	s_barrier
	s_setprio 1
	s_waitcnt lgkmcnt(0)
	v_mfma_f32_16x16x32_bf16 v[60:63], v[128:131], v[176:179], v[60:63]
	v_mfma_f32_16x16x32_bf16 v[56:59], v[136:139], v[176:179], v[56:59]
	v_mfma_f32_16x16x32_bf16 v[44:47], v[128:131], v[208:211], v[44:47]
	v_mfma_f32_16x16x32_bf16 v[40:43], v[136:139], v[208:211], v[40:43]
	v_mfma_f32_16x16x32_bf16 v[28:31], v[128:131], v[216:219], v[28:31]
	v_mfma_f32_16x16x32_bf16 v[24:27], v[136:139], v[216:219], v[24:27]
	v_mfma_f32_16x16x32_bf16 v[12:15], v[128:131], v[224:227], v[12:15]
	v_mfma_f32_16x16x32_bf16 v[8:11], v[136:139], v[224:227], v[8:11]
	v_mfma_f32_16x16x32_bf16 v[60:63], v[132:135], v[204:207], v[60:63]
	v_mfma_f32_16x16x32_bf16 v[56:59], v[140:143], v[204:207], v[56:59]
	v_mfma_f32_16x16x32_bf16 v[44:47], v[132:135], v[212:215], v[44:47]
	v_mfma_f32_16x16x32_bf16 v[40:43], v[140:143], v[212:215], v[40:43]
	v_mfma_f32_16x16x32_bf16 v[28:31], v[132:135], v[220:223], v[28:31]
	v_mfma_f32_16x16x32_bf16 v[24:27], v[140:143], v[220:223], v[24:27]
	v_mfma_f32_16x16x32_bf16 v[12:15], v[132:135], v[228:231], v[12:15]
	v_mfma_f32_16x16x32_bf16 v[8:11], v[140:143], v[228:231], v[8:11]
	s_setprio 0
	s_setprio 1
	v_mfma_f32_16x16x32_bf16 v[52:55], v[144:147], v[176:179], v[52:55]
	v_mfma_f32_16x16x32_bf16 v[48:51], v[164:167], v[176:179], v[48:51]
	v_mfma_f32_16x16x32_bf16 v[36:39], v[144:147], v[208:211], v[36:39]
	v_mfma_f32_16x16x32_bf16 v[32:35], v[164:167], v[208:211], v[32:35]
	v_mfma_f32_16x16x32_bf16 v[20:23], v[144:147], v[216:219], v[20:23]
	v_mfma_f32_16x16x32_bf16 v[16:19], v[164:167], v[216:219], v[16:19]
	v_mfma_f32_16x16x32_bf16 v[4:7], v[144:147], v[224:227], v[4:7]
	v_mfma_f32_16x16x32_bf16 v[0:3], v[164:167], v[224:227], v[0:3]
	v_mfma_f32_16x16x32_bf16 v[52:55], v[148:151], v[204:207], v[52:55]
	v_mfma_f32_16x16x32_bf16 v[48:51], v[172:175], v[204:207], v[48:51]
	v_mfma_f32_16x16x32_bf16 v[36:39], v[148:151], v[212:215], v[36:39]
	v_mfma_f32_16x16x32_bf16 v[32:35], v[172:175], v[212:215], v[32:35]
	v_mfma_f32_16x16x32_bf16 v[20:23], v[148:151], v[220:223], v[20:23]
	v_mfma_f32_16x16x32_bf16 v[16:19], v[172:175], v[220:223], v[16:19]
	v_mfma_f32_16x16x32_bf16 v[4:7], v[148:151], v[228:231], v[4:7]
	v_mfma_f32_16x16x32_bf16 v[0:3], v[172:175], v[228:231], v[0:3]
	s_setprio 0
	s_barrier
	s_add_i32 s67, s67, 2
	s_add_u32 s24, s24, 0x100
	s_addc_u32 s25, s25, 0
	s_cmp_gt_u32 s67, 41
	s_mov_b64 s[6:7], s[44:45]
	s_cbranch_scc0 .LBB0_845
	s_and_b64 vcc, exec, s[34:35]
	s_cbranch_vccz .LBB0_848
	s_barrier

; template <class Epi, class Sched, bool ALIGN_EPI = false, bool SP2 = false>
; __device__ __forceinline__ void gemm_phase(PG8_LAS unsigned char* lds, const Gemm g, const Sched& S, const Epi& E, int wv) {
;     ...
;         const bool has_next = S.next(ui + 1, nxt);
;         const char* nA = has_next ? (const char*)g.A + (size_t)nxt.pm * tstep : cA; const char* nB = has_next ? (const char*)g.Bt + (size_t)nxt.pn * tstep : cB;
;     ...
; #pragma unroll
;         for (int a = 0; a < 2; ++a)
; #pragma unroll
;             for (int b = 0; b < 2; ++b)
; #pragma unroll
;                 for (int m = 0; m < 4; ++m)
; #pragma unroll
;                     for (int n = 0; n < 2; ++n) acc[a][b][m][n] = (f32x4){0.f, 0.f, 0.f, 0.f};
;         cur = nxt; cA = nA; cB = nB; ++ui;
.LBB0_1187:
	s_ashr_i32 s13, s12, 31
	s_lshl_b64 s[40:41], s[12:13], 19
	s_add_u32 s40, s14, s40
	s_addc_u32 s41, s15, s41
	s_and_b64 s[42:43], s[34:35], exec
	s_cselect_b32 s13, s41, s45
	s_cselect_b32 s63, s40, s44
	s_ashr_i32 s19, s18, 31
	s_lshl_b64 s[42:43], s[18:19], 19
	s_add_u32 s42, s16, s42
	s_addc_u32 s43, s29, s43
	s_and_b64 s[50:51], s[34:35], exec
	s_cselect_b32 s19, s43, s49
	s_cselect_b32 s64, s42, s48
	s_add_u32 s44, s44, 0x40080
	s_addc_u32 s45, s45, 0
	s_add_u32 s65, s48, 0x100
	v_mov_b32_e32 v0, 0
	s_addc_u32 s66, s49, 0
	s_mov_b32 s67, -2
	v_mov_b32_e32 v1, v0
	v_mov_b32_e32 v2, v0
	v_mov_b32_e32 v3, v0
	v_mov_b32_e32 v4, v0
	v_mov_b32_e32 v5, v0
	v_mov_b32_e32 v6, v0
	v_mov_b32_e32 v7, v0
	v_mov_b32_e32 v8, v0
	v_mov_b32_e32 v9, v0
	v_mov_b32_e32 v10, v0
	v_mov_b32_e32 v11, v0
	v_mov_b32_e32 v16, v0
	v_mov_b32_e32 v17, v0
	v_mov_b32_e32 v18, v0
	v_mov_b32_e32 v19, v0
	v_mov_b32_e32 v24, v0
	v_mov_b32_e32 v25, v0
	v_mov_b32_e32 v26, v0
	v_mov_b32_e32 v27, v0
	v_mov_b32_e32 v32, v0
	v_mov_b32_e32 v33, v0
	v_mov_b32_e32 v34, v0
	v_mov_b32_e32 v35, v0
	v_mov_b32_e32 v40, v0
	v_mov_b32_e32 v41, v0
	v_mov_b32_e32 v42, v0
	v_mov_b32_e32 v43, v0
	v_mov_b32_e32 v48, v0
	v_mov_b32_e32 v49, v0
	v_mov_b32_e32 v50, v0
	v_mov_b32_e32 v51, v0
	v_mov_b32_e32 v12, v0
	v_mov_b32_e32 v13, v0
	v_mov_b32_e32 v14, v0
	v_mov_b32_e32 v15, v0
	v_mov_b32_e32 v20, v0
	v_mov_b32_e32 v21, v0
	v_mov_b32_e32 v22, v0
	v_mov_b32_e32 v23, v0
	v_mov_b32_e32 v28, v0
	v_mov_b32_e32 v29, v0
	v_mov_b32_e32 v30, v0
	v_mov_b32_e32 v31, v0
	v_mov_b32_e32 v36, v0
	v_mov_b32_e32 v37, v0
	v_mov_b32_e32 v38, v0
	v_mov_b32_e32 v39, v0
	v_mov_b32_e32 v44, v0
	v_mov_b32_e32 v45, v0
	v_mov_b32_e32 v46, v0
	v_mov_b32_e32 v47, v0
	v_mov_b32_e32 v52, v0
	v_mov_b32_e32 v53, v0
	v_mov_b32_e32 v54, v0
	v_mov_b32_e32 v55, v0
	v_mov_b32_e32 v56, v0
	v_mov_b32_e32 v57, v0
	v_mov_b32_e32 v58, v0
	v_mov_b32_e32 v59, v0
	v_mov_b32_e32 v60, v0
	v_mov_b32_e32 v61, v0
	v_mov_b32_e32 v62, v0
	v_mov_b32_e32 v63, v0
	v_mov_b32_e32 v64, v0
	v_mov_b32_e32 v65, v0
	v_mov_b32_e32 v66, v0
	v_mov_b32_e32 v67, v0
	v_mov_b32_e32 v68, v0
	v_mov_b32_e32 v69, v0
	v_mov_b32_e32 v70, v0
	v_mov_b32_e32 v71, v0
	v_mov_b32_e32 v72, v0
	v_mov_b32_e32 v73, v0
	v_mov_b32_e32 v74, v0
	v_mov_b32_e32 v75, v0
	v_mov_b32_e32 v80, v0
	v_mov_b32_e32 v81, v0
	v_mov_b32_e32 v82, v0
	v_mov_b32_e32 v83, v0
	v_mov_b32_e32 v88, v0
	v_mov_b32_e32 v89, v0
	v_mov_b32_e32 v90, v0
	v_mov_b32_e32 v91, v0
	v_mov_b32_e32 v92, v0
	v_mov_b32_e32 v93, v0
	v_mov_b32_e32 v94, v0
	v_mov_b32_e32 v95, v0
	v_mov_b32_e32 v104, v0
	v_mov_b32_e32 v105, v0
	v_mov_b32_e32 v106, v0
	v_mov_b32_e32 v107, v0
	v_mov_b32_e32 v108, v0
	v_mov_b32_e32 v109, v0
	v_mov_b32_e32 v110, v0
	v_mov_b32_e32 v111, v0
	v_mov_b32_e32 v76, v0
	v_mov_b32_e32 v77, v0
	v_mov_b32_e32 v78, v0
	v_mov_b32_e32 v79, v0
	v_mov_b32_e32 v84, v0
	v_mov_b32_e32 v85, v0
	v_mov_b32_e32 v86, v0
	v_mov_b32_e32 v87, v0
	v_mov_b32_e32 v96, v0
	v_mov_b32_e32 v97, v0
	v_mov_b32_e32 v98, v0
	v_mov_b32_e32 v99, v0
	v_mov_b32_e32 v100, v0
	v_mov_b32_e32 v101, v0
	v_mov_b32_e32 v102, v0
	v_mov_b32_e32 v103, v0
	v_mov_b32_e32 v112, v0
	v_mov_b32_e32 v113, v0
	v_mov_b32_e32 v114, v0
	v_mov_b32_e32 v115, v0
	v_mov_b32_e32 v116, v0
	v_mov_b32_e32 v117, v0
	v_mov_b32_e32 v118, v0
	v_mov_b32_e32 v119, v0
	v_mov_b32_e32 v120, v0
	v_mov_b32_e32 v121, v0
	v_mov_b32_e32 v122, v0
	v_mov_b32_e32 v123, v0
	v_mov_b32_e32 v124, v0
	v_mov_b32_e32 v125, v0
	v_mov_b32_e32 v126, v0
	v_mov_b32_e32 v127, v0

; template <class Epi, class Sched, bool ALIGN_EPI = false, bool SP2 = false>
; __device__ __forceinline__ void gemm_phase(PG8_LAS unsigned char* lds, const Gemm g, const Sched& S, const Epi& E, int wv) {
;     ...
;         const bool has_next = S.next(ui + 1, nxt);
;         const char* nA = has_next ? (const char*)g.A + (size_t)nxt.pm * tstep : cA; const char* nB = has_next ? (const char*)g.Bt + (size_t)nxt.pn * tstep : cB;
;     ...
; #pragma unroll
;         for (int a = 0; a < 2; ++a)
; #pragma unroll
;             for (int b = 0; b < 2; ++b)
; #pragma unroll
;                 for (int m = 0; m < 4; ++m)
; #pragma unroll
;                     for (int n = 0; n < 2; ++n) acc[a][b][m][n] = (f32x4){0.f, 0.f, 0.f, 0.f};
;         cur = nxt; cA = nA; cB = nB; ++ui;
.LBB0_1955:
	s_ashr_i32 s19, s18, 31
	s_lshl_b64 s[42:43], s[18:19], 19
	s_add_u32 s42, s14, s42
	s_addc_u32 s43, s15, s43
	s_and_b64 s[44:45], s[40:41], exec
	s_cselect_b32 s19, s43, s5
	s_cselect_b32 s63, s42, s4
	s_ashr_i32 s35, s34, 31
	s_lshl_b64 s[44:45], s[34:35], 19
	s_add_u32 s44, s16, s44
	s_addc_u32 s45, s29, s45
	s_and_b64 s[50:51], s[40:41], exec
	s_cselect_b32 s35, s45, s49
	s_cselect_b32 s64, s44, s48
	s_add_u32 s4, s4, 0x40080
	s_addc_u32 s5, s5, 0
	s_add_u32 s65, s48, 0x100
	v_mov_b32_e32 v0, 0
	s_addc_u32 s66, s49, 0
	s_mov_b32 s67, -2
	s_waitcnt lgkmcnt(0)
	v_mov_b32_e32 v1, v0
	v_mov_b32_e32 v2, v0
	v_mov_b32_e32 v3, v0
	v_mov_b32_e32 v4, v0
	v_mov_b32_e32 v5, v0
	v_mov_b32_e32 v6, v0
	v_mov_b32_e32 v7, v0
	v_mov_b32_e32 v16, v0
	v_mov_b32_e32 v17, v0
	v_mov_b32_e32 v18, v0
	v_mov_b32_e32 v19, v0
	v_mov_b32_e32 v20, v0
	v_mov_b32_e32 v21, v0
	v_mov_b32_e32 v22, v0
	v_mov_b32_e32 v23, v0
	v_mov_b32_e32 v32, v0
	v_mov_b32_e32 v33, v0
	v_mov_b32_e32 v34, v0
	v_mov_b32_e32 v35, v0
	v_mov_b32_e32 v36, v0
	v_mov_b32_e32 v37, v0
	v_mov_b32_e32 v38, v0
	v_mov_b32_e32 v39, v0
	v_mov_b32_e32 v48, v0
	v_mov_b32_e32 v49, v0
	v_mov_b32_e32 v50, v0
	v_mov_b32_e32 v51, v0
	v_mov_b32_e32 v52, v0
	v_mov_b32_e32 v53, v0
	v_mov_b32_e32 v54, v0
	v_mov_b32_e32 v55, v0
	v_mov_b32_e32 v8, v0
	v_mov_b32_e32 v9, v0
	v_mov_b32_e32 v10, v0
	v_mov_b32_e32 v11, v0
	v_mov_b32_e32 v12, v0
	v_mov_b32_e32 v13, v0
	v_mov_b32_e32 v14, v0
	v_mov_b32_e32 v15, v0
	v_mov_b32_e32 v24, v0
	v_mov_b32_e32 v25, v0
	v_mov_b32_e32 v26, v0
	v_mov_b32_e32 v27, v0
	v_mov_b32_e32 v28, v0
	v_mov_b32_e32 v29, v0
	v_mov_b32_e32 v30, v0
	v_mov_b32_e32 v31, v0
	v_mov_b32_e32 v40, v0
	v_mov_b32_e32 v41, v0
	v_mov_b32_e32 v42, v0
	v_mov_b32_e32 v43, v0
	v_mov_b32_e32 v44, v0
	v_mov_b32_e32 v45, v0
	v_mov_b32_e32 v46, v0
	v_mov_b32_e32 v47, v0
	v_mov_b32_e32 v56, v0
	v_mov_b32_e32 v57, v0
	v_mov_b32_e32 v58, v0
	v_mov_b32_e32 v59, v0
	v_mov_b32_e32 v60, v0
	v_mov_b32_e32 v61, v0
	v_mov_b32_e32 v62, v0
	v_mov_b32_e32 v63, v0
	v_mov_b32_e32 v64, v0
	v_mov_b32_e32 v65, v0
	v_mov_b32_e32 v66, v0
	v_mov_b32_e32 v67, v0
	v_mov_b32_e32 v68, v0
	v_mov_b32_e32 v69, v0
	v_mov_b32_e32 v70, v0
	v_mov_b32_e32 v71, v0
	v_mov_b32_e32 v80, v0
	v_mov_b32_e32 v81, v0
	v_mov_b32_e32 v82, v0
	v_mov_b32_e32 v83, v0
	v_mov_b32_e32 v84, v0
	v_mov_b32_e32 v85, v0
	v_mov_b32_e32 v86, v0
	v_mov_b32_e32 v87, v0
	v_mov_b32_e32 v96, v0
	v_mov_b32_e32 v97, v0
	v_mov_b32_e32 v98, v0
	v_mov_b32_e32 v99, v0
	v_mov_b32_e32 v100, v0
	v_mov_b32_e32 v101, v0
	v_mov_b32_e32 v102, v0
	v_mov_b32_e32 v103, v0
	v_mov_b32_e32 v112, v0
	v_mov_b32_e32 v113, v0
	v_mov_b32_e32 v114, v0
	v_mov_b32_e32 v115, v0
	v_mov_b32_e32 v116, v0
	v_mov_b32_e32 v117, v0
	v_mov_b32_e32 v118, v0
	v_mov_b32_e32 v119, v0
	v_mov_b32_e32 v72, v0
	v_mov_b32_e32 v73, v0
	v_mov_b32_e32 v74, v0
	v_mov_b32_e32 v75, v0
	v_mov_b32_e32 v76, v0
	v_mov_b32_e32 v77, v0
	v_mov_b32_e32 v78, v0
	v_mov_b32_e32 v79, v0
	v_mov_b32_e32 v88, v0
	v_mov_b32_e32 v89, v0
	v_mov_b32_e32 v90, v0
	v_mov_b32_e32 v91, v0
	v_mov_b32_e32 v92, v0
	v_mov_b32_e32 v93, v0
	v_mov_b32_e32 v94, v0
	v_mov_b32_e32 v95, v0
	v_mov_b32_e32 v104, v0
	v_mov_b32_e32 v105, v0
	v_mov_b32_e32 v106, v0
	v_mov_b32_e32 v107, v0
	v_mov_b32_e32 v108, v0
	v_mov_b32_e32 v109, v0
	v_mov_b32_e32 v110, v0
	v_mov_b32_e32 v111, v0
	v_mov_b32_e32 v120, v0
	v_mov_b32_e32 v121, v0
	v_mov_b32_e32 v122, v0
	v_mov_b32_e32 v123, v0
	v_mov_b32_e32 v124, v0
	v_mov_b32_e32 v125, v0
	v_mov_b32_e32 v126, v0
	v_mov_b32_e32 v127, v0

; #define GAS __attribute__((address_space(1)))
; template <class Epi, class Sched, bool ALIGN_EPI = false, bool SP2 = false>
; __device__ __forceinline__ void gemm_phase(PG8_LAS unsigned char* lds, const Gemm g, const Sched& S, const Epi& E, int wv) {
;     ...
; #pragma unroll
;         for (int a = 0; a < 2; ++a)
; #pragma unroll
;             for (int b = 0; b < 2; ++b)
; #pragma unroll
;                 for (int m = 0; m < 4; ++m)
; #pragma unroll
;                     for (int n = 0; n < 2; ++n) acc[a][b][m][n] = (f32x4){0.f, 0.f, 0.f, 0.f};
;         cur = nxt; cA = nA; cB = nB; ++ui;
;     __device__ __forceinline__ void operator()(const f32x4 (&acc)[2][2][4][2], const Unit& u, int wr, int wc, int fr_, int fq_) const {
;     ...
;         const GAS float* sq = (const GAS float*)ssq + row0; GAS bf16_t* ap = (GAS bf16_t*)act + (size_t)row0 * DFF + col0;
;         float rsv[8];
; #pragma unroll
;         for (int j = 0; j < 8; ++j) rsv[j] = sq[(j >> 2) * 128 + (j & 3) * 16];
.LBB0_2107:
	s_lshl_b32 s98, s25, 8
	s_add_i32 s98, s98, s56
	v_and_or_b32 v248, v182, 15, s98
	v_mov_b32_e32 v249, 0
	v_lshl_add_u64 v[248:249], v[248:249], 2, s[8:9]
	global_load_dword v240, v[248:249], off
	global_load_dword v241, v[248:249], off offset:64
	global_load_dword v242, v[248:249], off offset:128
	global_load_dword v243, v[248:249], off offset:192
	global_load_dword v244, v[248:249], off offset:512
	global_load_dword v245, v[248:249], off offset:576
	global_load_dword v246, v[248:249], off offset:640
	global_load_dword v247, v[248:249], off offset:704
	s_ashr_i32 s13, s12, 31
	s_lshl_b64 s[40:41], s[12:13], 19
	s_add_u32 s40, s14, s40
	s_addc_u32 s41, s15, s41
	s_and_b64 s[42:43], s[34:35], exec
	s_cselect_b32 s13, s41, s45
	s_cselect_b32 s63, s40, s44
	s_ashr_i32 s19, s18, 31
	s_lshl_b64 s[42:43], s[18:19], 19
	s_add_u32 s42, s16, s42
	s_addc_u32 s43, s29, s43
	s_and_b64 s[50:51], s[34:35], exec
	s_cselect_b32 s19, s43, s49
	s_cselect_b32 s64, s42, s48
	s_add_u32 s44, s44, 0x40080
	s_addc_u32 s45, s45, 0
	s_add_u32 s65, s48, 0x100
	v_mov_b32_e32 v0, 0
	s_addc_u32 s66, s49, 0
	s_mov_b32 s67, -2
	v_mov_b32_e32 v1, v0
	v_mov_b32_e32 v2, v0
	v_mov_b32_e32 v3, v0
	v_mov_b32_e32 v4, v0
	v_mov_b32_e32 v5, v0
	v_mov_b32_e32 v6, v0
	v_mov_b32_e32 v7, v0
	v_mov_b32_e32 v16, v0
	v_mov_b32_e32 v17, v0
	v_mov_b32_e32 v18, v0
	v_mov_b32_e32 v19, v0
	v_mov_b32_e32 v20, v0
	v_mov_b32_e32 v21, v0
	v_mov_b32_e32 v22, v0
	v_mov_b32_e32 v23, v0
	v_mov_b32_e32 v32, v0
	v_mov_b32_e32 v33, v0
	v_mov_b32_e32 v34, v0
	v_mov_b32_e32 v35, v0
	v_mov_b32_e32 v36, v0
	v_mov_b32_e32 v37, v0
	v_mov_b32_e32 v38, v0
	v_mov_b32_e32 v39, v0
	v_mov_b32_e32 v48, v0
	v_mov_b32_e32 v49, v0
	v_mov_b32_e32 v50, v0
	v_mov_b32_e32 v51, v0
	v_mov_b32_e32 v52, v0
	v_mov_b32_e32 v53, v0
	v_mov_b32_e32 v54, v0
	v_mov_b32_e32 v55, v0
	v_mov_b32_e32 v8, v0
	v_mov_b32_e32 v9, v0
	v_mov_b32_e32 v10, v0
	v_mov_b32_e32 v11, v0
	v_mov_b32_e32 v12, v0
	v_mov_b32_e32 v13, v0
	v_mov_b32_e32 v14, v0
	v_mov_b32_e32 v15, v0
	v_mov_b32_e32 v24, v0
	v_mov_b32_e32 v25, v0
	v_mov_b32_e32 v26, v0
	v_mov_b32_e32 v27, v0
	v_mov_b32_e32 v28, v0
	v_mov_b32_e32 v29, v0
	v_mov_b32_e32 v30, v0
	v_mov_b32_e32 v31, v0
	v_mov_b32_e32 v40, v0
	v_mov_b32_e32 v41, v0
	v_mov_b32_e32 v42, v0
	v_mov_b32_e32 v43, v0
	v_mov_b32_e32 v44, v0
	v_mov_b32_e32 v45, v0
	v_mov_b32_e32 v46, v0
	v_mov_b32_e32 v47, v0
	v_mov_b32_e32 v56, v0
	v_mov_b32_e32 v57, v0
	v_mov_b32_e32 v58, v0
	v_mov_b32_e32 v59, v0
	v_mov_b32_e32 v60, v0
	v_mov_b32_e32 v61, v0
	v_mov_b32_e32 v62, v0
	v_mov_b32_e32 v63, v0
	v_mov_b32_e32 v64, v0
	v_mov_b32_e32 v65, v0
	v_mov_b32_e32 v66, v0
	v_mov_b32_e32 v67, v0
	v_mov_b32_e32 v68, v0
	v_mov_b32_e32 v69, v0
	v_mov_b32_e32 v70, v0
	v_mov_b32_e32 v71, v0
	v_mov_b32_e32 v80, v0
	v_mov_b32_e32 v81, v0
	v_mov_b32_e32 v82, v0
	v_mov_b32_e32 v83, v0
	v_mov_b32_e32 v84, v0
	v_mov_b32_e32 v85, v0
	v_mov_b32_e32 v86, v0
	v_mov_b32_e32 v87, v0
	v_mov_b32_e32 v96, v0
	v_mov_b32_e32 v97, v0
	v_mov_b32_e32 v98, v0
	v_mov_b32_e32 v99, v0
	v_mov_b32_e32 v100, v0
	v_mov_b32_e32 v101, v0
	v_mov_b32_e32 v102, v0
	v_mov_b32_e32 v103, v0
	v_mov_b32_e32 v112, v0
	v_mov_b32_e32 v113, v0
	v_mov_b32_e32 v114, v0
	v_mov_b32_e32 v115, v0
	v_mov_b32_e32 v116, v0
	v_mov_b32_e32 v117, v0
	v_mov_b32_e32 v118, v0
	v_mov_b32_e32 v119, v0
	v_mov_b32_e32 v72, v0
	v_mov_b32_e32 v73, v0
	v_mov_b32_e32 v74, v0
	v_mov_b32_e32 v75, v0
	v_mov_b32_e32 v76, v0
	v_mov_b32_e32 v77, v0
	v_mov_b32_e32 v78, v0
	v_mov_b32_e32 v79, v0
	v_mov_b32_e32 v88, v0
	v_mov_b32_e32 v89, v0
	v_mov_b32_e32 v90, v0
	v_mov_b32_e32 v91, v0
	v_mov_b32_e32 v92, v0
	v_mov_b32_e32 v93, v0
	v_mov_b32_e32 v94, v0
	v_mov_b32_e32 v95, v0
	v_mov_b32_e32 v104, v0
	v_mov_b32_e32 v105, v0
	v_mov_b32_e32 v106, v0
	v_mov_b32_e32 v107, v0
	v_mov_b32_e32 v108, v0
	v_mov_b32_e32 v109, v0
	v_mov_b32_e32 v110, v0
	v_mov_b32_e32 v111, v0
	v_mov_b32_e32 v120, v0
	v_mov_b32_e32 v121, v0
	v_mov_b32_e32 v122, v0
	v_mov_b32_e32 v123, v0
	v_mov_b32_e32 v124, v0
	v_mov_b32_e32 v125, v0
	v_mov_b32_e32 v126, v0
	v_mov_b32_e32 v127, v0

; __device__ __forceinline__ unsigned pk2(float lo, float hi) { f32x2 v = {lo, hi}; bf16x2_t b = __builtin_convertvector(v, bf16x2_t); return __builtin_bit_cast(unsigned, b); }
; __device__ __forceinline__ float silu_f(float g) { return g * __builtin_amdgcn_rcpf(1.0f + __builtin_amdgcn_exp2f(-LOG2E * g)); }
; #define GAS __attribute__((address_space(1)))
;     __device__ __forceinline__ void operator()(const f32x4 (&acc)[2][2][4][2], const Unit& u, int wr, int wc, int fr_, int fq_) const {
;         int l_ = (int)__builtin_amdgcn_mbcnt_hi(~0u, __builtin_amdgcn_mbcnt_lo(~0u, 0u)); asm volatile("" : "+v"(l_)); const int fr = l_ & 15, fq = l_ >> 4; (void)fr_; (void)fq_;
;         const int row0 = u.pm * 256 + wr * 64 + fr, col0 = u.pn * 128 + wc * 32 + 8 * fq;
;         const GAS float* sq = (const GAS float*)ssq + row0; GAS bf16_t* ap = (GAS bf16_t*)act + (size_t)row0 * DFF + col0;
;         float rsv[8];
; #pragma unroll
;         for (int j = 0; j < 8; ++j) rsv[j] = sq[(j >> 2) * 128 + (j & 3) * 16];
; #pragma unroll
;         for (int j = 0; j < 8; ++j) rsv[j] = __builtin_amdgcn_rsqf(rsv[j] * (1.0f / 1024.0f) + EPS);
; #pragma unroll
;         for (int ai = 0; ai < 2; ++ai)
; #pragma unroll
;             for (int m = 0; m < 4; ++m) {
;                 const float rs = rsv[ai * 4 + m];
;                 const f32x4 g0 = acc[ai][0][m][0] * rs, g1 = acc[ai][0][m][1] * rs, u0 = acc[ai][1][m][0] * rs, u1 = acc[ai][1][m][1] * rs;
;                 u32x4 w;
;                 w.x = pk2(silu_f(g0[0]) * u0[0], silu_f(g0[1]) * u0[1]); w.y = pk2(silu_f(g0[2]) * u0[2], silu_f(g0[3]) * u0[3]);
;                 w.z = pk2(silu_f(g1[0]) * u1[0], silu_f(g1[1]) * u1[1]); w.w = pk2(silu_f(g1[2]) * u1[2], silu_f(g1[3]) * u1[3]);
;                 *(GAS u32x4*)(ap + (size_t)(ai * 128 + m * 16) * DFF) = w;
.LBB0_2111:
	v_and_b32_e32 v164, 15, v182
	v_lshrrev_b32_e32 v165, 4, v182
	s_bfe_u32 s13, s57, 0x10005
	s_lshl_b32 s21, s13, 2
	v_add_u32_e32 v166, s21, v165
	v_and_b32_e32 v167, 7, v164
	v_xor_b32_e32 v166, v166, v167
	v_lshlrev_b32_e32 v166, 4, v166
	v_lshl_add_u32 v166, v164, 7, v166
	s_lshr_b32 s21, s56, 5
	s_lshr_b32 s26, s57, 6
	s_add_i32 s21, s21, s26
	s_lshl_b32 s21, s21, 11
	s_add_i32 s21, s21, 0xc000
	v_add_u32_e32 v172, s21, v166
	v_lshrrev_b32_e32 v165, 3, v182
	v_and_b32_e32 v167, 7, v182
	v_xor_b32_e32 v168, v167, v165
	v_lshlrev_b32_e32 v168, 4, v168
	s_lshl_b32 s13, s13, 3
	v_add_u32_e32 v165, s13, v165
	v_lshl_add_u32 v168, v165, 7, v168
	v_add_u32_e32 v173, s21, v168
	v_add_u32_e32 v165, s56, v165
	s_lshl_b32 s26, s26, 15
	v_lshl_add_u32 v167, v167, 4, s26
	v_lshl_add_u32 v174, v165, 7, v167
	s_mul_i32 s13, s25, 0x160000
	s_lshl_b32 s21, s24, 16
	s_add_u32 s13, s13, s21
	s_add_u32 s98, s6, s13
	s_addc_u32 s99, s7, 0
	s_mov_b64 s[24:25], -1
	v_fmamk_f32 v240, v240, 0x3a800000, v189
	v_fmamk_f32 v241, v241, 0x3a800000, v189
	v_fmamk_f32 v242, v242, 0x3a800000, v189
	v_fmamk_f32 v243, v243, 0x3a800000, v189
	v_fmamk_f32 v244, v244, 0x3a800000, v189
	v_fmamk_f32 v245, v245, 0x3a800000, v189
	v_fmamk_f32 v246, v246, 0x3a800000, v189
	v_fmamk_f32 v247, v247, 0x3a800000, v189
	v_rsq_f32_e32 v240, v240
	v_rsq_f32_e32 v241, v241
	v_rsq_f32_e32 v242, v242
	v_rsq_f32_e32 v243, v243
	v_rsq_f32_e32 v244, v244
	v_rsq_f32_e32 v245, v245
	v_rsq_f32_e32 v246, v246
	v_rsq_f32_e32 v247, v247
	v_mov_b32_e32 v162, 1.0
	v_mul_f32_e32 v144, 0xbfb8aa3b, v240
	v_mul_f32_e32 v146, 0xbfb8aa3b, v241
	v_mul_f32_e32 v148, 0xbfb8aa3b, v242
	v_mul_f32_e32 v150, 0xbfb8aa3b, v243
	v_mul_f32_e32 v152, 0xbfb8aa3b, v244
	v_mul_f32_e32 v154, 0xbfb8aa3b, v245
	v_mul_f32_e32 v156, 0xbfb8aa3b, v246
	v_mul_f32_e32 v158, 0xbfb8aa3b, v247
	v_mul_f32_e32 v145, v240, v240
	v_mul_f32_e32 v147, v241, v241
	v_mul_f32_e32 v149, v242, v242
	v_mul_f32_e32 v151, v243, v243
	v_mul_f32_e32 v153, v244, v244
	v_mul_f32_e32 v155, v245, v245
	v_mul_f32_e32 v157, v246, v246
	v_mul_f32_e32 v159, v247, v247
	v_pk_mul_f32 v[116:117], v[124:125], v[116:117]
	v_pk_mul_f32 v[118:119], v[126:127], v[118:119]
	v_pk_mul_f32 v[112:113], v[120:121], v[112:113]
	v_pk_mul_f32 v[114:115], v[122:123], v[114:115]
	v_pk_mul_f32 v[124:125], v[124:125], v[144:145] op_sel_hi:[1,0]
	v_pk_mul_f32 v[126:127], v[126:127], v[144:145] op_sel_hi:[1,0]
	v_pk_mul_f32 v[120:121], v[120:121], v[144:145] op_sel_hi:[1,0]
	v_pk_mul_f32 v[122:123], v[122:123], v[144:145] op_sel_hi:[1,0]
	v_pk_mul_f32 v[116:117], v[116:117], v[144:145] op_sel:[0,1] op_sel_hi:[1,1]
	v_pk_mul_f32 v[118:119], v[118:119], v[144:145] op_sel:[0,1] op_sel_hi:[1,1]
	v_pk_mul_f32 v[112:113], v[112:113], v[144:145] op_sel:[0,1] op_sel_hi:[1,1]
	v_pk_mul_f32 v[114:115], v[114:115], v[144:145] op_sel:[0,1] op_sel_hi:[1,1]
	v_exp_f32_e32 v124, v124
	v_exp_f32_e32 v125, v125
	v_exp_f32_e32 v126, v126
	v_exp_f32_e32 v127, v127
	v_exp_f32_e32 v120, v120
	v_exp_f32_e32 v121, v121
	v_exp_f32_e32 v122, v122
	v_exp_f32_e32 v123, v123
	v_pk_add_f32 v[124:125], v[124:125], v[162:163] op_sel_hi:[1,0]
	v_pk_add_f32 v[126:127], v[126:127], v[162:163] op_sel_hi:[1,0]
	v_pk_add_f32 v[120:121], v[120:121], v[162:163] op_sel_hi:[1,0]
	v_pk_add_f32 v[122:123], v[122:123], v[162:163] op_sel_hi:[1,0]
	v_rcp_f32_e32 v124, v124
	v_rcp_f32_e32 v125, v125
	v_rcp_f32_e32 v126, v126
	v_rcp_f32_e32 v127, v127
	v_rcp_f32_e32 v120, v120
	v_rcp_f32_e32 v121, v121
	v_rcp_f32_e32 v122, v122
	v_rcp_f32_e32 v123, v123
	v_pk_mul_f32 v[116:117], v[116:117], v[124:125]
	v_pk_mul_f32 v[118:119], v[118:119], v[126:127]
	v_pk_mul_f32 v[112:113], v[112:113], v[120:121]
	v_pk_mul_f32 v[114:115], v[114:115], v[122:123]
	v_cvt_pk_bf16_f32 v124, v116, v117
	v_cvt_pk_bf16_f32 v125, v118, v119
	v_cvt_pk_bf16_f32 v126, v112, v113
	v_cvt_pk_bf16_f32 v127, v114, v115
	ds_write_b128 v172, v[124:127]
	s_waitcnt lgkmcnt(0)
	s_barrier
	ds_read_b128 v[176:179], v173
	v_pk_mul_f32 v[100:101], v[108:109], v[100:101]
	v_pk_mul_f32 v[102:103], v[110:111], v[102:103]
	v_pk_mul_f32 v[96:97], v[104:105], v[96:97]
	v_pk_mul_f32 v[98:99], v[106:107], v[98:99]
	v_pk_mul_f32 v[108:109], v[108:109], v[146:147] op_sel_hi:[1,0]
	v_pk_mul_f32 v[110:111], v[110:111], v[146:147] op_sel_hi:[1,0]
	v_pk_mul_f32 v[104:105], v[104:105], v[146:147] op_sel_hi:[1,0]
	v_pk_mul_f32 v[106:107], v[106:107], v[146:147] op_sel_hi:[1,0]
	v_pk_mul_f32 v[100:101], v[100:101], v[146:147] op_sel:[0,1] op_sel_hi:[1,1]
	v_pk_mul_f32 v[102:103], v[102:103], v[146:147] op_sel:[0,1] op_sel_hi:[1,1]
	v_pk_mul_f32 v[96:97], v[96:97], v[146:147] op_sel:[0,1] op_sel_hi:[1,1]
	v_pk_mul_f32 v[98:99], v[98:99], v[146:147] op_sel:[0,1] op_sel_hi:[1,1]
	v_exp_f32_e32 v108, v108
	v_exp_f32_e32 v109, v109
	v_exp_f32_e32 v110, v110
	v_exp_f32_e32 v111, v111
	v_exp_f32_e32 v104, v104
	v_exp_f32_e32 v105, v105
	v_exp_f32_e32 v106, v106
	v_exp_f32_e32 v107, v107
	v_pk_add_f32 v[108:109], v[108:109], v[162:163] op_sel_hi:[1,0]
	v_pk_add_f32 v[110:111], v[110:111], v[162:163] op_sel_hi:[1,0]
	v_pk_add_f32 v[104:105], v[104:105], v[162:163] op_sel_hi:[1,0]
	v_pk_add_f32 v[106:107], v[106:107], v[162:163] op_sel_hi:[1,0]
	v_rcp_f32_e32 v108, v108
	v_rcp_f32_e32 v109, v109
	v_rcp_f32_e32 v110, v110
	v_rcp_f32_e32 v111, v111
	v_rcp_f32_e32 v104, v104
	v_rcp_f32_e32 v105, v105
	v_rcp_f32_e32 v106, v106
	v_rcp_f32_e32 v107, v107
	v_pk_mul_f32 v[100:101], v[100:101], v[108:109]
	v_pk_mul_f32 v[102:103], v[102:103], v[110:111]
	v_pk_mul_f32 v[96:97], v[96:97], v[104:105]
	v_pk_mul_f32 v[98:99], v[98:99], v[106:107]
	v_cvt_pk_bf16_f32 v108, v100, v101
	v_cvt_pk_bf16_f32 v109, v102, v103
	v_cvt_pk_bf16_f32 v110, v96, v97
	v_cvt_pk_bf16_f32 v111, v98, v99
	ds_write_b128 v172, v[108:111] offset:8192
	s_waitcnt lgkmcnt(1)
	global_store_dwordx4 v174, v[176:179], s[98:99]
	s_waitcnt lgkmcnt(0)
	s_barrier
; __device__ __forceinline__ unsigned pk2(float lo, float hi) { f32x2 v = {lo, hi}; bf16x2_t b = __builtin_convertvector(v, bf16x2_t); return __builtin_bit_cast(unsigned, b); }
; __device__ __forceinline__ float silu_f(float g) { return g * __builtin_amdgcn_rcpf(1.0f + __builtin_amdgcn_exp2f(-LOG2E * g)); }
; #define GAS __attribute__((address_space(1)))
;     __device__ __forceinline__ void operator()(const f32x4 (&acc)[2][2][4][2], const Unit& u, int wr, int wc, int fr_, int fq_) const {
;     ...
;         for (int ai = 0; ai < 2; ++ai)
; #pragma unroll
;             for (int m = 0; m < 4; ++m) {
;                 const float rs = rsv[ai * 4 + m];
;                 const f32x4 g0 = acc[ai][0][m][0] * rs, g1 = acc[ai][0][m][1] * rs, u0 = acc[ai][1][m][0] * rs, u1 = acc[ai][1][m][1] * rs;
;                 u32x4 w;
;                 w.x = pk2(silu_f(g0[0]) * u0[0], silu_f(g0[1]) * u0[1]); w.y = pk2(silu_f(g0[2]) * u0[2], silu_f(g0[3]) * u0[3]);
;                 w.z = pk2(silu_f(g1[0]) * u1[0], silu_f(g1[1]) * u1[1]); w.w = pk2(silu_f(g1[2]) * u1[2], silu_f(g1[3]) * u1[3]);
;                 *(GAS u32x4*)(ap + (size_t)(ai * 128 + m * 16) * DFF) = w;
	ds_read_b128 v[176:179], v173 offset:8192
	v_pk_mul_f32 v[84:85], v[92:93], v[84:85]
	v_pk_mul_f32 v[86:87], v[94:95], v[86:87]
	v_pk_mul_f32 v[80:81], v[88:89], v[80:81]
	v_pk_mul_f32 v[82:83], v[90:91], v[82:83]
	v_pk_mul_f32 v[92:93], v[92:93], v[148:149] op_sel_hi:[1,0]
	v_pk_mul_f32 v[94:95], v[94:95], v[148:149] op_sel_hi:[1,0]
	v_pk_mul_f32 v[88:89], v[88:89], v[148:149] op_sel_hi:[1,0]
	v_pk_mul_f32 v[90:91], v[90:91], v[148:149] op_sel_hi:[1,0]
	v_pk_mul_f32 v[84:85], v[84:85], v[148:149] op_sel:[0,1] op_sel_hi:[1,1]
	v_pk_mul_f32 v[86:87], v[86:87], v[148:149] op_sel:[0,1] op_sel_hi:[1,1]
	v_pk_mul_f32 v[80:81], v[80:81], v[148:149] op_sel:[0,1] op_sel_hi:[1,1]
	v_pk_mul_f32 v[82:83], v[82:83], v[148:149] op_sel:[0,1] op_sel_hi:[1,1]
	v_exp_f32_e32 v92, v92
	v_exp_f32_e32 v93, v93
	v_exp_f32_e32 v94, v94
	v_exp_f32_e32 v95, v95
	v_exp_f32_e32 v88, v88
	v_exp_f32_e32 v89, v89
	v_exp_f32_e32 v90, v90
	v_exp_f32_e32 v91, v91
	v_pk_add_f32 v[92:93], v[92:93], v[162:163] op_sel_hi:[1,0]
	v_pk_add_f32 v[94:95], v[94:95], v[162:163] op_sel_hi:[1,0]
	v_pk_add_f32 v[88:89], v[88:89], v[162:163] op_sel_hi:[1,0]
	v_pk_add_f32 v[90:91], v[90:91], v[162:163] op_sel_hi:[1,0]
	v_rcp_f32_e32 v92, v92
	v_rcp_f32_e32 v93, v93
	v_rcp_f32_e32 v94, v94
	v_rcp_f32_e32 v95, v95
	v_rcp_f32_e32 v88, v88
	v_rcp_f32_e32 v89, v89
	v_rcp_f32_e32 v90, v90
	v_rcp_f32_e32 v91, v91
	v_pk_mul_f32 v[84:85], v[84:85], v[92:93]
	v_pk_mul_f32 v[86:87], v[86:87], v[94:95]
	v_pk_mul_f32 v[80:81], v[80:81], v[88:89]
	v_pk_mul_f32 v[82:83], v[82:83], v[90:91]
	v_cvt_pk_bf16_f32 v92, v84, v85
	v_cvt_pk_bf16_f32 v93, v86, v87
	v_cvt_pk_bf16_f32 v94, v80, v81
	v_cvt_pk_bf16_f32 v95, v82, v83
	ds_write_b128 v172, v[92:95]
	v_add_u32_e32 v175, 0x800, v174
	s_waitcnt lgkmcnt(1)
	global_store_dwordx4 v175, v[176:179], s[98:99]
	s_waitcnt lgkmcnt(0)
	s_barrier
	ds_read_b128 v[176:179], v173
	v_pk_mul_f32 v[68:69], v[76:77], v[68:69]
	v_pk_mul_f32 v[70:71], v[78:79], v[70:71]
	v_pk_mul_f32 v[64:65], v[72:73], v[64:65]
	v_pk_mul_f32 v[66:67], v[74:75], v[66:67]
	v_pk_mul_f32 v[76:77], v[76:77], v[150:151] op_sel_hi:[1,0]
	v_pk_mul_f32 v[78:79], v[78:79], v[150:151] op_sel_hi:[1,0]
	v_pk_mul_f32 v[72:73], v[72:73], v[150:151] op_sel_hi:[1,0]
	v_pk_mul_f32 v[74:75], v[74:75], v[150:151] op_sel_hi:[1,0]
	v_pk_mul_f32 v[68:69], v[68:69], v[150:151] op_sel:[0,1] op_sel_hi:[1,1]
	v_pk_mul_f32 v[70:71], v[70:71], v[150:151] op_sel:[0,1] op_sel_hi:[1,1]
	v_pk_mul_f32 v[64:65], v[64:65], v[150:151] op_sel:[0,1] op_sel_hi:[1,1]
	v_pk_mul_f32 v[66:67], v[66:67], v[150:151] op_sel:[0,1] op_sel_hi:[1,1]
	v_exp_f32_e32 v76, v76
	v_exp_f32_e32 v77, v77
	v_exp_f32_e32 v78, v78
	v_exp_f32_e32 v79, v79
	v_exp_f32_e32 v72, v72
	v_exp_f32_e32 v73, v73
	v_exp_f32_e32 v74, v74
	v_exp_f32_e32 v75, v75
	v_pk_add_f32 v[76:77], v[76:77], v[162:163] op_sel_hi:[1,0]
	v_pk_add_f32 v[78:79], v[78:79], v[162:163] op_sel_hi:[1,0]
	v_pk_add_f32 v[72:73], v[72:73], v[162:163] op_sel_hi:[1,0]
	v_pk_add_f32 v[74:75], v[74:75], v[162:163] op_sel_hi:[1,0]
	v_rcp_f32_e32 v76, v76
	v_rcp_f32_e32 v77, v77
	v_rcp_f32_e32 v78, v78
	v_rcp_f32_e32 v79, v79
	v_rcp_f32_e32 v72, v72
	v_rcp_f32_e32 v73, v73
	v_rcp_f32_e32 v74, v74
	v_rcp_f32_e32 v75, v75
	v_pk_mul_f32 v[68:69], v[68:69], v[76:77]
	v_pk_mul_f32 v[70:71], v[70:71], v[78:79]
	v_pk_mul_f32 v[64:65], v[64:65], v[72:73]
	v_pk_mul_f32 v[66:67], v[66:67], v[74:75]
	v_cvt_pk_bf16_f32 v76, v68, v69
	v_cvt_pk_bf16_f32 v77, v70, v71
	v_cvt_pk_bf16_f32 v78, v64, v65
	v_cvt_pk_bf16_f32 v79, v66, v67
	ds_write_b128 v172, v[76:79] offset:8192
	v_add_u32_e32 v175, 0x1000, v174
	s_waitcnt lgkmcnt(1)
	global_store_dwordx4 v175, v[176:179], s[98:99]
	s_waitcnt lgkmcnt(0)
	s_barrier
	ds_read_b128 v[176:179], v173 offset:8192
	v_pk_mul_f32 v[52:53], v[60:61], v[52:53]
	v_pk_mul_f32 v[54:55], v[62:63], v[54:55]
	v_pk_mul_f32 v[48:49], v[56:57], v[48:49]
	v_pk_mul_f32 v[50:51], v[58:59], v[50:51]
	v_pk_mul_f32 v[60:61], v[60:61], v[152:153] op_sel_hi:[1,0]
	v_pk_mul_f32 v[62:63], v[62:63], v[152:153] op_sel_hi:[1,0]
	v_pk_mul_f32 v[56:57], v[56:57], v[152:153] op_sel_hi:[1,0]
	v_pk_mul_f32 v[58:59], v[58:59], v[152:153] op_sel_hi:[1,0]
	v_pk_mul_f32 v[52:53], v[52:53], v[152:153] op_sel:[0,1] op_sel_hi:[1,1]
	v_pk_mul_f32 v[54:55], v[54:55], v[152:153] op_sel:[0,1] op_sel_hi:[1,1]
	v_pk_mul_f32 v[48:49], v[48:49], v[152:153] op_sel:[0,1] op_sel_hi:[1,1]
	v_pk_mul_f32 v[50:51], v[50:51], v[152:153] op_sel:[0,1] op_sel_hi:[1,1]
	v_exp_f32_e32 v60, v60
	v_exp_f32_e32 v61, v61
	v_exp_f32_e32 v62, v62
	v_exp_f32_e32 v63, v63
	v_exp_f32_e32 v56, v56
	v_exp_f32_e32 v57, v57
	v_exp_f32_e32 v58, v58
	v_exp_f32_e32 v59, v59
	v_pk_add_f32 v[60:61], v[60:61], v[162:163] op_sel_hi:[1,0]
	v_pk_add_f32 v[62:63], v[62:63], v[162:163] op_sel_hi:[1,0]
	v_pk_add_f32 v[56:57], v[56:57], v[162:163] op_sel_hi:[1,0]
	v_pk_add_f32 v[58:59], v[58:59], v[162:163] op_sel_hi:[1,0]
	v_rcp_f32_e32 v60, v60
	v_rcp_f32_e32 v61, v61
	v_rcp_f32_e32 v62, v62
	v_rcp_f32_e32 v63, v63
	v_rcp_f32_e32 v56, v56
	v_rcp_f32_e32 v57, v57
	v_rcp_f32_e32 v58, v58
	v_rcp_f32_e32 v59, v59
	v_pk_mul_f32 v[52:53], v[52:53], v[60:61]
	v_pk_mul_f32 v[54:55], v[54:55], v[62:63]
	v_pk_mul_f32 v[48:49], v[48:49], v[56:57]
	v_pk_mul_f32 v[50:51], v[50:51], v[58:59]
	v_cvt_pk_bf16_f32 v60, v52, v53
	v_cvt_pk_bf16_f32 v61, v54, v55
	v_cvt_pk_bf16_f32 v62, v48, v49
	v_cvt_pk_bf16_f32 v63, v50, v51
	ds_write_b128 v172, v[60:63]
	v_add_u32_e32 v175, 0x1800, v174
	s_waitcnt lgkmcnt(1)
	global_store_dwordx4 v175, v[176:179], s[98:99]
	s_waitcnt lgkmcnt(0)
	s_barrier
; __device__ __forceinline__ unsigned pk2(float lo, float hi) { f32x2 v = {lo, hi}; bf16x2_t b = __builtin_convertvector(v, bf16x2_t); return __builtin_bit_cast(unsigned, b); }
; __device__ __forceinline__ float silu_f(float g) { return g * __builtin_amdgcn_rcpf(1.0f + __builtin_amdgcn_exp2f(-LOG2E * g)); }
; #define GAS __attribute__((address_space(1)))
; template <class Epi, class Sched, bool ALIGN_EPI = false, bool SP2 = false>
; __device__ __forceinline__ void gemm_phase(PG8_LAS unsigned char* lds, const Gemm g, const Sched& S, const Epi& E, int wv) {
;     ...
;         if constexpr (!Epi::AFTER_DRAIN) { E(acc, cur, wr, wc, fr, fq); S.done(cur); }
;         if (!has_next) break;
;     __device__ __forceinline__ void operator()(const f32x4 (&acc)[2][2][4][2], const Unit& u, int wr, int wc, int fr_, int fq_) const {
;     ...
;         for (int ai = 0; ai < 2; ++ai)
; #pragma unroll
;             for (int m = 0; m < 4; ++m) {
;                 const float rs = rsv[ai * 4 + m];
;                 const f32x4 g0 = acc[ai][0][m][0] * rs, g1 = acc[ai][0][m][1] * rs, u0 = acc[ai][1][m][0] * rs, u1 = acc[ai][1][m][1] * rs;
;                 u32x4 w;
;                 w.x = pk2(silu_f(g0[0]) * u0[0], silu_f(g0[1]) * u0[1]); w.y = pk2(silu_f(g0[2]) * u0[2], silu_f(g0[3]) * u0[3]);
;                 w.z = pk2(silu_f(g1[0]) * u1[0], silu_f(g1[1]) * u1[1]); w.w = pk2(silu_f(g1[2]) * u1[2], silu_f(g1[3]) * u1[3]);
;                 *(GAS u32x4*)(ap + (size_t)(ai * 128 + m * 16) * DFF) = w;
	ds_read_b128 v[176:179], v173
	v_pk_mul_f32 v[36:37], v[44:45], v[36:37]
	v_pk_mul_f32 v[38:39], v[46:47], v[38:39]
	v_pk_mul_f32 v[32:33], v[40:41], v[32:33]
	v_pk_mul_f32 v[34:35], v[42:43], v[34:35]
	v_pk_mul_f32 v[44:45], v[44:45], v[154:155] op_sel_hi:[1,0]
	v_pk_mul_f32 v[46:47], v[46:47], v[154:155] op_sel_hi:[1,0]
	v_pk_mul_f32 v[40:41], v[40:41], v[154:155] op_sel_hi:[1,0]
	v_pk_mul_f32 v[42:43], v[42:43], v[154:155] op_sel_hi:[1,0]
	v_pk_mul_f32 v[36:37], v[36:37], v[154:155] op_sel:[0,1] op_sel_hi:[1,1]
	v_pk_mul_f32 v[38:39], v[38:39], v[154:155] op_sel:[0,1] op_sel_hi:[1,1]
	v_pk_mul_f32 v[32:33], v[32:33], v[154:155] op_sel:[0,1] op_sel_hi:[1,1]
	v_pk_mul_f32 v[34:35], v[34:35], v[154:155] op_sel:[0,1] op_sel_hi:[1,1]
	v_exp_f32_e32 v44, v44
	v_exp_f32_e32 v45, v45
	v_exp_f32_e32 v46, v46
	v_exp_f32_e32 v47, v47
	v_exp_f32_e32 v40, v40
	v_exp_f32_e32 v41, v41
	v_exp_f32_e32 v42, v42
	v_exp_f32_e32 v43, v43
	v_pk_add_f32 v[44:45], v[44:45], v[162:163] op_sel_hi:[1,0]
	v_pk_add_f32 v[46:47], v[46:47], v[162:163] op_sel_hi:[1,0]
	v_pk_add_f32 v[40:41], v[40:41], v[162:163] op_sel_hi:[1,0]
	v_pk_add_f32 v[42:43], v[42:43], v[162:163] op_sel_hi:[1,0]
	v_rcp_f32_e32 v44, v44
	v_rcp_f32_e32 v45, v45
	v_rcp_f32_e32 v46, v46
	v_rcp_f32_e32 v47, v47
	v_rcp_f32_e32 v40, v40
	v_rcp_f32_e32 v41, v41
	v_rcp_f32_e32 v42, v42
	v_rcp_f32_e32 v43, v43
	v_pk_mul_f32 v[36:37], v[36:37], v[44:45]
	v_pk_mul_f32 v[38:39], v[38:39], v[46:47]
	v_pk_mul_f32 v[32:33], v[32:33], v[40:41]
	v_pk_mul_f32 v[34:35], v[34:35], v[42:43]
	v_cvt_pk_bf16_f32 v44, v36, v37
	v_cvt_pk_bf16_f32 v45, v38, v39
	v_cvt_pk_bf16_f32 v46, v32, v33
	v_cvt_pk_bf16_f32 v47, v34, v35
	ds_write_b128 v172, v[44:47] offset:8192
	v_add_u32_e32 v175, 0x4000, v174
	s_waitcnt lgkmcnt(1)
	global_store_dwordx4 v175, v[176:179], s[98:99]
	s_waitcnt lgkmcnt(0)
	s_barrier
	ds_read_b128 v[176:179], v173 offset:8192
	v_pk_mul_f32 v[20:21], v[28:29], v[20:21]
	v_pk_mul_f32 v[22:23], v[30:31], v[22:23]
	v_pk_mul_f32 v[16:17], v[24:25], v[16:17]
	v_pk_mul_f32 v[18:19], v[26:27], v[18:19]
	v_pk_mul_f32 v[28:29], v[28:29], v[156:157] op_sel_hi:[1,0]
	v_pk_mul_f32 v[30:31], v[30:31], v[156:157] op_sel_hi:[1,0]
	v_pk_mul_f32 v[24:25], v[24:25], v[156:157] op_sel_hi:[1,0]
	v_pk_mul_f32 v[26:27], v[26:27], v[156:157] op_sel_hi:[1,0]
	v_pk_mul_f32 v[20:21], v[20:21], v[156:157] op_sel:[0,1] op_sel_hi:[1,1]
	v_pk_mul_f32 v[22:23], v[22:23], v[156:157] op_sel:[0,1] op_sel_hi:[1,1]
	v_pk_mul_f32 v[16:17], v[16:17], v[156:157] op_sel:[0,1] op_sel_hi:[1,1]
	v_pk_mul_f32 v[18:19], v[18:19], v[156:157] op_sel:[0,1] op_sel_hi:[1,1]
	v_exp_f32_e32 v28, v28
	v_exp_f32_e32 v29, v29
	v_exp_f32_e32 v30, v30
	v_exp_f32_e32 v31, v31
	v_exp_f32_e32 v24, v24
	v_exp_f32_e32 v25, v25
	v_exp_f32_e32 v26, v26
	v_exp_f32_e32 v27, v27
	v_pk_add_f32 v[28:29], v[28:29], v[162:163] op_sel_hi:[1,0]
	v_pk_add_f32 v[30:31], v[30:31], v[162:163] op_sel_hi:[1,0]
	v_pk_add_f32 v[24:25], v[24:25], v[162:163] op_sel_hi:[1,0]
	v_pk_add_f32 v[26:27], v[26:27], v[162:163] op_sel_hi:[1,0]
	v_rcp_f32_e32 v28, v28
	v_rcp_f32_e32 v29, v29
	v_rcp_f32_e32 v30, v30
	v_rcp_f32_e32 v31, v31
	v_rcp_f32_e32 v24, v24
	v_rcp_f32_e32 v25, v25
	v_rcp_f32_e32 v26, v26
	v_rcp_f32_e32 v27, v27
	v_pk_mul_f32 v[20:21], v[20:21], v[28:29]
	v_pk_mul_f32 v[22:23], v[22:23], v[30:31]
	v_pk_mul_f32 v[16:17], v[16:17], v[24:25]
	v_pk_mul_f32 v[18:19], v[18:19], v[26:27]
	v_cvt_pk_bf16_f32 v28, v20, v21
	v_cvt_pk_bf16_f32 v29, v22, v23
	v_cvt_pk_bf16_f32 v30, v16, v17
	v_cvt_pk_bf16_f32 v31, v18, v19
	ds_write_b128 v172, v[28:31]
	v_add_u32_e32 v175, 0x4800, v174
	s_waitcnt lgkmcnt(1)
	global_store_dwordx4 v175, v[176:179], s[98:99]
	s_waitcnt lgkmcnt(0)
	s_barrier
	ds_read_b128 v[176:179], v173
	v_pk_mul_f32 v[4:5], v[12:13], v[4:5]
	v_pk_mul_f32 v[6:7], v[14:15], v[6:7]
	v_pk_mul_f32 v[0:1], v[8:9], v[0:1]
	v_pk_mul_f32 v[2:3], v[10:11], v[2:3]
	v_pk_mul_f32 v[12:13], v[12:13], v[158:159] op_sel_hi:[1,0]
	v_pk_mul_f32 v[14:15], v[14:15], v[158:159] op_sel_hi:[1,0]
	v_pk_mul_f32 v[8:9], v[8:9], v[158:159] op_sel_hi:[1,0]
	v_pk_mul_f32 v[10:11], v[10:11], v[158:159] op_sel_hi:[1,0]
	v_pk_mul_f32 v[4:5], v[4:5], v[158:159] op_sel:[0,1] op_sel_hi:[1,1]
	v_pk_mul_f32 v[6:7], v[6:7], v[158:159] op_sel:[0,1] op_sel_hi:[1,1]
	v_pk_mul_f32 v[0:1], v[0:1], v[158:159] op_sel:[0,1] op_sel_hi:[1,1]
	v_pk_mul_f32 v[2:3], v[2:3], v[158:159] op_sel:[0,1] op_sel_hi:[1,1]
	v_exp_f32_e32 v12, v12
	v_exp_f32_e32 v13, v13
	v_exp_f32_e32 v14, v14
	v_exp_f32_e32 v15, v15
	v_exp_f32_e32 v8, v8
	v_exp_f32_e32 v9, v9
	v_exp_f32_e32 v10, v10
	v_exp_f32_e32 v11, v11
	v_pk_add_f32 v[12:13], v[12:13], v[162:163] op_sel_hi:[1,0]
	v_pk_add_f32 v[14:15], v[14:15], v[162:163] op_sel_hi:[1,0]
	v_pk_add_f32 v[8:9], v[8:9], v[162:163] op_sel_hi:[1,0]
	v_pk_add_f32 v[10:11], v[10:11], v[162:163] op_sel_hi:[1,0]
	v_rcp_f32_e32 v12, v12
	v_rcp_f32_e32 v13, v13
	v_rcp_f32_e32 v14, v14
	v_rcp_f32_e32 v15, v15
	v_rcp_f32_e32 v8, v8
	v_rcp_f32_e32 v9, v9
	v_rcp_f32_e32 v10, v10
	v_rcp_f32_e32 v11, v11
	v_pk_mul_f32 v[4:5], v[4:5], v[12:13]
	v_pk_mul_f32 v[6:7], v[6:7], v[14:15]
	v_pk_mul_f32 v[0:1], v[0:1], v[8:9]
	v_pk_mul_f32 v[2:3], v[2:3], v[10:11]
	v_cvt_pk_bf16_f32 v12, v4, v5
	v_cvt_pk_bf16_f32 v13, v6, v7
	v_cvt_pk_bf16_f32 v14, v0, v1
	v_cvt_pk_bf16_f32 v15, v2, v3
	ds_write_b128 v172, v[12:15] offset:8192
	v_add_u32_e32 v175, 0x5000, v174
	s_waitcnt lgkmcnt(1)
	global_store_dwordx4 v175, v[176:179], s[98:99]
	s_waitcnt lgkmcnt(0)
	s_barrier
	ds_read_b128 v[176:179], v173 offset:8192
	v_add_u32_e32 v175, 0x5800, v174
	s_waitcnt lgkmcnt(0)
	global_store_dwordx4 v175, v[176:179], s[98:99]
	s_barrier
	s_andn2_b64 vcc, exec, s[34:35]
	s_cbranch_vccnz .LBB0_2104
	s_andn2_b64 vcc, exec, s[4:5]
	s_cbranch_vccnz .LBB0_2103
	s_barrier
	s_branch .LBB0_2103

; #define PG8_STAGE(bufoff, gbase, voff) do { _Pragma("unroll") for (int _i = 0; _i < 2; ++_i) \
;         __builtin_amdgcn_global_load_lds((const unsigned*)((const char*)(gbase) + (voff)[_i]), (PG8_LAS unsigned*)(lds + (bufoff) + ldsw + _i * 8192), 16, 0, 0); } while (0)
; #define PG8_WAIT_V(n) asm volatile("s_waitcnt vmcnt(" #n ")" ::: "memory")
; #define PG8_BAR __builtin_amdgcn_s_barrier()
; template <class Epi, class Sched, bool ALIGN_EPI = false, bool SP2 = false>
; __device__ __forceinline__ void gemm_phase(PG8_LAS unsigned char* lds, const Gemm g, const Sched& S, const Epi& E, int wv) {
;     ...
;     for (int i = 0; i < 2; ++i) { int R, C; stage_rc(tid * 16 + i * 8192, R, C); const int Rb = Epi::PERM ? ((R & ~31) + perm32(R & 31)) : R;
;         voffA[i] = (unsigned)(R * K + C) * 2u; voffB[i] = (unsigned)(Rb * K + C) * 2u; }
;     const size_t kstep = (size_t)(BK * 2);
;     const size_t hstep = (size_t)HALF * K * 2;
;     const size_t tstep = 2 * hstep;
;     const unsigned ldsw = (unsigned)wid * 1024u;
;     const int aoff = lds_byte(wr * 64 + fr, fq * 8), boff = lds_byte(wc * 32 + fr, fq * 8);
;     ...
;     const char* cA = (const char*)g.A + (size_t)cur.pm * tstep; const char* cB = (const char*)g.Bt + (size_t)cur.pn * tstep;
;     S.a_ready(cur);
;     if constexpr (SP2) {
;         PG8_STAGE(PG8_SB(0, 0), cB, voffB); PG8_STAGE(PG8_SB(0, 1), cB + hstep, voffB); PG8_STAGE(PG8_SA(0, 0), cA, voffA); PG8_STAGE(PG8_SA(0, 1), cA + hstep, voffA);
;         if (wr == 1) PG8_BAR;
;         PG8_WAIT_V(2); PG8_BAR;
;         PG8_STAGE(PG8_SB(1, 0), cB + kstep, voffB); PG8_STAGE(PG8_SA(1, 0), cA + kstep, voffA); PG8_STAGE(PG8_SB(1, 1), cB + hstep + kstep, voffB);
;         PG8_WAIT_V(6); PG8_BAR;
.LBB0_2167:
	s_or_b64 exec, exec, s[4:5]
	v_readlane_b32 s12, v250, 0
	s_mov_b64 s[4:5], 0
	s_waitcnt lgkmcnt(0)
	v_mov_b32_e32 v0, v161
	s_barrier
	v_readlane_b32 s8, v250, 42
	v_add_u32_e32 v0, 0, v0
	v_add_u32_e32 v0, 0x201c0, v0
	ds_read_b64 v[0:1], v0
	v_mov_b32_e32 v16, v183
	v_readlane_b32 s9, v250, 43
	s_and_b64 vcc, exec, s[8:9]
	s_waitcnt lgkmcnt(0)
	v_readfirstlane_b32 s7, v0
	v_mov_b32_e32 v0, v161
	v_readfirstlane_b32 s6, v1
	v_add_u32_e32 v0, 0, v0
	v_add_u32_e32 v0, 0x201c8, v0
	ds_read_b64 v[0:1], v0
	s_nop 0
	v_readfirstlane_b32 s18, v16
	s_cbranch_vccnz .LBB0_2203
	s_waitcnt lgkmcnt(0)
	v_lshlrev_b32_e32 v0, 4, v16
	v_add_u32_e32 v1, 0x2000, v0
	v_ashrrev_i32_e32 v2, 31, v1
	v_lshrrev_b32_e32 v2, 22, v2
	v_add_u32_e32 v2, v1, v2
	v_ashrrev_i32_e32 v8, 10, v2
	v_mul_i32_i24_e32 v2, 0x400, v8
	v_sub_u32_e32 v1, v1, v2
	v_lshrrev_b32_e32 v2, 4, v1
	v_bitop3_b32 v1, v2, v1, 32 bitop3:0x6c
	v_ashrrev_i32_e32 v2, 31, v1
	v_lshrrev_b32_e32 v2, 26, v2
	v_add_u32_e32 v2, v1, v2
	v_lshlrev_b32_e32 v3, 3, v8
	v_ashrrev_i32_e32 v9, 6, v2
	v_and_b32_e32 v3, -16, v3
	s_add_u32 s10, s7, s4
	v_add_u32_e32 v3, v9, v3
	s_addc_u32 s11, s6, s5
	v_and_b32_e32 v4, 3, v9
	s_mov_b32 s6, 0xffffe0
	v_lshrrev_b32_e32 v5, 2, v3
	v_lshlrev_b32_e32 v6, 1, v3
	v_and_b32_e32 v2, 0xc0, v2
	v_and_or_b32 v4, v3, s6, v4
	v_and_b32_e32 v5, 4, v5
	v_and_b32_e32 v6, 24, v6
	v_sub_u32_e32 v1, v1, v2
	v_or3_b32 v4, v4, v5, v6
	v_lshlrev_b32_e32 v5, 5, v8
	v_ashrrev_i16_sdwa v1, v193, sext(v1) dst_sel:DWORD dst_unused:UNUSED_PAD src0_sel:DWORD src1_sel:BYTE_0
	v_and_b32_e32 v10, 32, v5
	v_bfe_i32 v11, v1, 0, 16
	s_movk_i32 s7, 0xb00
	v_mul_u32_u24_e32 v4, 0xb00, v4
	v_add_u32_e32 v1, v10, v11
	v_lshlrev_b32_e32 v2, 6, v3
	v_add_lshl_u32 v152, v4, v1, 1
	v_add_lshl_u32 v154, v1, v2, 1
	v_bfe_i32 v1, v16, 27, 1
	v_lshrrev_b32_e32 v1, 22, v1
	v_add_u32_e32 v1, v0, v1
	v_and_b32_e32 v1, 0xfffffc00, v1
	v_sub_u32_e32 v0, v0, v1
	v_lshrrev_b32_e32 v1, 4, v0
	v_ashrrev_i32_e32 v2, 31, v16
	v_bitop3_b32 v0, v1, v0, 32 bitop3:0x6c
	v_lshrrev_b32_e32 v2, 26, v2
	v_ashrrev_i32_e32 v1, 31, v0
	v_add_u32_e32 v2, v16, v2
	s_add_u32 s14, s10, 0xd600000
	v_lshrrev_b32_e32 v1, 26, v1
	v_ashrrev_i32_e32 v13, 6, v2
	s_addc_u32 s15, s11, 0
	s_mul_i32 s5, s12, 0x2900000
	v_add_u32_e32 v1, v0, v1
	v_lshlrev_b32_e32 v2, 3, v13
	s_mul_hi_i32 s4, s12, 0x2900000
	s_add_u32 s13, s10, s5
	v_ashrrev_i32_e32 v12, 6, v1
	v_and_b32_e32 v2, -16, v2
	s_addc_u32 s19, s11, s4
	v_add_u32_e32 v2, v12, v2
	s_add_u32 s16, s13, 0x2000000
	v_and_b32_e32 v3, 3, v12
	v_lshrrev_b32_e32 v4, 2, v2
	v_lshlrev_b32_e32 v5, 1, v2
	v_and_b32_e32 v1, 0xc0, v1
	s_addc_u32 s29, s19, 0
	s_ashr_i32 s4, s18, 6
	v_and_or_b32 v3, v2, s6, v3
	v_and_b32_e32 v4, 4, v4
	v_and_b32_e32 v5, 24, v5
	v_sub_u32_e32 v0, v0, v1
	s_ashr_i32 s5, s18, 8
	s_lshl_b32 s30, s4, 10
	v_or3_b32 v3, v3, v4, v5
	v_lshlrev_b32_e32 v4, 5, v13
	v_ashrrev_i16_sdwa v0, v193, sext(v0) dst_sel:DWORD dst_unused:UNUSED_PAD src0_sel:DWORD src1_sel:BYTE_0
	v_readlane_b32 s6, v250, 14
	v_and_b32_e32 v14, 32, v4
	v_bfe_i32 v15, v0, 0, 16
	s_add_u32 s42, s16, s6
	v_readlane_b32 s6, v250, 12
	v_mul_u32_u24_e32 v3, 0xb00, v3
	v_add_u32_e32 v0, v14, v15
	s_addc_u32 s43, s29, s6
	s_add_i32 s31, s30, 0
	v_add_lshl_u32 v160, v3, v0, 1
	s_add_i32 m0, s31, 0x10000
	v_lshlrev_b32_e32 v1, 6, v2
	global_load_lds_dwordx4 v160, s[42:43]
	s_add_i32 m0, s31, 0x12000
	s_add_u32 s6, s42, 0xb0000
	global_load_lds_dwordx4 v152, s[42:43]
	s_addc_u32 s7, s43, 0
	s_add_i32 m0, s31, 0x14000
	v_add_lshl_u32 v156, v0, v1, 1
	global_load_lds_dwordx4 v160, s[6:7]
	s_add_i32 m0, s31, 0x16000
	v_mov_b32_e32 v153, v161
	global_load_lds_dwordx4 v152, s[6:7]
	v_readlane_b32 s6, v250, 11
	s_add_u32 s6, s14, s6
	v_readlane_b32 s7, v250, 10
	s_addc_u32 s7, s15, s7
	s_add_i32 s50, s31, 0x2000
	s_mov_b32 m0, s31
	s_mov_b64 s[98:99], 0x8000
	s_add_u32 s8, s6, 0x4000
	s_addc_u32 s9, s7, 0
	global_load_lds_dwordx4 v156, s[6:7]
	s_mov_b32 m0, s50
	s_add_i32 s51, s31, 0x4000
	global_load_lds_dwordx4 v154, s[6:7]
	s_mov_b32 m0, s51
	s_add_i32 s52, s31, 0x6000
	global_load_lds_dwordx4 v156, s[8:9]
	s_mov_b32 m0, s52
	v_mov_b32_e32 v157, v161
	global_load_lds_dwordx4 v154, s[8:9]
	v_mov_b32_e32 v155, v161
	s_cmp_eq_u32 s5, 1
	v_lshl_add_u64 v[6:7], s[42:43], 0, v[160:161]
	v_lshl_add_u64 v[4:5], s[42:43], 0, v[152:153]
	v_lshl_add_u64 v[0:1], s[6:7], 0, v[156:157]
	s_cselect_b64 s[8:9], -1, 0
	s_cmp_lg_u32 s5, 1
	v_lshl_add_u64 v[2:3], s[6:7], 0, v[154:155]
	s_cbranch_scc1 .LBB0_2170
	s_barrier
.LBB0_2170:
	s_add_u32 s10, s10, 0x5200000
	s_addc_u32 s11, s11, 0
	s_mul_hi_i32 s21, s12, 0xfd808000
	s_mul_i32 s12, s12, 0xfd808000
	s_add_u32 s12, s13, s12
	s_addc_u32 s13, s19, s21
	s_add_u32 s12, s12, 0x283c6000
	s_addc_u32 s13, s13, 0
	s_lshl_b32 s4, s4, 5
	v_and_b32_e32 v17, 48, v16
	v_lshlrev_b32_e32 v18, 6, v16
	s_movk_i32 s19, 0x3c0
	v_lshlrev_b32_e32 v16, 2, v16
	s_and_b32 s54, s4, 0x60
	s_add_i32 m0, s31, 0x18000
	v_lshl_add_u64 v[6:7], v[6:7], 0, s[74:75]
	s_lshl_b32 s53, s5, 6
	s_lshl_b32 s5, s5, 13
	v_and_or_b32 v17, v18, s19, v17
	v_and_b32_e32 v16, 32, v16
	s_lshl_b32 s4, s54, 7
	s_waitcnt vmcnt(2)
	s_barrier
	global_load_lds_dwordx4 v[6:7], off
	v_lshl_add_u64 v[4:5], v[4:5], 0, s[74:75]
	s_add_i32 m0, s31, 0x1a000
	s_add_i32 s56, s31, 0x8000
	s_add_i32 s57, s31, 0xa000
	v_bitop3_b32 v168, s4, v17, v16 bitop3:0xf6
	global_load_lds_dwordx4 v[4:5], off
	v_lshl_add_u64 v[0:1], v[0:1], 0, s[98:99]
	s_mov_b32 m0, s56
	s_add_u32 s4, s42, 0xb0080
	v_bitop3_b32 v18, v17, s5, v16 bitop3:0xde
	global_load_lds_dwordx4 v[0:1], off
	v_lshl_add_u64 v[0:1], v[2:3], 0, s[98:99]
	s_mov_b32 m0, s57
	s_addc_u32 s5, s43, 0
	global_load_lds_dwordx4 v[0:1], off
	s_add_i32 m0, s31, 0x1c000
	v_lshl_add_u64 v[0:1], s[4:5], 0, v[160:161]
	global_load_lds_dwordx4 v[0:1], off
	v_lshl_add_u64 v[0:1], s[4:5], 0, v[152:153]
	s_add_i32 m0, s31, 0x1e000
	s_movk_i32 s21, 0x40
	global_load_lds_dwordx4 v[0:1], off
	v_lshrrev_b32_e32 v1, 1, v13
	v_mul_lo_u32 v0, v12, s21
	s_mov_b32 s24, 0x400
	v_mad_u64_u32 v[0:1], s[4:5], v1, s24, v[0:1]
	v_or_b32_e32 v0, v0, v14
	v_add_lshl_u32 v0, v0, v15, 1
	v_mov_b32_e32 v1, v161
	s_mov_b64 s[34:35], 0xc000
	v_lshl_add_u64 v[158:159], v[0:1], 0, s[34:35]
	v_lshrrev_b32_e32 v1, 1, v8
	v_mul_lo_u32 v0, v9, s21
	v_mad_u64_u32 v[0:1], s[4:5], v1, s24, v[0:1]
	s_waitcnt vmcnt(6)
	v_or_b32_e32 v0, v0, v10
	s_cmpk_lt_u32 s18, 0x100
	v_add_lshl_u32 v0, v0, v11, 1
	v_mov_b32_e32 v1, v161
	v_readlane_b32 s4, v250, 27
	s_cselect_b64 s[18:19], -1, 0
	v_lshl_add_u64 v[162:163], v[0:1], 0, s[34:35]
	s_mov_b32 s60, 0
	v_add_u32_e32 v169, 0, v18
	v_readlane_b32 s63, v250, 13
	s_mov_b32 s64, s4
	s_barrier
	v_readlane_b32 s5, v250, 28
	s_branch .LBB0_2173

; #define PG8_STAGE(bufoff, gbase, voff) do { _Pragma("unroll") for (int _i = 0; _i < 2; ++_i) \
;         __builtin_amdgcn_global_load_lds((const unsigned*)((const char*)(gbase) + (voff)[_i]), (PG8_LAS unsigned*)(lds + (bufoff) + ldsw + _i * 8192), 16, 0, 0); } while (0)
; #define PG8_LDA(dst, b, h) do { _Pragma("unroll") for (int m = 0; m < 4; ++m) _Pragma("unroll") for (int k = 0; k < 2; ++k) dst[m][k] = *(const PG8_LAS bf16x8*)(lds + PG8_SA(b, h) + aoff + m * 2048 + k * 1024); } while (0)
; #define PG8_LDB(dst, b, h) do { _Pragma("unroll") for (int n = 0; n < 2; ++n) _Pragma("unroll") for (int k = 0; k < 2; ++k) dst[n][k] = *(const PG8_LAS bf16x8*)(lds + PG8_SB(b, h) + boff + n * 2048 + k * 1024); } while (0)
; #define PG8_MMA(ai, bj, At, Bt) do { __builtin_amdgcn_s_setprio(1); _Pragma("unroll") for (int m = 0; m < 4; ++m) _Pragma("unroll") for (int n = 0; n < 2; ++n) _Pragma("unroll") for (int k = 0; k < 2; ++k) \
;         acc[ai][bj][m][n] = __builtin_amdgcn_mfma_f32_16x16x32_bf16(Bt[n][k], At[m][k], acc[ai][bj][m][n], 0, 0, 0); __builtin_amdgcn_s_setprio(0); } while (0)
; #define PG8_BAR __builtin_amdgcn_s_barrier()
; template <class Epi, class Sched, bool ALIGN_EPI = false, bool SP2 = false>
; __device__ __forceinline__ void gemm_phase(PG8_LAS unsigned char* lds, const Gemm g, const Sched& S, const Epi& E, int wv) {
;     ...
;         for (int t = 0; t < nt; t += 2) {
;             const bool last = (t == nt - 2);
;             const char* a1 = cA + (size_t)(t + 1) * kstep;
;             const char* a2 = last ? nA : cA + (size_t)(t + 2) * kstep; const char* b2 = last ? nB : cB + (size_t)(t + 2) * kstep;
;             const char* a3 = a2 + kstep; const char* b3 = b2 + kstep;
;             if (last && has_next) S.a_ready(nxt);
;             if constexpr (SP2) {
;             PG8_LDB(B0, 0, 0); PG8_LDB(B1, 0, 1); PG8_SCHED; PG8_LDA(At, 0, 0); PG8_STAGE(PG8_SA(1, 1), a1 + hstep, voffA);
;             PG8_WAIT_V(8); PG8_WAIT_L(0); PG8_BAR; PG8_MMA(0, 0, At, B0); PG8_MMA(0, 1, At, B1); PG8_BAR; PG8_SCHED;
;     ...
; #pragma unroll
;         for (int a = 0; a < 2; ++a)
; #pragma unroll
;             for (int b = 0; b < 2; ++b)
; #pragma unroll
;                 for (int m = 0; m < 4; ++m)
; #pragma unroll
;                     for (int n = 0; n < 2; ++n) acc[a][b][m][n] = (f32x4){0.f, 0.f, 0.f, 0.f};
;         cur = nxt; cA = nA; cB = nB; ++ui;
.LBB0_2179:
	s_add_u32 s24, s42, 0x100
	v_mov_b32_e32 v0, 0
	s_addc_u32 s25, s43, 0
	s_mov_b32 s65, -2
	s_waitcnt lgkmcnt(0)
	v_mov_b32_e32 v1, v0
	v_mov_b32_e32 v2, v0
	v_mov_b32_e32 v3, v0
	v_mov_b32_e32 v4, v0
	v_mov_b32_e32 v5, v0
	v_mov_b32_e32 v6, v0
	v_mov_b32_e32 v7, v0
	v_mov_b32_e32 v16, v0
	v_mov_b32_e32 v17, v0
	v_mov_b32_e32 v18, v0
	v_mov_b32_e32 v19, v0
	v_mov_b32_e32 v20, v0
	v_mov_b32_e32 v21, v0
	v_mov_b32_e32 v22, v0
	v_mov_b32_e32 v23, v0
	v_mov_b32_e32 v32, v0
	v_mov_b32_e32 v33, v0
	v_mov_b32_e32 v34, v0
	v_mov_b32_e32 v35, v0
	v_mov_b32_e32 v36, v0
	v_mov_b32_e32 v37, v0
	v_mov_b32_e32 v38, v0
	v_mov_b32_e32 v39, v0
	v_mov_b32_e32 v48, v0
	v_mov_b32_e32 v49, v0
	v_mov_b32_e32 v50, v0
	v_mov_b32_e32 v51, v0
	v_mov_b32_e32 v52, v0
	v_mov_b32_e32 v53, v0
	v_mov_b32_e32 v54, v0
	v_mov_b32_e32 v55, v0
	v_mov_b32_e32 v8, v0
	v_mov_b32_e32 v9, v0
	v_mov_b32_e32 v10, v0
	v_mov_b32_e32 v11, v0
	v_mov_b32_e32 v12, v0
	v_mov_b32_e32 v13, v0
	v_mov_b32_e32 v14, v0
	v_mov_b32_e32 v15, v0
	v_mov_b32_e32 v24, v0
	v_mov_b32_e32 v25, v0
	v_mov_b32_e32 v26, v0
	v_mov_b32_e32 v27, v0
	v_mov_b32_e32 v28, v0
	v_mov_b32_e32 v29, v0
	v_mov_b32_e32 v30, v0
	v_mov_b32_e32 v31, v0
	v_mov_b32_e32 v40, v0
	v_mov_b32_e32 v41, v0
	v_mov_b32_e32 v42, v0
	v_mov_b32_e32 v43, v0
	v_mov_b32_e32 v44, v0
	v_mov_b32_e32 v45, v0
	v_mov_b32_e32 v46, v0
	v_mov_b32_e32 v47, v0
	v_mov_b32_e32 v56, v0
	v_mov_b32_e32 v57, v0
	v_mov_b32_e32 v58, v0
	v_mov_b32_e32 v59, v0
	v_mov_b32_e32 v60, v0
	v_mov_b32_e32 v61, v0
	v_mov_b32_e32 v62, v0
	v_mov_b32_e32 v63, v0
	v_mov_b32_e32 v64, v0
	v_mov_b32_e32 v65, v0
	v_mov_b32_e32 v66, v0
	v_mov_b32_e32 v67, v0
	v_mov_b32_e32 v68, v0
	v_mov_b32_e32 v69, v0
	v_mov_b32_e32 v70, v0
	v_mov_b32_e32 v71, v0
	v_mov_b32_e32 v80, v0
	v_mov_b32_e32 v81, v0
	v_mov_b32_e32 v82, v0
	v_mov_b32_e32 v83, v0
	v_mov_b32_e32 v84, v0
	v_mov_b32_e32 v85, v0
	v_mov_b32_e32 v86, v0
	v_mov_b32_e32 v87, v0
	v_mov_b32_e32 v96, v0
	v_mov_b32_e32 v97, v0
	v_mov_b32_e32 v98, v0
	v_mov_b32_e32 v99, v0
	v_mov_b32_e32 v100, v0
	v_mov_b32_e32 v101, v0
	v_mov_b32_e32 v102, v0
	v_mov_b32_e32 v103, v0
	v_mov_b32_e32 v112, v0
	v_mov_b32_e32 v113, v0
	v_mov_b32_e32 v114, v0
	v_mov_b32_e32 v115, v0
	v_mov_b32_e32 v116, v0
	v_mov_b32_e32 v117, v0
	v_mov_b32_e32 v118, v0
	v_mov_b32_e32 v119, v0
	v_mov_b32_e32 v72, v0
	v_mov_b32_e32 v73, v0
	v_mov_b32_e32 v74, v0
	v_mov_b32_e32 v75, v0
	v_mov_b32_e32 v76, v0
	v_mov_b32_e32 v77, v0
	v_mov_b32_e32 v78, v0
	v_mov_b32_e32 v79, v0
	v_mov_b32_e32 v88, v0
	v_mov_b32_e32 v89, v0
	v_mov_b32_e32 v90, v0
	v_mov_b32_e32 v91, v0
	v_mov_b32_e32 v92, v0
	v_mov_b32_e32 v93, v0
	v_mov_b32_e32 v94, v0
	v_mov_b32_e32 v95, v0
	v_mov_b32_e32 v104, v0
	v_mov_b32_e32 v105, v0
	v_mov_b32_e32 v106, v0
	v_mov_b32_e32 v107, v0
	v_mov_b32_e32 v108, v0
	v_mov_b32_e32 v109, v0
	v_mov_b32_e32 v110, v0
	v_mov_b32_e32 v111, v0
	v_mov_b32_e32 v120, v0
	v_mov_b32_e32 v121, v0
	v_mov_b32_e32 v122, v0
	v_mov_b32_e32 v123, v0
	v_mov_b32_e32 v124, v0
	v_mov_b32_e32 v125, v0
	v_mov_b32_e32 v126, v0
	v_mov_b32_e32 v127, v0
.LBB0_2180:
	s_add_u32 s42, s6, 0x10000
	s_addc_u32 s43, s7, 0
	s_add_i32 s21, 0, 0x10000
	s_cmp_eq_u32 s65, 40
	s_cselect_b32 s49, s35, s43
	s_cselect_b32 s48, s34, s42
	s_cselect_b32 s45, s41, s25
	s_cselect_b32 s44, s40, s24
	s_add_i32 s26, 0, 0x14000
	v_add_u32_e32 v140, s21, v168
	v_add_u32_e32 v170, s26, v168
	ds_read_b128 v[128:131], v140
	ds_read_b128 v[132:135], v140 offset:1024
	ds_read_b128 v[136:139], v140 offset:2048
	ds_read_b128 v[140:143], v140 offset:3072
	ds_read_b128 v[144:147], v170
	ds_read_b128 v[148:151], v170 offset:1024
	ds_read_b128 v[164:167], v170 offset:2048
	ds_read_b128 v[170:173], v170 offset:3072
	v_lshl_add_u64 v[228:229], s[6:7], 0, v[158:159]
	s_add_i32 m0, s31, 0xc000
	ds_read_b128 v[174:177], v169
	ds_read_b128 v[178:181], v169 offset:1024
	ds_read_b128 v[204:207], v169 offset:2048
	ds_read_b128 v[208:211], v169 offset:3072
	ds_read_b128 v[212:215], v169 offset:4096
	ds_read_b128 v[216:219], v169 offset:5120
	ds_read_b128 v[220:223], v169 offset:6144
	ds_read_b128 v[224:227], v169 offset:7168
	global_load_lds_dwordx4 v[228:229], off
	v_lshl_add_u64 v[228:229], s[6:7], 0, v[162:163]
	s_add_i32 m0, s31, 0xe000
	s_nop 0
	global_load_lds_dwordx4 v[228:229], off
	s_waitcnt vmcnt(8)
	s_waitcnt lgkmcnt(0)
	s_barrier
	s_setprio 1
	s_waitcnt lgkmcnt(0)
	v_mfma_f32_16x16x32_bf16 v[124:127], v[128:131], v[174:177], v[124:127]
	v_mfma_f32_16x16x32_bf16 v[120:123], v[136:139], v[174:177], v[120:123]
	v_mfma_f32_16x16x32_bf16 v[108:111], v[128:131], v[204:207], v[108:111]
	v_mfma_f32_16x16x32_bf16 v[104:107], v[136:139], v[204:207], v[104:107]
	v_mfma_f32_16x16x32_bf16 v[92:95], v[128:131], v[212:215], v[92:95]
	v_mfma_f32_16x16x32_bf16 v[88:91], v[136:139], v[212:215], v[88:91]
	v_mfma_f32_16x16x32_bf16 v[76:79], v[128:131], v[220:223], v[76:79]
	v_mfma_f32_16x16x32_bf16 v[72:75], v[136:139], v[220:223], v[72:75]
	v_mfma_f32_16x16x32_bf16 v[124:127], v[132:135], v[178:181], v[124:127]
	v_mfma_f32_16x16x32_bf16 v[120:123], v[140:143], v[178:181], v[120:123]
	v_mfma_f32_16x16x32_bf16 v[108:111], v[132:135], v[208:211], v[108:111]
	v_mfma_f32_16x16x32_bf16 v[104:107], v[140:143], v[208:211], v[104:107]
	v_mfma_f32_16x16x32_bf16 v[92:95], v[132:135], v[216:219], v[92:95]
	v_mfma_f32_16x16x32_bf16 v[88:91], v[140:143], v[216:219], v[88:91]
	v_mfma_f32_16x16x32_bf16 v[76:79], v[132:135], v[224:227], v[76:79]
	v_mfma_f32_16x16x32_bf16 v[72:75], v[140:143], v[224:227], v[72:75]
	s_setprio 0
	s_setprio 1
	v_mfma_f32_16x16x32_bf16 v[116:119], v[144:147], v[174:177], v[116:119]
	v_mfma_f32_16x16x32_bf16 v[112:115], v[164:167], v[174:177], v[112:115]
	v_mfma_f32_16x16x32_bf16 v[100:103], v[144:147], v[204:207], v[100:103]
	v_mfma_f32_16x16x32_bf16 v[96:99], v[164:167], v[204:207], v[96:99]
	v_mfma_f32_16x16x32_bf16 v[84:87], v[144:147], v[212:215], v[84:87]
	v_mfma_f32_16x16x32_bf16 v[80:83], v[164:167], v[212:215], v[80:83]
	v_mfma_f32_16x16x32_bf16 v[68:71], v[144:147], v[220:223], v[68:71]
	v_mfma_f32_16x16x32_bf16 v[64:67], v[164:167], v[220:223], v[64:67]
	v_mfma_f32_16x16x32_bf16 v[116:119], v[148:151], v[178:181], v[116:119]
	v_mfma_f32_16x16x32_bf16 v[112:115], v[170:173], v[178:181], v[112:115]
	v_mfma_f32_16x16x32_bf16 v[100:103], v[148:151], v[208:211], v[100:103]
	v_mfma_f32_16x16x32_bf16 v[96:99], v[170:173], v[208:211], v[96:99]
	v_mfma_f32_16x16x32_bf16 v[84:87], v[148:151], v[216:219], v[84:87]
	v_mfma_f32_16x16x32_bf16 v[80:83], v[170:173], v[216:219], v[80:83]
	v_mfma_f32_16x16x32_bf16 v[68:71], v[148:151], v[224:227], v[68:71]
	v_mfma_f32_16x16x32_bf16 v[64:67], v[170:173], v[224:227], v[64:67]
	s_setprio 0
	s_barrier
; #define PG8_STAGE(bufoff, gbase, voff) do { _Pragma("unroll") for (int _i = 0; _i < 2; ++_i) \
;         __builtin_amdgcn_global_load_lds((const unsigned*)((const char*)(gbase) + (voff)[_i]), (PG8_LAS unsigned*)(lds + (bufoff) + ldsw + _i * 8192), 16, 0, 0); } while (0)
; #define PG8_LDA(dst, b, h) do { _Pragma("unroll") for (int m = 0; m < 4; ++m) _Pragma("unroll") for (int k = 0; k < 2; ++k) dst[m][k] = *(const PG8_LAS bf16x8*)(lds + PG8_SA(b, h) + aoff + m * 2048 + k * 1024); } while (0)
; #define PG8_LDB(dst, b, h) do { _Pragma("unroll") for (int n = 0; n < 2; ++n) _Pragma("unroll") for (int k = 0; k < 2; ++k) dst[n][k] = *(const PG8_LAS bf16x8*)(lds + PG8_SB(b, h) + boff + n * 2048 + k * 1024); } while (0)
; #define PG8_MMA(ai, bj, At, Bt) do { __builtin_amdgcn_s_setprio(1); _Pragma("unroll") for (int m = 0; m < 4; ++m) _Pragma("unroll") for (int n = 0; n < 2; ++n) _Pragma("unroll") for (int k = 0; k < 2; ++k) \
;         acc[ai][bj][m][n] = __builtin_amdgcn_mfma_f32_16x16x32_bf16(Bt[n][k], At[m][k], acc[ai][bj][m][n], 0, 0, 0); __builtin_amdgcn_s_setprio(0); } while (0)
; #define PG8_WAIT_V(n) asm volatile("s_waitcnt vmcnt(" #n ")" ::: "memory")
; #define PG8_WAIT_L(n) asm volatile("s_waitcnt lgkmcnt(" #n ")" ::: "memory")
; #define PG8_BAR __builtin_amdgcn_s_barrier()
; #define PG8_SCHED __builtin_amdgcn_sched_barrier(0)
; template <class Epi, class Sched, bool ALIGN_EPI = false, bool SP2 = false>
; __device__ __forceinline__ void gemm_phase(PG8_LAS unsigned char* lds, const Gemm g, const Sched& S, const Epi& E, int wv) {
;     ...
;             PG8_WAIT_V(8); PG8_WAIT_L(0); PG8_BAR; PG8_MMA(0, 0, At, B0); PG8_MMA(0, 1, At, B1); PG8_BAR; PG8_SCHED;
;             PG8_LDA(At, 0, 1); PG8_STAGE(PG8_SB(0, 0), b2, voffB); PG8_STAGE(PG8_SB(0, 1), b2 + hstep, voffB); PG8_STAGE(PG8_SA(0, 0), a2, voffA);
;             PG8_WAIT_V(8); PG8_WAIT_L(0); PG8_BAR; PG8_MMA(1, 0, At, B0); PG8_MMA(1, 1, At, B1); PG8_BAR; PG8_SCHED;
;             PG8_LDB(B0, 1, 0); PG8_LDB(B1, 1, 1); PG8_SCHED; PG8_LDA(At, 1, 0); PG8_STAGE(PG8_SA(0, 1), a2 + hstep, voffA);
;             PG8_WAIT_V(8); PG8_WAIT_L(0); PG8_BAR; PG8_MMA(0, 0, At, B0); PG8_MMA(0, 1, At, B1); PG8_BAR; PG8_SCHED;
	s_add_i32 s6, s21, s30
	v_lshl_add_u64 v[228:229], s[44:45], 0, v[160:161]
	s_mov_b32 m0, s6
	ds_read_b128 v[174:177], v169 offset:16384
	ds_read_b128 v[178:181], v169 offset:17408
	ds_read_b128 v[204:207], v169 offset:18432
	ds_read_b128 v[208:211], v169 offset:19456
	ds_read_b128 v[212:215], v169 offset:20480
	ds_read_b128 v[216:219], v169 offset:21504
	ds_read_b128 v[220:223], v169 offset:22528
	ds_read_b128 v[224:227], v169 offset:23552
	global_load_lds_dwordx4 v[228:229], off
	s_add_i32 m0, s6, 0x2000
	s_add_u32 s6, s44, 0xb0000
	v_lshl_add_u64 v[230:231], s[44:45], 0, v[152:153]
	s_addc_u32 s7, s45, 0
	s_add_i32 s21, s26, s30
	global_load_lds_dwordx4 v[230:231], off
	v_lshl_add_u64 v[232:233], s[6:7], 0, v[160:161]
	s_mov_b32 m0, s21
	v_lshl_add_u64 v[234:235], s[48:49], 0, v[154:155]
	global_load_lds_dwordx4 v[232:233], off
	v_lshl_add_u64 v[232:233], s[6:7], 0, v[152:153]
	s_add_i32 m0, s21, 0x2000
	s_nop 0
	global_load_lds_dwordx4 v[232:233], off
	v_lshl_add_u64 v[232:233], s[48:49], 0, v[156:157]
	s_mov_b32 m0, s31
	s_nop 0
	global_load_lds_dwordx4 v[232:233], off
	s_mov_b32 m0, s50
	s_nop 0
	global_load_lds_dwordx4 v[234:235], off
	s_waitcnt vmcnt(8)
	s_waitcnt lgkmcnt(0)
	s_barrier
	s_setprio 1
	s_waitcnt lgkmcnt(0)
	v_mfma_f32_16x16x32_bf16 v[60:63], v[128:131], v[174:177], v[60:63]
	v_mfma_f32_16x16x32_bf16 v[56:59], v[136:139], v[174:177], v[56:59]
	v_mfma_f32_16x16x32_bf16 v[44:47], v[128:131], v[204:207], v[44:47]
	v_mfma_f32_16x16x32_bf16 v[40:43], v[136:139], v[204:207], v[40:43]
	v_mfma_f32_16x16x32_bf16 v[28:31], v[128:131], v[212:215], v[28:31]
	v_mfma_f32_16x16x32_bf16 v[24:27], v[136:139], v[212:215], v[24:27]
	v_mfma_f32_16x16x32_bf16 v[12:15], v[128:131], v[220:223], v[12:15]
	v_mfma_f32_16x16x32_bf16 v[8:11], v[136:139], v[220:223], v[8:11]
	v_mfma_f32_16x16x32_bf16 v[60:63], v[132:135], v[178:181], v[60:63]
	v_mfma_f32_16x16x32_bf16 v[56:59], v[140:143], v[178:181], v[56:59]
	v_mfma_f32_16x16x32_bf16 v[44:47], v[132:135], v[208:211], v[44:47]
	v_mfma_f32_16x16x32_bf16 v[40:43], v[140:143], v[208:211], v[40:43]
	v_mfma_f32_16x16x32_bf16 v[28:31], v[132:135], v[216:219], v[28:31]
	v_mfma_f32_16x16x32_bf16 v[24:27], v[140:143], v[216:219], v[24:27]
	v_mfma_f32_16x16x32_bf16 v[12:15], v[132:135], v[224:227], v[12:15]
	v_mfma_f32_16x16x32_bf16 v[8:11], v[140:143], v[224:227], v[8:11]
	s_setprio 0
	s_setprio 1
	v_mfma_f32_16x16x32_bf16 v[52:55], v[144:147], v[174:177], v[52:55]
	v_mfma_f32_16x16x32_bf16 v[48:51], v[164:167], v[174:177], v[48:51]
	v_mfma_f32_16x16x32_bf16 v[36:39], v[144:147], v[204:207], v[36:39]
	v_mfma_f32_16x16x32_bf16 v[32:35], v[164:167], v[204:207], v[32:35]
	v_mfma_f32_16x16x32_bf16 v[20:23], v[144:147], v[212:215], v[20:23]
	v_mfma_f32_16x16x32_bf16 v[16:19], v[164:167], v[212:215], v[16:19]
	v_mfma_f32_16x16x32_bf16 v[4:7], v[144:147], v[220:223], v[4:7]
	v_mfma_f32_16x16x32_bf16 v[0:3], v[164:167], v[220:223], v[0:3]
	v_mfma_f32_16x16x32_bf16 v[52:55], v[148:151], v[178:181], v[52:55]
	v_mfma_f32_16x16x32_bf16 v[48:51], v[170:173], v[178:181], v[48:51]
	v_mfma_f32_16x16x32_bf16 v[36:39], v[148:151], v[208:211], v[36:39]
	v_mfma_f32_16x16x32_bf16 v[32:35], v[170:173], v[208:211], v[32:35]
	v_mfma_f32_16x16x32_bf16 v[20:23], v[148:151], v[216:219], v[20:23]
	v_mfma_f32_16x16x32_bf16 v[16:19], v[170:173], v[216:219], v[16:19]
	v_mfma_f32_16x16x32_bf16 v[4:7], v[148:151], v[224:227], v[4:7]
	v_mfma_f32_16x16x32_bf16 v[0:3], v[170:173], v[224:227], v[0:3]
	s_setprio 0
	s_barrier
	s_add_i32 s21, 0, 0x18000
	s_add_i32 s26, 0, 0x1c000
	v_add_u32_e32 v140, s21, v168
	v_add_u32_e32 v170, s26, v168
	ds_read_b128 v[128:131], v140
	ds_read_b128 v[132:135], v140 offset:1024
	ds_read_b128 v[136:139], v140 offset:2048
	ds_read_b128 v[140:143], v140 offset:3072
	ds_read_b128 v[144:147], v170
	ds_read_b128 v[148:151], v170 offset:1024
	ds_read_b128 v[164:167], v170 offset:2048
	ds_read_b128 v[170:173], v170 offset:3072
	s_add_u32 s6, s48, 0x4000
	s_addc_u32 s7, s49, 0
	s_mov_b32 m0, s51
	v_lshl_add_u64 v[236:237], s[6:7], 0, v[156:157]
	ds_read_b128 v[174:177], v169 offset:32768
	ds_read_b128 v[178:181], v169 offset:33792
	ds_read_b128 v[204:207], v169 offset:34816
	ds_read_b128 v[208:211], v169 offset:35840
	ds_read_b128 v[212:215], v169 offset:36864
	ds_read_b128 v[216:219], v169 offset:37888
	ds_read_b128 v[220:223], v169 offset:38912
	ds_read_b128 v[224:227], v169 offset:39936
	global_load_lds_dwordx4 v[236:237], off
	v_lshl_add_u64 v[236:237], s[6:7], 0, v[154:155]
	s_mov_b32 m0, s52
	s_nop 0
	global_load_lds_dwordx4 v[236:237], off
	s_waitcnt vmcnt(8)
	s_waitcnt lgkmcnt(0)
	s_barrier
; #define PG8_STAGE(bufoff, gbase, voff) do { _Pragma("unroll") for (int _i = 0; _i < 2; ++_i) \
;         __builtin_amdgcn_global_load_lds((const unsigned*)((const char*)(gbase) + (voff)[_i]), (PG8_LAS unsigned*)(lds + (bufoff) + ldsw + _i * 8192), 16, 0, 0); } while (0)
; #define PG8_LDA(dst, b, h) do { _Pragma("unroll") for (int m = 0; m < 4; ++m) _Pragma("unroll") for (int k = 0; k < 2; ++k) dst[m][k] = *(const PG8_LAS bf16x8*)(lds + PG8_SA(b, h) + aoff + m * 2048 + k * 1024); } while (0)
; #define PG8_MMA(ai, bj, At, Bt) do { __builtin_amdgcn_s_setprio(1); _Pragma("unroll") for (int m = 0; m < 4; ++m) _Pragma("unroll") for (int n = 0; n < 2; ++n) _Pragma("unroll") for (int k = 0; k < 2; ++k) \
;         acc[ai][bj][m][n] = __builtin_amdgcn_mfma_f32_16x16x32_bf16(Bt[n][k], At[m][k], acc[ai][bj][m][n], 0, 0, 0); __builtin_amdgcn_s_setprio(0); } while (0)
; #define PG8_WAIT_V(n) asm volatile("s_waitcnt vmcnt(" #n ")" ::: "memory")
; #define PG8_WAIT_L(n) asm volatile("s_waitcnt lgkmcnt(" #n ")" ::: "memory")
; #define PG8_BAR __builtin_amdgcn_s_barrier()
; #define PG8_SCHED __builtin_amdgcn_sched_barrier(0)
; template <class Epi, class Sched, bool ALIGN_EPI = false, bool SP2 = false>
; __device__ __forceinline__ void gemm_phase(PG8_LAS unsigned char* lds, const Gemm g, const Sched& S, const Epi& E, int wv) {
;     ...
;         for (int t = 0; t < nt; t += 2) {
;     ...
;             PG8_WAIT_V(8); PG8_WAIT_L(0); PG8_BAR; PG8_MMA(0, 0, At, B0); PG8_MMA(0, 1, At, B1); PG8_BAR; PG8_SCHED;
;             PG8_LDA(At, 1, 1); PG8_STAGE(PG8_SB(1, 0), b3, voffB); PG8_STAGE(PG8_SB(1, 1), b3 + hstep, voffB); PG8_STAGE(PG8_SA(1, 0), a3, voffA);
;             PG8_WAIT_V(8); PG8_WAIT_L(0); PG8_BAR; PG8_MMA(1, 0, At, B0); PG8_MMA(1, 1, At, B1); PG8_BAR; PG8_SCHED;
	s_setprio 1
	s_waitcnt lgkmcnt(0)
	v_mfma_f32_16x16x32_bf16 v[124:127], v[128:131], v[174:177], v[124:127]
	v_mfma_f32_16x16x32_bf16 v[120:123], v[136:139], v[174:177], v[120:123]
	v_mfma_f32_16x16x32_bf16 v[108:111], v[128:131], v[204:207], v[108:111]
	v_mfma_f32_16x16x32_bf16 v[104:107], v[136:139], v[204:207], v[104:107]
	v_mfma_f32_16x16x32_bf16 v[92:95], v[128:131], v[212:215], v[92:95]
	v_mfma_f32_16x16x32_bf16 v[88:91], v[136:139], v[212:215], v[88:91]
	v_mfma_f32_16x16x32_bf16 v[76:79], v[128:131], v[220:223], v[76:79]
	v_mfma_f32_16x16x32_bf16 v[72:75], v[136:139], v[220:223], v[72:75]
	v_mfma_f32_16x16x32_bf16 v[124:127], v[132:135], v[178:181], v[124:127]
	v_mfma_f32_16x16x32_bf16 v[120:123], v[140:143], v[178:181], v[120:123]
	v_mfma_f32_16x16x32_bf16 v[108:111], v[132:135], v[208:211], v[108:111]
	v_mfma_f32_16x16x32_bf16 v[104:107], v[140:143], v[208:211], v[104:107]
	v_mfma_f32_16x16x32_bf16 v[92:95], v[132:135], v[216:219], v[92:95]
	v_mfma_f32_16x16x32_bf16 v[88:91], v[140:143], v[216:219], v[88:91]
	v_mfma_f32_16x16x32_bf16 v[76:79], v[132:135], v[224:227], v[76:79]
	v_mfma_f32_16x16x32_bf16 v[72:75], v[140:143], v[224:227], v[72:75]
	s_setprio 0
	s_setprio 1
	v_mfma_f32_16x16x32_bf16 v[116:119], v[144:147], v[174:177], v[116:119]
	v_mfma_f32_16x16x32_bf16 v[112:115], v[164:167], v[174:177], v[112:115]
	v_mfma_f32_16x16x32_bf16 v[100:103], v[144:147], v[204:207], v[100:103]
	v_mfma_f32_16x16x32_bf16 v[96:99], v[164:167], v[204:207], v[96:99]
	v_mfma_f32_16x16x32_bf16 v[84:87], v[144:147], v[212:215], v[84:87]
	v_mfma_f32_16x16x32_bf16 v[80:83], v[164:167], v[212:215], v[80:83]
	v_mfma_f32_16x16x32_bf16 v[68:71], v[144:147], v[220:223], v[68:71]
	v_mfma_f32_16x16x32_bf16 v[64:67], v[164:167], v[220:223], v[64:67]
	v_mfma_f32_16x16x32_bf16 v[116:119], v[148:151], v[178:181], v[116:119]
	v_mfma_f32_16x16x32_bf16 v[112:115], v[170:173], v[178:181], v[112:115]
	v_mfma_f32_16x16x32_bf16 v[100:103], v[148:151], v[208:211], v[100:103]
	v_mfma_f32_16x16x32_bf16 v[96:99], v[170:173], v[208:211], v[96:99]
	v_mfma_f32_16x16x32_bf16 v[84:87], v[148:151], v[216:219], v[84:87]
	v_mfma_f32_16x16x32_bf16 v[80:83], v[170:173], v[216:219], v[80:83]
	v_mfma_f32_16x16x32_bf16 v[68:71], v[148:151], v[224:227], v[68:71]
	v_mfma_f32_16x16x32_bf16 v[64:67], v[170:173], v[224:227], v[64:67]
	s_setprio 0
	s_barrier
	s_add_i32 s6, s21, s30
	v_lshl_add_u64 v[228:229], v[228:229], 0, s[74:75]
	s_mov_b32 m0, s6
	ds_read_b128 v[174:177], v169 offset:49152
	ds_read_b128 v[178:181], v169 offset:50176
	ds_read_b128 v[204:207], v169 offset:51200
	ds_read_b128 v[208:211], v169 offset:52224
	ds_read_b128 v[212:215], v169 offset:53248
	ds_read_b128 v[216:219], v169 offset:54272
	ds_read_b128 v[220:223], v169 offset:55296
	ds_read_b128 v[224:227], v169 offset:56320
	global_load_lds_dwordx4 v[228:229], off
	s_add_i32 m0, s6, 0x2000
	s_add_u32 s6, s44, 0xb0080
	v_lshl_add_u64 v[228:229], v[230:231], 0, s[74:75]
	s_addc_u32 s7, s45, 0
	s_add_i32 s21, s26, s30
	global_load_lds_dwordx4 v[228:229], off
	v_lshl_add_u64 v[228:229], s[6:7], 0, v[160:161]
	s_mov_b32 m0, s21
	s_nop 0
	global_load_lds_dwordx4 v[228:229], off
	v_lshl_add_u64 v[228:229], s[6:7], 0, v[152:153]
	s_add_i32 m0, s21, 0x2000
	s_nop 0
	global_load_lds_dwordx4 v[228:229], off
	v_lshl_add_u64 v[228:229], v[232:233], 0, s[98:99]
	s_mov_b32 m0, s56
	s_nop 0
	global_load_lds_dwordx4 v[228:229], off
	v_lshl_add_u64 v[228:229], v[234:235], 0, s[98:99]
	s_mov_b32 m0, s57
	s_nop 0
	global_load_lds_dwordx4 v[228:229], off
	s_waitcnt vmcnt(8)
	s_waitcnt lgkmcnt(0)
	s_barrier
	s_setprio 1
	s_waitcnt lgkmcnt(0)
	v_mfma_f32_16x16x32_bf16 v[60:63], v[128:131], v[174:177], v[60:63]
	v_mfma_f32_16x16x32_bf16 v[56:59], v[136:139], v[174:177], v[56:59]
	v_mfma_f32_16x16x32_bf16 v[44:47], v[128:131], v[204:207], v[44:47]
	v_mfma_f32_16x16x32_bf16 v[40:43], v[136:139], v[204:207], v[40:43]
	v_mfma_f32_16x16x32_bf16 v[28:31], v[128:131], v[212:215], v[28:31]
	v_mfma_f32_16x16x32_bf16 v[24:27], v[136:139], v[212:215], v[24:27]
	v_mfma_f32_16x16x32_bf16 v[12:15], v[128:131], v[220:223], v[12:15]
	v_mfma_f32_16x16x32_bf16 v[8:11], v[136:139], v[220:223], v[8:11]
	v_mfma_f32_16x16x32_bf16 v[60:63], v[132:135], v[178:181], v[60:63]
	v_mfma_f32_16x16x32_bf16 v[56:59], v[140:143], v[178:181], v[56:59]
	v_mfma_f32_16x16x32_bf16 v[44:47], v[132:135], v[208:211], v[44:47]
	v_mfma_f32_16x16x32_bf16 v[40:43], v[140:143], v[208:211], v[40:43]
	v_mfma_f32_16x16x32_bf16 v[28:31], v[132:135], v[216:219], v[28:31]
	v_mfma_f32_16x16x32_bf16 v[24:27], v[140:143], v[216:219], v[24:27]
	v_mfma_f32_16x16x32_bf16 v[12:15], v[132:135], v[224:227], v[12:15]
	v_mfma_f32_16x16x32_bf16 v[8:11], v[140:143], v[224:227], v[8:11]
	s_setprio 0
	s_setprio 1
	v_mfma_f32_16x16x32_bf16 v[52:55], v[144:147], v[174:177], v[52:55]
	v_mfma_f32_16x16x32_bf16 v[48:51], v[164:167], v[174:177], v[48:51]
	v_mfma_f32_16x16x32_bf16 v[36:39], v[144:147], v[204:207], v[36:39]
	v_mfma_f32_16x16x32_bf16 v[32:35], v[164:167], v[204:207], v[32:35]
	v_mfma_f32_16x16x32_bf16 v[20:23], v[144:147], v[212:215], v[20:23]
	v_mfma_f32_16x16x32_bf16 v[16:19], v[164:167], v[212:215], v[16:19]
	v_mfma_f32_16x16x32_bf16 v[4:7], v[144:147], v[220:223], v[4:7]
	v_mfma_f32_16x16x32_bf16 v[0:3], v[164:167], v[220:223], v[0:3]
	v_mfma_f32_16x16x32_bf16 v[52:55], v[148:151], v[178:181], v[52:55]
	v_mfma_f32_16x16x32_bf16 v[48:51], v[170:173], v[178:181], v[48:51]
	v_mfma_f32_16x16x32_bf16 v[36:39], v[148:151], v[208:211], v[36:39]
	v_mfma_f32_16x16x32_bf16 v[32:35], v[170:173], v[208:211], v[32:35]
	v_mfma_f32_16x16x32_bf16 v[20:23], v[148:151], v[216:219], v[20:23]
	v_mfma_f32_16x16x32_bf16 v[16:19], v[170:173], v[216:219], v[16:19]
	v_mfma_f32_16x16x32_bf16 v[4:7], v[148:151], v[224:227], v[4:7]
	v_mfma_f32_16x16x32_bf16 v[0:3], v[170:173], v[224:227], v[0:3]
	s_setprio 0
	s_barrier
	s_add_i32 s65, s65, 2
	s_add_u32 s24, s24, 0x100
	s_addc_u32 s25, s25, 0
	s_cmp_gt_u32 s65, 41
	s_mov_b64 s[6:7], s[42:43]
	s_cbranch_scc0 .LBB0_2180
	s_and_b64 vcc, exec, s[18:19]
	s_cbranch_vccz .LBB0_2183
	s_barrier
